# GLA output stage: per-lane bf16 LDS fetches batched eight at a time instead of one full LDS round trip each
# speedup vs baseline: 1.0014x; 1.0014x over previous
; #define LAS __attribute__((address_space(3)))
; #define MFMA32(a, b, c) __builtin_amdgcn_mfma_f32_32x32x16_bf16((a), (b), (c), 0, 0, 0)
; DI void gla_stage3(const Ctx& c0, int layer, int unit, int cb, LAS unsigned char* lds) {
;     ...
;     const int lane = c.lane, r = lane & 31, hi = lane >> 5;
;     const int bh = unit >> 6, n = unit & 63, b = bh >> 2, h = bh & 3;
;     const size_t row0 = (size_t)b * SEQ + n * 64 + 32 * cb;
;     LAS unsigned char* R = lds + c.wid * G3_BYTES;
;     const LAS unsigned char* Re = R + (4 * hi) * G3_PITCH + r * 2;
;     const bf16* qgp = (const bf16*)(c.ws + O_QG) + (row0 + r) * 256 + h * 64 + 8 * hi;
;     const float* sp = (const float*)(c.ws + O_UPD) + (size_t)unit * 8192;
;     const float* gn = c.a->in[I_GNORM] + (size_t)layer * 128;
;     bf16x8 qf[4];
; #pragma unroll
;     for (int s = 0; s < 4; ++s) qf[s] = *(const bf16x8*)(qgp + 16 * s);
;     f32x16 o[4];
; #pragma unroll
;     for (int vb = 0; vb < 4; ++vb) {
;         o[vb] = f32x16{};
; #pragma unroll
;         for (int s = 0; s < 4; ++s) { const float* s0 = sp + (size_t)(16 * s + 8 * hi) * 128 + 32 * vb + r;
;             const bf16x8 bfv = pack8(s0[0], s0[128], s0[256], s0[384], s0[512], s0[640], s0[768], s0[896]);
;             o[vb] = MFMA32(qf[s], bfv, o[vb]); }
;         asm volatile("" ::: "memory");
.LBB0_604:
	s_mov_b64 s[2:3], s[84:85]
	s_mov_b64 s[0:1], s[86:87]
	s_ashr_i32 s2, s35, 8
	s_ashr_i32 s3, s2, 31
	s_lshl_b64 s[2:3], s[2:3], 12
	s_and_b32 s5, s8, 0xfc0
	s_or_b32 s2, s2, s5
	s_or_b64 s[2:3], s[2:3], s[6:7]
	v_mov_b32_e32 v3, s3
	v_or_b32_e32 v2, s2, v152
	s_bfe_u32 s4, s35, 0x20006
	v_lshlrev_b64 v[2:3], 9, v[2:3]
	v_lshl_add_u64 v[2:3], s[0:1], 0, v[2:3]
	s_lshl_b32 s10, s4, 7
	v_lshl_add_u64 v[2:3], v[2:3], 0, s[10:11]
	v_lshl_add_u64 v[2:3], v[2:3], 0, v[86:87]
	v_lshl_add_u64 v[4:5], v[2:3], 0, s[16:17]
	v_add_co_u32_e32 v2, vcc, s13, v2
	v_lshl_add_u64 v[90:91], s[0:1], 0, v[84:85]
	s_nop 0
	v_addc_co_u32_e32 v3, vcc, 0, v3, vcc
	global_load_dwordx4 v[50:53], v[2:3], off
	global_load_dwordx4 v[110:113], v[4:5], off offset:96
	global_load_dwordx4 v[106:109], v[4:5], off offset:64
	global_load_dwordx4 v[102:105], v[4:5], off offset:32
	v_add_co_u32_e32 v2, vcc, s24, v90
	s_lshl_b64 s[2:3], s[2:3], 10
	s_nop 0
	v_addc_co_u32_e32 v3, vcc, -1, v91, vcc
	v_add_co_u32_e32 v58, vcc, s28, v90
	global_load_dword v2, v[2:3], off
	s_nop 0
	v_addc_co_u32_e32 v59, vcc, -1, v91, vcc
	global_load_dword v3, v[58:59], off offset:384
	global_load_dword v4, v[58:59], off offset:896
	global_load_dword v5, v[58:59], off offset:1408
	global_load_dword v6, v[58:59], off offset:1920
	global_load_dword v7, v[58:59], off offset:2432
	global_load_dword v8, v[58:59], off offset:2944
	global_load_dword v9, v[58:59], off offset:3456
	v_add_co_u32_e32 v18, vcc, s25, v90
	s_lshl_b32 s4, s4, 8
	s_nop 0
	v_addc_co_u32_e32 v19, vcc, -1, v91, vcc
	v_add_co_u32_e32 v114, vcc, s29, v90
	global_load_dword v18, v[18:19], off
	s_nop 0
	v_addc_co_u32_e32 v115, vcc, -1, v91, vcc
	global_load_dword v19, v[114:115], off offset:384
	global_load_dword v20, v[114:115], off offset:896
	global_load_dword v21, v[114:115], off offset:1408
	global_load_dword v22, v[114:115], off offset:1920
	global_load_dword v23, v[114:115], off offset:2432
	global_load_dword v24, v[114:115], off offset:2944
	global_load_dword v25, v[114:115], off offset:3456
	s_add_u32 s0, s0, s2
	s_addc_u32 s1, s1, s3
	s_add_u32 s0, s0, s4
	s_addc_u32 s1, s1, 0
	s_add_i32 s35, s35, s12
	s_add_i32 s8, s8, s9
	v_lshl_add_u64 v[84:85], v[84:85], 0, s[14:15]
	s_cmpk_lt_i32 s35, 0x800
	s_waitcnt vmcnt(0) lgkmcnt(0)
	global_load_dword v41, v[114:115], off offset:3584
	global_load_dword v40, v[114:115], off offset:3072
	global_load_dword v39, v[114:115], off offset:2560
	global_load_dword v38, v[114:115], off offset:2048
	global_load_dword v37, v[114:115], off offset:1536
	global_load_dword v36, v[114:115], off offset:1024
	global_load_dword v35, v[114:115], off offset:512
	global_load_dword v34, v[114:115], off
	global_load_dword v145, v[58:59], off offset:3584
	global_load_dword v146, v[58:59], off offset:3072
	global_load_dword v143, v[58:59], off offset:2560
	global_load_dword v144, v[58:59], off offset:2048
	global_load_dword v141, v[58:59], off offset:1536
	global_load_dword v142, v[58:59], off offset:1024
	global_load_dword v139, v[58:59], off offset:512
	global_load_dword v140, v[58:59], off
	v_cvt_pk_bf16_f32 v2, v2, v3
	v_cvt_pk_bf16_f32 v3, v4, v5
	v_cvt_pk_bf16_f32 v4, v6, v7
	v_cvt_pk_bf16_f32 v5, v8, v9
	v_cvt_pk_bf16_f32 v18, v18, v19
	s_nop 0
	v_mfma_f32_32x32x16_bf16 v[2:17], v[50:53], v[2:5], 0
	v_cvt_pk_bf16_f32 v19, v20, v21
	v_cvt_pk_bf16_f32 v20, v22, v23
	v_cvt_pk_bf16_f32 v21, v24, v25
	s_nop 1
	v_mfma_f32_32x32x16_bf16 v[2:17], v[102:105], v[18:21], v[2:17]
	v_add_co_u32_e32 v18, vcc, s26, v90
	s_nop 1
	v_addc_co_u32_e32 v19, vcc, -1, v91, vcc
	v_add_co_u32_e32 v118, vcc, s30, v90
	global_load_dword v18, v[18:19], off
	s_nop 0
	v_addc_co_u32_e32 v119, vcc, -1, v91, vcc
	global_load_dword v19, v[118:119], off offset:384
	global_load_dword v20, v[118:119], off offset:896
	global_load_dword v21, v[118:119], off offset:1408
	global_load_dword v22, v[118:119], off offset:1920
	global_load_dword v23, v[118:119], off offset:2432
	global_load_dword v24, v[118:119], off offset:2944
	global_load_dword v25, v[118:119], off offset:3456
	s_waitcnt vmcnt(0) lgkmcnt(0)
	global_load_dword v63, v[114:115], off offset:3712
	global_load_dword v62, v[114:115], off offset:3200
	global_load_dword v61, v[114:115], off offset:2688
	global_load_dword v60, v[114:115], off offset:2176
	global_load_dword v57, v[114:115], off offset:1664
	global_load_dword v56, v[114:115], off offset:1152
	global_load_dword v55, v[114:115], off offset:640
	global_load_dword v54, v[114:115], off offset:128
	global_load_dword v173, v[58:59], off offset:3712
	global_load_dword v176, v[58:59], off offset:3200
	global_load_dword v171, v[58:59], off offset:2688
	global_load_dword v174, v[58:59], off offset:2176
	global_load_dword v169, v[58:59], off offset:1664
	global_load_dword v172, v[58:59], off offset:1152
	global_load_dword v167, v[58:59], off offset:640
	global_load_dword v170, v[58:59], off offset:128
	global_load_dword v157, v[118:119], off offset:3584
	global_load_dword v160, v[118:119], off offset:3072
	global_load_dword v155, v[118:119], off offset:2560
	global_load_dword v158, v[118:119], off offset:2048
	global_load_dword v149, v[118:119], off offset:1536
	global_load_dword v156, v[118:119], off offset:1024
	global_load_dword v147, v[118:119], off offset:512
	global_load_dword v148, v[118:119], off
	v_cvt_pk_bf16_f32 v18, v18, v19
	v_cvt_pk_bf16_f32 v19, v20, v21
	v_cvt_pk_bf16_f32 v20, v22, v23
	v_cvt_pk_bf16_f32 v21, v24, v25
	s_nop 1
	v_mfma_f32_32x32x16_bf16 v[2:17], v[106:109], v[18:21], v[2:17]
	v_add_co_u32_e32 v18, vcc, s27, v90
	s_nop 1
	v_addc_co_u32_e32 v19, vcc, -1, v91, vcc
	v_add_co_u32_e32 v120, vcc, s31, v90
	global_load_dword v18, v[18:19], off
	s_nop 0
	v_addc_co_u32_e32 v121, vcc, -1, v91, vcc
	global_load_dword v19, v[120:121], off offset:384
	global_load_dword v20, v[120:121], off offset:896
	global_load_dword v21, v[120:121], off offset:1408
	global_load_dword v22, v[120:121], off offset:1920
	global_load_dword v23, v[120:121], off offset:2432
	global_load_dword v24, v[120:121], off offset:2944
	global_load_dword v25, v[120:121], off offset:3456
	v_cmp_lt_i32_e32 vcc, v94, v95
	s_waitcnt vmcnt(0) lgkmcnt(0)
; #define MFMA32(a, b, c) __builtin_amdgcn_mfma_f32_32x32x16_bf16((a), (b), (c), 0, 0, 0)
; DI void gla_stage3(const Ctx& c0, int layer, int unit, int cb, LAS unsigned char* lds) {
;     ...
;     f32x16 o[4];
; #pragma unroll
;     for (int vb = 0; vb < 4; ++vb) {
;         o[vb] = f32x16{};
; #pragma unroll
;         for (int s = 0; s < 4; ++s) { const float* s0 = sp + (size_t)(16 * s + 8 * hi) * 128 + 32 * vb + r;
;             const bf16x8 bfv = pack8(s0[0], s0[128], s0[256], s0[384], s0[512], s0[640], s0[768], s0[896]);
;             o[vb] = MFMA32(qf[s], bfv, o[vb]); }
;         asm volatile("" ::: "memory");
;     ...
;     for (int vb = 0; vb < 4; ++vb) { const float g = gn[32 * vb + r];
	global_load_dword v127, v[114:115], off offset:3840
	global_load_dword v126, v[114:115], off offset:3328
	global_load_dword v125, v[114:115], off offset:2816
	global_load_dword v124, v[114:115], off offset:2304
	global_load_dword v123, v[114:115], off offset:1792
	global_load_dword v122, v[114:115], off offset:1280
	global_load_dword v117, v[114:115], off offset:768
	global_load_dword v116, v[114:115], off offset:256
	global_load_dword v214, v[58:59], off offset:3840
	global_load_dword v212, v[58:59], off offset:3328
	global_load_dword v205, v[58:59], off offset:2816
	global_load_dword v210, v[58:59], off offset:2304
	global_load_dword v203, v[58:59], off offset:1792
	global_load_dword v208, v[58:59], off offset:1280
	global_load_dword v201, v[58:59], off offset:768
	global_load_dword v206, v[58:59], off offset:256
	global_load_dword v199, v[120:121], off offset:3712
	global_load_dword v204, v[120:121], off offset:3200
	global_load_dword v197, v[120:121], off offset:2688
	global_load_dword v202, v[120:121], off offset:2176
	global_load_dword v195, v[120:121], off offset:1664
	global_load_dword v200, v[120:121], off offset:1152
	global_load_dword v183, v[120:121], off offset:640
	global_load_dword v198, v[120:121], off offset:128
	global_load_dword v181, v[118:119], off offset:3712
	global_load_dword v196, v[118:119], off offset:3200
	global_load_dword v179, v[118:119], off offset:2688
	global_load_dword v182, v[118:119], off offset:2176
	global_load_dword v177, v[118:119], off offset:1664
	global_load_dword v180, v[118:119], off offset:1152
	global_load_dword v175, v[118:119], off offset:640
	global_load_dword v178, v[118:119], off offset:128
	global_load_dword v165, v[120:121], off offset:3584
	global_load_dword v168, v[120:121], off offset:3072
	global_load_dword v163, v[120:121], off offset:2560
	global_load_dword v166, v[120:121], off offset:2048
	global_load_dword v161, v[120:121], off offset:1536
	global_load_dword v164, v[120:121], off offset:1024
	global_load_dword v159, v[120:121], off offset:512
	global_load_dword v162, v[120:121], off
	v_cvt_pk_bf16_f32 v18, v18, v19
	v_cvt_pk_bf16_f32 v19, v20, v21
	v_cvt_pk_bf16_f32 v20, v22, v23
	v_cvt_pk_bf16_f32 v21, v24, v25
	s_nop 1
	v_mfma_f32_32x32x16_bf16 v[2:17], v[110:113], v[18:21], v[2:17]
	s_waitcnt vmcnt(40) lgkmcnt(0)
	global_load_dword v238, v[82:83], off offset:384
	global_load_dword v236, v[82:83], off offset:256
	global_load_dword v234, v[82:83], off offset:128
	global_load_dword v232, v[82:83], off
	global_load_dword v90, v[90:91], off
	global_load_dword v230, v[120:121], off offset:3328
	global_load_dword v219, v[120:121], off offset:2816
	global_load_dword v228, v[120:121], off offset:2304
	global_load_dword v217, v[120:121], off offset:1792
	global_load_dword v226, v[120:121], off offset:1280
	global_load_dword v215, v[120:121], off offset:768
	global_load_dword v224, v[120:121], off offset:256
	global_load_dword v213, v[118:119], off offset:3840
	global_load_dword v222, v[118:119], off offset:3328
	global_load_dword v211, v[118:119], off offset:2816
	global_load_dword v220, v[118:119], off offset:2304
	global_load_dword v209, v[118:119], off offset:1792
	global_load_dword v218, v[118:119], off offset:1280
	global_load_dword v207, v[118:119], off offset:768
	global_load_dword v216, v[118:119], off offset:256
	v_cvt_pk_bf16_f32 v18, v140, v139
	v_cvt_pk_bf16_f32 v34, v34, v35
	v_cvt_pk_bf16_f32 v19, v142, v141
	v_cvt_pk_bf16_f32 v35, v36, v37
	v_cvt_pk_bf16_f32 v20, v144, v143
	v_cvt_pk_bf16_f32 v36, v38, v39
	v_cvt_pk_bf16_f32 v21, v146, v145
	v_cvt_pk_bf16_f32 v37, v40, v41
	s_nop 0
	v_mfma_f32_32x32x16_bf16 v[18:33], v[50:53], v[18:21], 0
	v_mfma_f32_32x32x16_bf16 v[18:33], v[102:105], v[34:37], v[18:33]
	s_waitcnt vmcnt(60) lgkmcnt(0)
	v_cvt_pk_bf16_f32 v34, v148, v147
	v_cvt_pk_bf16_f32 v35, v156, v149
	v_cvt_pk_bf16_f32 v36, v158, v155
	v_cvt_pk_bf16_f32 v37, v160, v157
	s_nop 1
	v_mfma_f32_32x32x16_bf16 v[18:33], v[106:109], v[34:37], v[18:33]
	s_waitcnt vmcnt(20) lgkmcnt(0)
	v_cvt_pk_bf16_f32 v34, v162, v159
	v_cvt_pk_bf16_f32 v35, v164, v161
	v_cvt_pk_bf16_f32 v36, v166, v163
	v_cvt_pk_bf16_f32 v37, v168, v165
	s_nop 1
	v_mfma_f32_32x32x16_bf16 v[18:33], v[110:113], v[34:37], v[18:33]
	s_waitcnt vmcnt(62) lgkmcnt(0)
	v_cvt_pk_bf16_f32 v34, v170, v167
	v_cvt_pk_bf16_f32 v54, v54, v55
	v_cvt_pk_bf16_f32 v35, v172, v169
	v_cvt_pk_bf16_f32 v55, v56, v57
	v_cvt_pk_bf16_f32 v36, v174, v171
	v_cvt_pk_bf16_f32 v56, v60, v61
	v_cvt_pk_bf16_f32 v37, v176, v173
	v_cvt_pk_bf16_f32 v57, v62, v63
	s_nop 0
	v_mfma_f32_32x32x16_bf16 v[34:49], v[50:53], v[34:37], 0
	v_mfma_f32_32x32x16_bf16 v[34:49], v[102:105], v[54:57], v[34:49]
	s_waitcnt vmcnt(28) lgkmcnt(0)
	v_cvt_pk_bf16_f32 v54, v178, v175
	v_cvt_pk_bf16_f32 v55, v180, v177
	v_cvt_pk_bf16_f32 v56, v182, v179
	v_cvt_pk_bf16_f32 v57, v196, v181
	s_nop 1
	v_mfma_f32_32x32x16_bf16 v[34:49], v[106:109], v[54:57], v[34:49]
	s_waitcnt vmcnt(36) lgkmcnt(0)
	v_cvt_pk_bf16_f32 v54, v198, v183
	v_cvt_pk_bf16_f32 v55, v200, v195
	v_cvt_pk_bf16_f32 v56, v202, v197
	v_cvt_pk_bf16_f32 v57, v204, v199
	s_nop 1
	v_mfma_f32_32x32x16_bf16 v[34:49], v[110:113], v[54:57], v[34:49]
	s_nop 0
	s_nop 0
	s_waitcnt vmcnt(44) lgkmcnt(0)
	v_cvt_pk_bf16_f32 v54, v206, v201
	v_cvt_pk_bf16_f32 v114, v116, v117
	v_cvt_pk_bf16_f32 v55, v208, v203
	v_cvt_pk_bf16_f32 v115, v122, v123
	v_cvt_pk_bf16_f32 v56, v210, v205
	v_cvt_pk_bf16_f32 v116, v124, v125
	v_cvt_pk_bf16_f32 v57, v212, v214
	v_cvt_pk_bf16_f32 v117, v126, v127
	s_nop 0
	v_mfma_f32_32x32x16_bf16 v[50:65], v[50:53], v[54:57], 0
	v_mfma_f32_32x32x16_bf16 v[50:65], v[102:105], v[114:117], v[50:65]
	s_waitcnt vmcnt(0) lgkmcnt(0)
; #define LAS __attribute__((address_space(3)))
; #define LDS_WAIT() asm volatile("s_waitcnt lgkmcnt(0)" ::: "memory")
; DI float bf2f(bf16 b) { return __uint_as_float(((unsigned)b) << 16); }
; DI void g3_tile_in(const bf16* g, LAS unsigned char* R, int lane) {
; #pragma unroll
;     for (int it = 0; it < 8; ++it) { const int row = 4 * it + (lane >> 4), ch = lane & 15;
;         *(LAS u32x4*)(R + row * G3_PITCH + ch * 16) = *(const u32x4*)(g + (size_t)row * 512 + ch * 8); }
;     LDS_WAIT();
; }
; DI void gla_stage3(const Ctx& c0, int layer, int unit, int cb, LAS unsigned char* lds) {
;     ...
;     g3_tile_in((const bf16*)(c.ws + O_OINTRA) + row0 * 512 + h * 128, R, lane);
; #pragma unroll
;     for (int vb = 0; vb < 4; ++vb) {
; #pragma unroll
;         for (int rg = 0; rg < 16; ++rg) o[vb][rg] += bf2f(*(const LAS bf16*)(Re + ((rg & 3) + 8 * (rg >> 2)) * G3_PITCH + 64 * vb));
;         asm volatile("" ::: "memory");
;     }
	v_cvt_pk_bf16_f32 v102, v216, v207
	v_cvt_pk_bf16_f32 v103, v218, v209
	v_cvt_pk_bf16_f32 v104, v220, v211
	v_cvt_pk_bf16_f32 v105, v222, v213
	s_nop 1
	v_mfma_f32_32x32x16_bf16 v[50:65], v[106:109], v[102:105], v[50:65]
	s_nop 0
	s_waitcnt vmcnt(8) lgkmcnt(0)
	v_cvt_pk_bf16_f32 v102, v224, v215
	v_cvt_pk_bf16_f32 v103, v226, v217
	v_cvt_pk_bf16_f32 v104, v228, v219
	v_cvt_pk_bf16_f32 v105, v230, v90
	v_lshl_add_u64 v[90:91], s[0:1], 0, v[88:89]
	v_lshl_add_u64 v[106:107], v[90:91], 0, s[18:19]
	v_mfma_f32_32x32x16_bf16 v[50:65], v[110:113], v[102:105], v[50:65]
	v_lshl_add_u64 v[102:103], v[106:107], 0, v[66:67]
	global_load_dwordx4 v[102:105], v[102:103], off
	s_waitcnt vmcnt(0) lgkmcnt(0)
	v_lshl_add_u64 v[168:169], v[90:91], 0, s[20:21]
	v_lshl_add_u64 v[140:141], v[168:169], 0, v[70:71]
	global_load_dwordx4 v[174:177], v[140:141], off
	v_lshl_add_u64 v[140:141], v[106:107], 0, v[70:71]
	global_load_dwordx4 v[146:149], v[140:141], off
	v_lshl_add_u64 v[144:145], v[106:107], 0, v[68:69]
	global_load_dwordx4 v[140:143], v[144:145], off
	ds_write_b128 v92, v[102:105]
	s_waitcnt vmcnt(0) lgkmcnt(0)
	v_lshl_add_u64 v[144:145], v[168:169], 0, v[76:77]
	global_load_dwordx4 v[200:203], v[144:145], off
	v_lshl_add_u64 v[144:145], v[168:169], 0, v[74:75]
	global_load_dwordx4 v[196:199], v[144:145], off
	v_lshl_add_u64 v[144:145], v[168:169], 0, v[72:73]
	global_load_dwordx4 v[178:181], v[144:145], off
	v_lshl_add_u64 v[144:145], v[106:107], 0, v[74:75]
	global_load_dwordx4 v[156:159], v[144:145], off
	v_lshl_add_u64 v[102:103], v[106:107], 0, v[72:73]
	global_load_dwordx4 v[102:105], v[102:103], off
	ds_write_b128 v92, v[140:143] offset:1088
	s_waitcnt vmcnt(5) lgkmcnt(0)
	v_lshl_add_u64 v[140:141], v[168:169], 0, v[78:79]
	global_load_dwordx4 v[204:207], v[140:141], off
	v_lshl_add_u64 v[140:141], v[106:107], 0, v[78:79]
	global_load_dwordx4 v[160:163], v[140:141], off
	v_lshl_add_u64 v[144:145], v[106:107], 0, v[76:77]
	global_load_dwordx4 v[140:143], v[144:145], off
	ds_write_b128 v92, v[146:149] offset:2176
	s_waitcnt vmcnt(3) lgkmcnt(0)
	v_lshl_add_u64 v[144:145], v[168:169], 0, v[66:67]
	global_load_dwordx4 v[164:167], v[144:145], off
	v_lshl_add_u64 v[148:149], v[106:107], 0, v[80:81]
	global_load_dwordx4 v[144:147], v[148:149], off
	ds_write_b128 v92, v[102:105] offset:3264
	s_waitcnt vmcnt(6) lgkmcnt(0)
	v_lshl_add_u64 v[148:149], v[168:169], 0, v[68:69]
	global_load_dwordx4 v[170:173], v[148:149], off
	ds_write_b128 v92, v[156:159] offset:4352
	s_waitcnt vmcnt(3) lgkmcnt(0)
	ds_write_b128 v92, v[140:143] offset:5440
	s_waitcnt vmcnt(4) lgkmcnt(0)
	ds_write_b128 v92, v[160:163] offset:6528
	s_waitcnt vmcnt(1) lgkmcnt(0)
	ds_write_b128 v92, v[144:147] offset:7616
	s_waitcnt lgkmcnt(0)
	ds_read_u16 v138, v1
	ds_read_u16 v137, v1 offset:272
	ds_read_u16 v136, v1 offset:544
	ds_read_u16 v135, v1 offset:816
	ds_read_u16 v134, v1 offset:2176
	ds_read_u16 v133, v1 offset:2448
	ds_read_u16 v132, v1 offset:2720
	ds_read_u16 v131, v1 offset:2992
	s_waitcnt lgkmcnt(0)
	v_lshlrev_b32_e32 v138, 16, v138
	v_add_f32_e32 v138, v2, v138
	v_lshlrev_b32_e32 v137, 16, v137
	v_add_f32_e32 v137, v3, v137
	v_lshlrev_b32_e32 v136, 16, v136
	v_add_f32_e32 v136, v4, v136
	v_lshlrev_b32_e32 v135, 16, v135
	v_add_f32_e32 v135, v5, v135
	v_lshlrev_b32_e32 v134, 16, v134
	v_add_f32_e32 v134, v6, v134
	v_lshlrev_b32_e32 v133, 16, v133
	v_add_f32_e32 v133, v7, v133
	v_lshlrev_b32_e32 v132, 16, v132
	v_add_f32_e32 v132, v8, v132
	v_lshlrev_b32_e32 v131, 16, v131
	v_add_f32_e32 v131, v9, v131
	ds_read_u16 v130, v1 offset:4352
	ds_read_u16 v129, v1 offset:4624
	ds_read_u16 v128, v1 offset:4896
	ds_read_u16 v127, v1 offset:5168
	ds_read_u16 v126, v1 offset:6528
	ds_read_u16 v125, v1 offset:6800
	ds_read_u16 v124, v1 offset:7072
	s_waitcnt lgkmcnt(0)
	v_lshlrev_b32_e32 v130, 16, v130
	v_add_f32_e32 v130, v10, v130
	v_lshlrev_b32_e32 v129, 16, v129
	v_add_f32_e32 v129, v11, v129
	v_lshlrev_b32_e32 v128, 16, v128
	v_add_f32_e32 v128, v12, v128
	v_lshlrev_b32_e32 v127, 16, v127
	v_add_f32_e32 v127, v13, v127
	v_lshlrev_b32_e32 v126, 16, v126
	v_add_f32_e32 v126, v14, v126
	v_lshlrev_b32_e32 v125, 16, v125
	v_add_f32_e32 v125, v15, v125
	v_lshlrev_b32_e32 v124, 16, v124
	v_add_f32_e32 v124, v16, v124
	ds_read_u16 v2, v1 offset:7344
	s_waitcnt lgkmcnt(0)
	v_lshlrev_b32_e32 v2, 16, v2
	v_add_f32_e32 v123, v17, v2
	ds_read_u16 v122, v1 offset:64
	ds_read_u16 v121, v1 offset:336
	ds_read_u16 v120, v1 offset:608
	ds_read_u16 v119, v1 offset:880
	ds_read_u16 v118, v1 offset:2240
	ds_read_u16 v117, v1 offset:2512
	ds_read_u16 v116, v1 offset:2784
	ds_read_u16 v115, v1 offset:3056
	s_waitcnt lgkmcnt(0)
	v_lshlrev_b32_e32 v122, 16, v122
	v_add_f32_e32 v122, v18, v122
	v_lshlrev_b32_e32 v121, 16, v121
	v_add_f32_e32 v121, v19, v121
	v_lshlrev_b32_e32 v120, 16, v120
	v_add_f32_e32 v120, v20, v120
	v_lshlrev_b32_e32 v119, 16, v119
	v_add_f32_e32 v119, v21, v119
	v_lshlrev_b32_e32 v118, 16, v118
	v_add_f32_e32 v118, v22, v118
	v_lshlrev_b32_e32 v117, 16, v117
	v_add_f32_e32 v117, v23, v117
	v_lshlrev_b32_e32 v116, 16, v116
	v_add_f32_e32 v116, v24, v116
	v_lshlrev_b32_e32 v115, 16, v115
	v_add_f32_e32 v115, v25, v115
	ds_read_u16 v114, v1 offset:4416
	ds_read_u16 v113, v1 offset:4688
	ds_read_u16 v112, v1 offset:4960
	ds_read_u16 v111, v1 offset:5232
	ds_read_u16 v110, v1 offset:6592
	ds_read_u16 v109, v1 offset:6864
	ds_read_u16 v108, v1 offset:7136
	s_waitcnt lgkmcnt(0)
; #define LAS __attribute__((address_space(3)))
; DI float bf2f(bf16 b) { return __uint_as_float(((unsigned)b) << 16); }
; DI void gla_stage3(const Ctx& c0, int layer, int unit, int cb, LAS unsigned char* lds) {
;     ...
;     for (int vb = 0; vb < 4; ++vb) {
; #pragma unroll
;         for (int rg = 0; rg < 16; ++rg) o[vb][rg] += bf2f(*(const LAS bf16*)(Re + ((rg & 3) + 8 * (rg >> 2)) * G3_PITCH + 64 * vb));
;         asm volatile("" ::: "memory");
;     }
;     float rs[16];
; #pragma unroll
;     for (int rg = 0; rg < 16; ++rg) { float ss = o[0][rg] * o[0][rg] + o[1][rg] * o[1][rg] + o[2][rg] * o[2][rg] + o[3][rg] * o[3][rg];
;         ss += __shfl_xor(ss, 1); ss += __shfl_xor(ss, 2); ss += __shfl_xor(ss, 4); ss += __shfl_xor(ss, 8); ss += __shfl_xor(ss, 16);
;         rs[rg] = 1.f / sqrtf(ss * (1.f / 128.f) + EPS); }
	v_lshlrev_b32_e32 v114, 16, v114
	v_add_f32_e32 v114, v26, v114
	v_lshlrev_b32_e32 v113, 16, v113
	v_add_f32_e32 v113, v27, v113
	v_lshlrev_b32_e32 v112, 16, v112
	v_add_f32_e32 v112, v28, v112
	v_lshlrev_b32_e32 v111, 16, v111
	v_add_f32_e32 v111, v29, v111
	v_lshlrev_b32_e32 v110, 16, v110
	v_add_f32_e32 v110, v30, v110
	v_lshlrev_b32_e32 v109, 16, v109
	v_add_f32_e32 v109, v31, v109
	v_lshlrev_b32_e32 v108, 16, v108
	v_add_f32_e32 v108, v32, v108
	ds_read_u16 v2, v1 offset:7408
	s_waitcnt lgkmcnt(0)
	v_lshlrev_b32_e32 v2, 16, v2
	v_add_f32_e32 v107, v33, v2
	ds_read_u16 v2, v1 offset:128
	s_waitcnt lgkmcnt(0)
	v_lshlrev_b32_e32 v2, 16, v2
	v_add_f32_e32 v106, v34, v2
	ds_read_u16 v2, v1 offset:400
	s_waitcnt lgkmcnt(0)
	v_lshlrev_b32_e32 v2, 16, v2
	v_add_f32_e32 v105, v35, v2
	ds_read_u16 v2, v1 offset:672
	s_waitcnt lgkmcnt(0)
	v_lshlrev_b32_e32 v2, 16, v2
	v_add_f32_e32 v104, v36, v2
	ds_read_u16 v2, v1 offset:944
	s_waitcnt lgkmcnt(0)
	v_lshlrev_b32_e32 v2, 16, v2
	v_add_f32_e32 v103, v37, v2
	ds_read_u16 v2, v1 offset:2304
	s_waitcnt lgkmcnt(0)
	v_lshlrev_b32_e32 v2, 16, v2
	v_add_f32_e32 v102, v38, v2
	ds_read_u16 v2, v1 offset:2576
	s_waitcnt lgkmcnt(0)
	v_lshlrev_b32_e32 v2, 16, v2
	v_add_f32_e32 v39, v39, v2
	ds_read_u16 v2, v1 offset:2848
	s_waitcnt lgkmcnt(0)
	v_lshlrev_b32_e32 v2, 16, v2
	v_add_f32_e32 v38, v40, v2
	ds_read_u16 v2, v1 offset:3120
	s_waitcnt lgkmcnt(0)
	v_lshlrev_b32_e32 v2, 16, v2
	v_add_f32_e32 v37, v41, v2
	ds_read_u16 v36, v1 offset:4480
	ds_read_u16 v34, v1 offset:4752
	ds_read_u16 v33, v1 offset:5024
	ds_read_u16 v32, v1 offset:5296
	ds_read_u16 v30, v1 offset:6656
	ds_read_u16 v29, v1 offset:6928
	ds_read_u16 v28, v1 offset:7200
	s_waitcnt lgkmcnt(0)
	v_lshlrev_b32_e32 v36, 16, v36
	v_add_f32_e32 v36, v42, v36
	v_lshlrev_b32_e32 v34, 16, v34
	v_add_f32_e32 v34, v43, v34
	v_lshlrev_b32_e32 v33, 16, v33
	v_add_f32_e32 v33, v44, v33
	v_lshlrev_b32_e32 v32, 16, v32
	v_add_f32_e32 v32, v45, v32
	v_lshlrev_b32_e32 v30, 16, v30
	v_add_f32_e32 v30, v46, v30
	v_lshlrev_b32_e32 v29, 16, v29
	v_add_f32_e32 v29, v47, v29
	v_lshlrev_b32_e32 v28, 16, v28
	v_add_f32_e32 v28, v48, v28
	ds_read_u16 v2, v1 offset:7472
	s_waitcnt lgkmcnt(0)
	v_lshlrev_b32_e32 v2, 16, v2
	v_add_f32_e32 v26, v49, v2
	ds_read_u16 v19, v1 offset:192
	ds_read_u16 v18, v1 offset:464
	ds_read_u16 v17, v1 offset:736
	ds_read_u16 v16, v1 offset:1008
	ds_read_u16 v15, v1 offset:2368
	ds_read_u16 v14, v1 offset:2640
	ds_read_u16 v13, v1 offset:2912
	ds_read_u16 v12, v1 offset:3184
	s_waitcnt lgkmcnt(0)
	v_lshlrev_b32_e32 v19, 16, v19
	v_add_f32_e32 v19, v50, v19
	v_lshlrev_b32_e32 v18, 16, v18
	v_add_f32_e32 v18, v51, v18
	v_lshlrev_b32_e32 v17, 16, v17
	v_add_f32_e32 v17, v52, v17
	v_lshlrev_b32_e32 v16, 16, v16
	v_add_f32_e32 v16, v53, v16
	v_lshlrev_b32_e32 v15, 16, v15
	v_add_f32_e32 v15, v54, v15
	v_lshlrev_b32_e32 v14, 16, v14
	v_add_f32_e32 v14, v55, v14
	v_lshlrev_b32_e32 v13, 16, v13
	v_add_f32_e32 v13, v56, v13
	v_lshlrev_b32_e32 v12, 16, v12
	v_add_f32_e32 v12, v57, v12
	ds_read_u16 v11, v1 offset:4544
	ds_read_u16 v10, v1 offset:4816
	ds_read_u16 v9, v1 offset:5088
	ds_read_u16 v8, v1 offset:5360
	ds_read_u16 v7, v1 offset:6720
	ds_read_u16 v6, v1 offset:6992
	ds_read_u16 v5, v1 offset:7264
	s_waitcnt lgkmcnt(0)
	v_lshlrev_b32_e32 v11, 16, v11
	v_add_f32_e32 v11, v58, v11
	v_lshlrev_b32_e32 v10, 16, v10
	v_add_f32_e32 v10, v59, v10
	v_lshlrev_b32_e32 v9, 16, v9
	v_add_f32_e32 v9, v60, v9
	v_lshlrev_b32_e32 v8, 16, v8
	v_add_f32_e32 v8, v61, v8
	v_lshlrev_b32_e32 v7, 16, v7
	v_add_f32_e32 v7, v62, v7
	v_lshlrev_b32_e32 v6, 16, v6
	v_add_f32_e32 v6, v63, v6
	v_lshlrev_b32_e32 v5, 16, v5
	v_add_f32_e32 v5, v64, v5
	ds_read_u16 v2, v1 offset:7536
	s_waitcnt lgkmcnt(0)
	s_waitcnt lgkmcnt(0)
	v_lshlrev_b32_e32 v2, 16, v2
	v_add_f32_e32 v4, v65, v2
	v_cndmask_b32_e32 v2, v93, v94, vcc
	v_cmp_lt_i32_e32 vcc, v96, v95
	v_lshlrev_b32_e32 v2, 2, v2
	s_nop 0
	v_cndmask_b32_e32 v3, v93, v96, vcc
	v_cmp_lt_i32_e32 vcc, v97, v95
	v_lshlrev_b32_e32 v3, 2, v3
	s_nop 0
	v_cndmask_b32_e32 v20, v93, v97, vcc
	v_cmp_lt_i32_e32 vcc, v98, v95
	v_lshlrev_b32_e32 v20, 2, v20
	s_nop 0
	v_cndmask_b32_e32 v21, v93, v98, vcc
	v_cmp_lt_i32_e32 vcc, v99, v95
	v_lshlrev_b32_e32 v47, 2, v21
	s_nop 0
	v_cndmask_b32_e32 v21, v93, v99, vcc
	v_lshlrev_b32_e32 v48, 2, v21
	v_mul_f32_e32 v21, v122, v122
	v_fmac_f32_e32 v21, v138, v138
	v_fmac_f32_e32 v21, v106, v106
	v_fmac_f32_e32 v21, v19, v19
	s_nop 1
	v_add_f32_dpp v21, v21, v21 quad_perm:[1,0,3,2] row_mask:0xf bank_mask:0xf
	s_nop 1
	v_add_f32_dpp v21, v21, v21 quad_perm:[2,3,0,1] row_mask:0xf bank_mask:0xf
	s_nop 1
	v_add_f32_dpp v21, v21, v21 row_half_mirror row_mask:0xf bank_mask:0xf
	s_nop 1
	v_add_f32_dpp v21, v21, v21 row_mirror row_mask:0xf bank_mask:0xf
	v_mov_b32_e32 v22, v21
	v_mov_b32_e32 v23, v21
	s_nop 1
	v_permlane16_swap_b32_e32 v22, v23
	v_add_f32_e32 v21, v22, v23
	v_fmamk_f32 v21, v21, 0x3c000000, v100
	v_cmp_gt_f32_e32 vcc, s34, v21
	v_mul_f32_e32 v22, 0x4f800000, v21
	s_nop 0
	v_cndmask_b32_e32 v21, v21, v22, vcc
	v_sqrt_f32_e32 v22, v21
	s_nop 0
	v_add_u32_e32 v23, -1, v22
	v_fma_f32 v24, -v23, v22, v21
	v_cmp_ge_f32_e64 s[4:5], 0, v24
	v_add_u32_e32 v24, 1, v22
	s_nop 0
	v_cndmask_b32_e64 v23, v22, v23, s[4:5]
	v_fma_f32 v22, -v24, v22, v21
	v_cmp_lt_f32_e64 s[4:5], 0, v22
	s_nop 1
	v_cndmask_b32_e64 v22, v23, v24, s[4:5]
	v_mul_f32_e32 v23, 0x37800000, v22
	v_cndmask_b32_e32 v22, v22, v23, vcc
	v_cmp_class_f32_e32 vcc, v21, v101
	s_nop 1
	v_cndmask_b32_e32 v21, v22, v21, vcc
	s_nop 0
	v_div_scale_f32 v24, vcc, 1.0, v21, 1.0
	v_rcp_f32_e32 v46, v21
	v_mul_f32_e32 v21, v121, v121
; DI void gla_stage3(const Ctx& c0, int layer, int unit, int cb, LAS unsigned char* lds) {
;     ...
;     float rs[16];
; #pragma unroll
;     for (int rg = 0; rg < 16; ++rg) { float ss = o[0][rg] * o[0][rg] + o[1][rg] * o[1][rg] + o[2][rg] * o[2][rg] + o[3][rg] * o[3][rg];
;         ss += __shfl_xor(ss, 1); ss += __shfl_xor(ss, 2); ss += __shfl_xor(ss, 4); ss += __shfl_xor(ss, 8); ss += __shfl_xor(ss, 16);
;         rs[rg] = 1.f / sqrtf(ss * (1.f / 128.f) + EPS); }
	v_fmac_f32_e32 v21, v137, v137
	v_fmac_f32_e32 v21, v105, v105
	v_fmac_f32_e32 v21, v18, v18
	s_nop 1
	v_add_f32_dpp v21, v21, v21 quad_perm:[1,0,3,2] row_mask:0xf bank_mask:0xf
	v_mul_f32_e32 v19, v19, v46
	s_nop 1
	v_add_f32_dpp v21, v21, v21 quad_perm:[2,3,0,1] row_mask:0xf bank_mask:0xf
	s_nop 1
	v_add_f32_dpp v21, v21, v21 row_half_mirror row_mask:0xf bank_mask:0xf
	s_nop 1
	v_add_f32_dpp v21, v21, v21 row_mirror row_mask:0xf bank_mask:0xf
	v_mov_b32_e32 v22, v21
	v_mov_b32_e32 v23, v21
	s_nop 1
	v_permlane16_swap_b32_e32 v22, v23
	v_add_f32_e32 v21, v22, v23
	v_fmamk_f32 v21, v21, 0x3c000000, v100
	v_cmp_gt_f32_e32 vcc, s34, v21
	v_mul_f32_e32 v22, 0x4f800000, v21
	s_nop 0
	v_cndmask_b32_e32 v21, v21, v22, vcc
	v_sqrt_f32_e32 v22, v21
	s_nop 0
	v_add_u32_e32 v23, -1, v22
	v_fma_f32 v24, -v23, v22, v21
	v_cmp_ge_f32_e64 s[4:5], 0, v24
	v_add_u32_e32 v24, 1, v22
	s_nop 0
	v_cndmask_b32_e64 v23, v22, v23, s[4:5]
	v_fma_f32 v22, -v24, v22, v21
	v_cmp_lt_f32_e64 s[4:5], 0, v22
	s_nop 1
	v_cndmask_b32_e64 v22, v23, v24, s[4:5]
	v_mul_f32_e32 v23, 0x37800000, v22
	v_cndmask_b32_e32 v22, v22, v23, vcc
	v_cmp_class_f32_e32 vcc, v21, v101
	s_nop 1
	v_cndmask_b32_e32 v21, v22, v21, vcc
	s_nop 0
	v_div_scale_f32 v24, vcc, 1.0, v21, 1.0
	v_rcp_f32_e32 v45, v21
	v_mul_f32_e32 v21, v120, v120
	v_fmac_f32_e32 v21, v136, v136
	v_fmac_f32_e32 v21, v104, v104
	v_fmac_f32_e32 v21, v17, v17
	s_nop 1
	v_add_f32_dpp v21, v21, v21 quad_perm:[1,0,3,2] row_mask:0xf bank_mask:0xf
	v_mul_f32_e32 v18, v18, v45
	s_nop 1
	v_add_f32_dpp v21, v21, v21 quad_perm:[2,3,0,1] row_mask:0xf bank_mask:0xf
	s_nop 1
	v_add_f32_dpp v21, v21, v21 row_half_mirror row_mask:0xf bank_mask:0xf
	s_nop 1
	v_add_f32_dpp v21, v21, v21 row_mirror row_mask:0xf bank_mask:0xf
	v_mov_b32_e32 v22, v21
	v_mov_b32_e32 v23, v21
	s_nop 1
	v_permlane16_swap_b32_e32 v22, v23
	v_add_f32_e32 v21, v22, v23
	v_fmamk_f32 v21, v21, 0x3c000000, v100
	v_cmp_gt_f32_e32 vcc, s34, v21
	v_mul_f32_e32 v22, 0x4f800000, v21
	s_nop 0
	v_cndmask_b32_e32 v21, v21, v22, vcc
	v_sqrt_f32_e32 v22, v21
	s_nop 0
	v_add_u32_e32 v23, -1, v22
	v_fma_f32 v24, -v23, v22, v21
	v_cmp_ge_f32_e64 s[4:5], 0, v24
	v_add_u32_e32 v24, 1, v22
	s_nop 0
	v_cndmask_b32_e64 v23, v22, v23, s[4:5]
	v_fma_f32 v22, -v24, v22, v21
	v_cmp_lt_f32_e64 s[4:5], 0, v22
	s_nop 1
	v_cndmask_b32_e64 v22, v23, v24, s[4:5]
	v_mul_f32_e32 v23, 0x37800000, v22
	v_cndmask_b32_e32 v22, v22, v23, vcc
	v_cmp_class_f32_e32 vcc, v21, v101
	s_nop 1
	v_cndmask_b32_e32 v21, v22, v21, vcc
	s_nop 0
	v_div_scale_f32 v24, vcc, 1.0, v21, 1.0
	v_rcp_f32_e32 v44, v21
	v_mul_f32_e32 v21, v119, v119
	v_fmac_f32_e32 v21, v135, v135
	v_fmac_f32_e32 v21, v103, v103
	v_fmac_f32_e32 v21, v16, v16
	s_nop 1
	v_add_f32_dpp v21, v21, v21 quad_perm:[1,0,3,2] row_mask:0xf bank_mask:0xf
	v_mul_f32_e32 v17, v17, v44
	s_nop 1
	v_add_f32_dpp v21, v21, v21 quad_perm:[2,3,0,1] row_mask:0xf bank_mask:0xf
	s_nop 1
	v_add_f32_dpp v21, v21, v21 row_half_mirror row_mask:0xf bank_mask:0xf
	s_nop 1
	v_add_f32_dpp v21, v21, v21 row_mirror row_mask:0xf bank_mask:0xf
	v_mov_b32_e32 v22, v21
	v_mov_b32_e32 v23, v21
	s_nop 1
	v_permlane16_swap_b32_e32 v22, v23
	v_add_f32_e32 v21, v22, v23
	v_fmamk_f32 v21, v21, 0x3c000000, v100
	v_cmp_gt_f32_e32 vcc, s34, v21
	v_mul_f32_e32 v22, 0x4f800000, v21
	s_nop 0
	v_cndmask_b32_e32 v21, v21, v22, vcc
	v_sqrt_f32_e32 v22, v21
	s_nop 0
	v_add_u32_e32 v23, -1, v22
	v_fma_f32 v24, -v23, v22, v21
	v_cmp_ge_f32_e64 s[4:5], 0, v24
	v_add_u32_e32 v24, 1, v22
	s_nop 0
	v_cndmask_b32_e64 v23, v22, v23, s[4:5]
	v_fma_f32 v22, -v24, v22, v21
	v_cmp_lt_f32_e64 s[4:5], 0, v22
	s_nop 1
	v_cndmask_b32_e64 v22, v23, v24, s[4:5]
	v_mul_f32_e32 v23, 0x37800000, v22
	v_cndmask_b32_e32 v22, v22, v23, vcc
	v_cmp_class_f32_e32 vcc, v21, v101
	s_nop 1
	v_cndmask_b32_e32 v21, v22, v21, vcc
	s_nop 0
	v_div_scale_f32 v24, vcc, 1.0, v21, 1.0
	v_rcp_f32_e32 v43, v21
	v_mul_f32_e32 v21, v118, v118
	v_fmac_f32_e32 v21, v134, v134
	v_fmac_f32_e32 v21, v102, v102
	v_fmac_f32_e32 v21, v15, v15
	s_nop 1
	v_add_f32_dpp v21, v21, v21 quad_perm:[1,0,3,2] row_mask:0xf bank_mask:0xf
	v_mul_f32_e32 v16, v16, v43
	s_nop 1
	v_add_f32_dpp v21, v21, v21 quad_perm:[2,3,0,1] row_mask:0xf bank_mask:0xf
	s_nop 1
	v_add_f32_dpp v21, v21, v21 row_half_mirror row_mask:0xf bank_mask:0xf
	s_nop 1
	v_add_f32_dpp v21, v21, v21 row_mirror row_mask:0xf bank_mask:0xf
	v_mov_b32_e32 v22, v21
	v_mov_b32_e32 v23, v21
	s_nop 1
	v_permlane16_swap_b32_e32 v22, v23
	v_add_f32_e32 v21, v22, v23
	v_fmamk_f32 v21, v21, 0x3c000000, v100
	v_cmp_gt_f32_e32 vcc, s34, v21
	v_mul_f32_e32 v22, 0x4f800000, v21
	s_nop 0
	v_cndmask_b32_e32 v21, v21, v22, vcc
	v_sqrt_f32_e32 v22, v21
	s_nop 0
	v_add_u32_e32 v23, -1, v22
	v_fma_f32 v24, -v23, v22, v21
	v_cmp_ge_f32_e64 s[4:5], 0, v24
	v_add_u32_e32 v24, 1, v22
	s_nop 0
	v_cndmask_b32_e64 v23, v22, v23, s[4:5]
	v_fma_f32 v22, -v24, v22, v21
	v_cmp_lt_f32_e64 s[4:5], 0, v22
	s_nop 1
	v_cndmask_b32_e64 v22, v23, v24, s[4:5]
	v_mul_f32_e32 v23, 0x37800000, v22
	v_cndmask_b32_e32 v22, v22, v23, vcc
	v_cmp_class_f32_e32 vcc, v21, v101
	s_nop 1
	v_cndmask_b32_e32 v21, v22, v21, vcc
	s_nop 0
	v_div_scale_f32 v24, vcc, 1.0, v21, 1.0
	v_rcp_f32_e32 v42, v21
	v_mul_f32_e32 v21, v117, v117
	v_fmac_f32_e32 v21, v133, v133
	v_fmac_f32_e32 v21, v39, v39
	v_fmac_f32_e32 v21, v14, v14
	s_nop 1
	v_add_f32_dpp v21, v21, v21 quad_perm:[1,0,3,2] row_mask:0xf bank_mask:0xf
	v_mul_f32_e32 v15, v15, v42
	s_nop 1
	v_add_f32_dpp v21, v21, v21 quad_perm:[2,3,0,1] row_mask:0xf bank_mask:0xf
	s_nop 1
	v_add_f32_dpp v21, v21, v21 row_half_mirror row_mask:0xf bank_mask:0xf
	s_nop 1
	v_add_f32_dpp v21, v21, v21 row_mirror row_mask:0xf bank_mask:0xf
; DI void gla_stage3(const Ctx& c0, int layer, int unit, int cb, LAS unsigned char* lds) {
;     ...
;     float rs[16];
; #pragma unroll
;     for (int rg = 0; rg < 16; ++rg) { float ss = o[0][rg] * o[0][rg] + o[1][rg] * o[1][rg] + o[2][rg] * o[2][rg] + o[3][rg] * o[3][rg];
;         ss += __shfl_xor(ss, 1); ss += __shfl_xor(ss, 2); ss += __shfl_xor(ss, 4); ss += __shfl_xor(ss, 8); ss += __shfl_xor(ss, 16);
;         rs[rg] = 1.f / sqrtf(ss * (1.f / 128.f) + EPS); }
	v_mov_b32_e32 v22, v21
	v_mov_b32_e32 v23, v21
	s_nop 1
	v_permlane16_swap_b32_e32 v22, v23
	v_add_f32_e32 v21, v22, v23
	v_fmamk_f32 v21, v21, 0x3c000000, v100
	v_cmp_gt_f32_e32 vcc, s34, v21
	v_mul_f32_e32 v22, 0x4f800000, v21
	s_nop 0
	v_cndmask_b32_e32 v21, v21, v22, vcc
	v_sqrt_f32_e32 v22, v21
	s_nop 0
	v_add_u32_e32 v23, -1, v22
	v_fma_f32 v24, -v23, v22, v21
	v_cmp_ge_f32_e64 s[4:5], 0, v24
	v_add_u32_e32 v24, 1, v22
	s_nop 0
	v_cndmask_b32_e64 v23, v22, v23, s[4:5]
	v_fma_f32 v22, -v24, v22, v21
	v_cmp_lt_f32_e64 s[4:5], 0, v22
	s_nop 1
	v_cndmask_b32_e64 v22, v23, v24, s[4:5]
	v_mul_f32_e32 v23, 0x37800000, v22
	v_cndmask_b32_e32 v22, v22, v23, vcc
	v_cmp_class_f32_e32 vcc, v21, v101
	s_nop 1
	v_cndmask_b32_e32 v21, v22, v21, vcc
	s_nop 0
	v_div_scale_f32 v24, vcc, 1.0, v21, 1.0
	v_rcp_f32_e32 v41, v21
	v_mul_f32_e32 v21, v116, v116
	v_fmac_f32_e32 v21, v132, v132
	v_fmac_f32_e32 v21, v38, v38
	v_fmac_f32_e32 v21, v13, v13
	s_nop 1
	v_add_f32_dpp v21, v21, v21 quad_perm:[1,0,3,2] row_mask:0xf bank_mask:0xf
	v_mul_f32_e32 v39, v39, v41
	v_mul_f32_e32 v14, v14, v41
	s_nop 1
	v_add_f32_dpp v21, v21, v21 quad_perm:[2,3,0,1] row_mask:0xf bank_mask:0xf
	s_nop 1
	v_add_f32_dpp v21, v21, v21 row_half_mirror row_mask:0xf bank_mask:0xf
	s_nop 1
	v_add_f32_dpp v21, v21, v21 row_mirror row_mask:0xf bank_mask:0xf
	v_mov_b32_e32 v22, v21
	v_mov_b32_e32 v23, v21
	s_nop 1
	v_permlane16_swap_b32_e32 v22, v23
	v_add_f32_e32 v21, v22, v23
	v_fmamk_f32 v21, v21, 0x3c000000, v100
	v_cmp_gt_f32_e32 vcc, s34, v21
	v_mul_f32_e32 v22, 0x4f800000, v21
	s_nop 0
	v_cndmask_b32_e32 v21, v21, v22, vcc
	v_sqrt_f32_e32 v22, v21
	s_nop 0
	v_add_u32_e32 v23, -1, v22
	v_fma_f32 v24, -v23, v22, v21
	v_cmp_ge_f32_e64 s[4:5], 0, v24
	v_add_u32_e32 v24, 1, v22
	s_nop 0
	v_cndmask_b32_e64 v23, v22, v23, s[4:5]
	v_fma_f32 v22, -v24, v22, v21
	v_cmp_lt_f32_e64 s[4:5], 0, v22
	s_nop 1
	v_cndmask_b32_e64 v22, v23, v24, s[4:5]
	v_mul_f32_e32 v23, 0x37800000, v22
	v_cndmask_b32_e32 v22, v22, v23, vcc
	v_cmp_class_f32_e32 vcc, v21, v101
	s_nop 1
	v_cndmask_b32_e32 v21, v22, v21, vcc
	s_nop 0
	v_div_scale_f32 v24, vcc, 1.0, v21, 1.0
	v_rcp_f32_e32 v40, v21
	v_mul_f32_e32 v21, v115, v115
	v_fmac_f32_e32 v21, v131, v131
	v_fmac_f32_e32 v21, v37, v37
	v_fmac_f32_e32 v21, v12, v12
	s_nop 1
	v_add_f32_dpp v21, v21, v21 quad_perm:[1,0,3,2] row_mask:0xf bank_mask:0xf
	v_mul_f32_e32 v38, v38, v40
	v_mul_f32_e32 v13, v13, v40
	s_nop 1
	v_add_f32_dpp v21, v21, v21 quad_perm:[2,3,0,1] row_mask:0xf bank_mask:0xf
	s_nop 1
	v_add_f32_dpp v21, v21, v21 row_half_mirror row_mask:0xf bank_mask:0xf
	s_nop 1
	v_add_f32_dpp v21, v21, v21 row_mirror row_mask:0xf bank_mask:0xf
	v_mov_b32_e32 v22, v21
	v_mov_b32_e32 v23, v21
	s_nop 1
	v_permlane16_swap_b32_e32 v22, v23
	v_add_f32_e32 v21, v22, v23
	v_fmamk_f32 v21, v21, 0x3c000000, v100
	v_cmp_gt_f32_e32 vcc, s34, v21
	v_mul_f32_e32 v22, 0x4f800000, v21
	s_nop 0
	v_cndmask_b32_e32 v21, v21, v22, vcc
	v_sqrt_f32_e32 v22, v21
	s_nop 0
	v_add_u32_e32 v23, -1, v22
	v_fma_f32 v24, -v23, v22, v21
	v_cmp_ge_f32_e64 s[4:5], 0, v24
	v_add_u32_e32 v24, 1, v22
	s_nop 0
	v_cndmask_b32_e64 v23, v22, v23, s[4:5]
	v_fma_f32 v22, -v24, v22, v21
	v_cmp_lt_f32_e64 s[4:5], 0, v22
	s_nop 1
	v_cndmask_b32_e64 v22, v23, v24, s[4:5]
	v_mul_f32_e32 v23, 0x37800000, v22
	v_cndmask_b32_e32 v22, v22, v23, vcc
	v_cmp_class_f32_e32 vcc, v21, v101
	s_nop 1
	v_cndmask_b32_e32 v21, v22, v21, vcc
	s_nop 0
	v_div_scale_f32 v24, vcc, 1.0, v21, 1.0
	v_rcp_f32_e32 v35, v21
	v_mul_f32_e32 v21, v114, v114
	v_fmac_f32_e32 v21, v130, v130
	v_fmac_f32_e32 v21, v36, v36
	v_fmac_f32_e32 v21, v11, v11
	s_nop 1
	v_add_f32_dpp v21, v21, v21 quad_perm:[1,0,3,2] row_mask:0xf bank_mask:0xf
	v_mul_f32_e32 v37, v37, v35
	v_mul_f32_e32 v12, v12, v35
	s_nop 1
	v_add_f32_dpp v21, v21, v21 quad_perm:[2,3,0,1] row_mask:0xf bank_mask:0xf
	s_nop 1
	v_add_f32_dpp v21, v21, v21 row_half_mirror row_mask:0xf bank_mask:0xf
	s_nop 1
	v_add_f32_dpp v21, v21, v21 row_mirror row_mask:0xf bank_mask:0xf
	v_mov_b32_e32 v22, v21
	v_mov_b32_e32 v23, v21
	s_nop 1
	v_permlane16_swap_b32_e32 v22, v23
	v_add_f32_e32 v21, v22, v23
	v_fmamk_f32 v21, v21, 0x3c000000, v100
	v_cmp_gt_f32_e32 vcc, s34, v21
	v_mul_f32_e32 v22, 0x4f800000, v21
	s_nop 0
	v_cndmask_b32_e32 v21, v21, v22, vcc
	v_sqrt_f32_e32 v22, v21
	s_nop 0
	v_add_u32_e32 v23, -1, v22
	v_fma_f32 v24, -v23, v22, v21
	v_cmp_ge_f32_e64 s[4:5], 0, v24
	v_add_u32_e32 v24, 1, v22
	s_nop 0
	v_cndmask_b32_e64 v23, v22, v23, s[4:5]
	v_fma_f32 v22, -v24, v22, v21
	v_cmp_lt_f32_e64 s[4:5], 0, v22
	s_nop 1
	v_cndmask_b32_e64 v22, v23, v24, s[4:5]
	v_mul_f32_e32 v23, 0x37800000, v22
	v_cndmask_b32_e32 v22, v22, v23, vcc
	v_cmp_class_f32_e32 vcc, v21, v101
	s_nop 1
	v_cndmask_b32_e32 v21, v22, v21, vcc
	s_nop 0
	v_div_scale_f32 v24, vcc, 1.0, v21, 1.0
	v_rcp_f32_e32 v31, v21
	v_mul_f32_e32 v21, v113, v113
	v_fmac_f32_e32 v21, v129, v129
	v_fmac_f32_e32 v21, v34, v34
	v_fmac_f32_e32 v21, v10, v10
	s_nop 1
	v_add_f32_dpp v21, v21, v21 quad_perm:[1,0,3,2] row_mask:0xf bank_mask:0xf
	v_mul_f32_e32 v36, v36, v31
	v_mul_f32_e32 v11, v11, v31
	s_nop 1
	v_add_f32_dpp v21, v21, v21 quad_perm:[2,3,0,1] row_mask:0xf bank_mask:0xf
	s_nop 1
	v_add_f32_dpp v21, v21, v21 row_half_mirror row_mask:0xf bank_mask:0xf
	s_nop 1
	v_add_f32_dpp v21, v21, v21 row_mirror row_mask:0xf bank_mask:0xf
	v_mov_b32_e32 v22, v21
	v_mov_b32_e32 v23, v21
	s_nop 1
	v_permlane16_swap_b32_e32 v22, v23
	v_add_f32_e32 v21, v22, v23
	v_fmamk_f32 v21, v21, 0x3c000000, v100
	v_cmp_gt_f32_e32 vcc, s34, v21
	v_mul_f32_e32 v22, 0x4f800000, v21
	s_nop 0
	v_cndmask_b32_e32 v21, v21, v22, vcc
	v_sqrt_f32_e32 v22, v21
	s_nop 0
; DI void gla_stage3(const Ctx& c0, int layer, int unit, int cb, LAS unsigned char* lds) {
;     ...
;     float rs[16];
; #pragma unroll
;     for (int rg = 0; rg < 16; ++rg) { float ss = o[0][rg] * o[0][rg] + o[1][rg] * o[1][rg] + o[2][rg] * o[2][rg] + o[3][rg] * o[3][rg];
;         ss += __shfl_xor(ss, 1); ss += __shfl_xor(ss, 2); ss += __shfl_xor(ss, 4); ss += __shfl_xor(ss, 8); ss += __shfl_xor(ss, 16);
;         rs[rg] = 1.f / sqrtf(ss * (1.f / 128.f) + EPS); }
	v_add_u32_e32 v23, -1, v22
	v_fma_f32 v24, -v23, v22, v21
	v_cmp_ge_f32_e64 s[4:5], 0, v24
	v_add_u32_e32 v24, 1, v22
	s_nop 0
	v_cndmask_b32_e64 v23, v22, v23, s[4:5]
	v_fma_f32 v22, -v24, v22, v21
	v_cmp_lt_f32_e64 s[4:5], 0, v22
	s_nop 1
	v_cndmask_b32_e64 v22, v23, v24, s[4:5]
	v_mul_f32_e32 v23, 0x37800000, v22
	v_cndmask_b32_e32 v22, v22, v23, vcc
	v_cmp_class_f32_e32 vcc, v21, v101
	s_nop 1
	v_cndmask_b32_e32 v21, v22, v21, vcc
	s_nop 0
	v_div_scale_f32 v24, vcc, 1.0, v21, 1.0
	v_rcp_f32_e32 v27, v21
	v_mul_f32_e32 v21, v112, v112
	v_fmac_f32_e32 v21, v128, v128
	v_fmac_f32_e32 v21, v33, v33
	v_fmac_f32_e32 v21, v9, v9
	s_nop 1
	v_add_f32_dpp v21, v21, v21 quad_perm:[1,0,3,2] row_mask:0xf bank_mask:0xf
	v_mul_f32_e32 v34, v34, v27
	v_mul_f32_e32 v10, v10, v27
	s_nop 1
	v_add_f32_dpp v21, v21, v21 quad_perm:[2,3,0,1] row_mask:0xf bank_mask:0xf
	s_nop 1
	v_add_f32_dpp v21, v21, v21 row_half_mirror row_mask:0xf bank_mask:0xf
	s_nop 1
	v_add_f32_dpp v21, v21, v21 row_mirror row_mask:0xf bank_mask:0xf
	v_mov_b32_e32 v22, v21
	v_mov_b32_e32 v23, v21
	s_nop 1
	v_permlane16_swap_b32_e32 v22, v23
	v_add_f32_e32 v21, v22, v23
	v_fmamk_f32 v21, v21, 0x3c000000, v100
	v_cmp_gt_f32_e32 vcc, s34, v21
	v_mul_f32_e32 v22, 0x4f800000, v21
	s_nop 0
	v_cndmask_b32_e32 v21, v21, v22, vcc
	v_sqrt_f32_e32 v22, v21
	s_nop 0
	v_add_u32_e32 v23, -1, v22
	v_fma_f32 v24, -v23, v22, v21
	v_cmp_ge_f32_e64 s[4:5], 0, v24
	v_add_u32_e32 v24, 1, v22
	s_nop 0
	v_cndmask_b32_e64 v23, v22, v23, s[4:5]
	v_fma_f32 v22, -v24, v22, v21
	v_cmp_lt_f32_e64 s[4:5], 0, v22
	s_nop 1
	v_cndmask_b32_e64 v22, v23, v24, s[4:5]
	v_mul_f32_e32 v23, 0x37800000, v22
	v_cndmask_b32_e32 v22, v22, v23, vcc
	v_cmp_class_f32_e32 vcc, v21, v101
	s_nop 1
	v_cndmask_b32_e32 v21, v22, v21, vcc
	s_nop 0
	v_div_scale_f32 v24, vcc, 1.0, v21, 1.0
	v_rcp_f32_e32 v25, v21
	v_mul_f32_e32 v21, v111, v111
	v_fmac_f32_e32 v21, v127, v127
	v_fmac_f32_e32 v21, v32, v32
	v_fmac_f32_e32 v21, v8, v8
	s_nop 1
	v_add_f32_dpp v21, v21, v21 quad_perm:[1,0,3,2] row_mask:0xf bank_mask:0xf
	v_mul_f32_e32 v33, v33, v25
	v_mul_f32_e32 v9, v9, v25
	s_nop 1
	v_add_f32_dpp v21, v21, v21 quad_perm:[2,3,0,1] row_mask:0xf bank_mask:0xf
	s_nop 1
	v_add_f32_dpp v21, v21, v21 row_half_mirror row_mask:0xf bank_mask:0xf
	s_nop 1
	v_add_f32_dpp v21, v21, v21 row_mirror row_mask:0xf bank_mask:0xf
	v_mov_b32_e32 v22, v21
	v_mov_b32_e32 v23, v21
	s_nop 1
	v_permlane16_swap_b32_e32 v22, v23
	v_add_f32_e32 v21, v22, v23
	v_fmamk_f32 v21, v21, 0x3c000000, v100
	v_cmp_gt_f32_e32 vcc, s34, v21
	v_mul_f32_e32 v22, 0x4f800000, v21
	s_nop 0
	v_cndmask_b32_e32 v21, v21, v22, vcc
	v_sqrt_f32_e32 v22, v21
	s_nop 0
	v_add_u32_e32 v23, -1, v22
	v_fma_f32 v24, -v23, v22, v21
	v_cmp_ge_f32_e64 s[4:5], 0, v24
	v_add_u32_e32 v24, 1, v22
	s_nop 0
	v_cndmask_b32_e64 v23, v22, v23, s[4:5]
	v_fma_f32 v22, -v24, v22, v21
	v_cmp_lt_f32_e64 s[4:5], 0, v22
	s_nop 1
	v_cndmask_b32_e64 v22, v23, v24, s[4:5]
	v_mul_f32_e32 v23, 0x37800000, v22
	v_cndmask_b32_e32 v22, v22, v23, vcc
	v_cmp_class_f32_e32 vcc, v21, v101
	s_nop 1
	v_cndmask_b32_e32 v21, v22, v21, vcc
	s_nop 0
	v_div_scale_f32 v24, vcc, 1.0, v21, 1.0
	v_rcp_f32_e32 v24, v21
	v_mul_f32_e32 v21, v110, v110
	v_fmac_f32_e32 v21, v126, v126
	v_fmac_f32_e32 v21, v30, v30
	v_fmac_f32_e32 v21, v7, v7
	s_nop 1
	v_add_f32_dpp v21, v21, v21 quad_perm:[1,0,3,2] row_mask:0xf bank_mask:0xf
	v_mul_f32_e32 v32, v32, v24
	v_mul_f32_e32 v8, v8, v24
	s_nop 1
	v_add_f32_dpp v21, v21, v21 quad_perm:[2,3,0,1] row_mask:0xf bank_mask:0xf
	s_nop 1
	v_add_f32_dpp v21, v21, v21 row_half_mirror row_mask:0xf bank_mask:0xf
	s_nop 1
	v_add_f32_dpp v21, v21, v21 row_mirror row_mask:0xf bank_mask:0xf
	v_mov_b32_e32 v22, v21
	v_mov_b32_e32 v23, v21
	s_nop 1
	v_permlane16_swap_b32_e32 v22, v23
	v_add_f32_e32 v21, v22, v23
	v_fmamk_f32 v21, v21, 0x3c000000, v100
	v_cmp_gt_f32_e32 vcc, s34, v21
	v_mul_f32_e32 v22, 0x4f800000, v21
	s_nop 0
	v_cndmask_b32_e32 v21, v21, v22, vcc
	v_sqrt_f32_e32 v22, v21
	s_nop 0
	v_add_u32_e32 v23, -1, v22
	v_fma_f32 v49, -v23, v22, v21
	v_cmp_ge_f32_e64 s[4:5], 0, v49
	v_add_u32_e32 v49, 1, v22
	s_nop 0
	v_cndmask_b32_e64 v23, v22, v23, s[4:5]
	v_fma_f32 v22, -v49, v22, v21
	v_cmp_lt_f32_e64 s[4:5], 0, v22
	s_nop 1
	v_cndmask_b32_e64 v22, v23, v49, s[4:5]
	v_mul_f32_e32 v23, 0x37800000, v22
	v_cndmask_b32_e32 v22, v22, v23, vcc
	v_cmp_class_f32_e32 vcc, v21, v101
	s_nop 1
	v_cndmask_b32_e32 v21, v22, v21, vcc
	s_nop 0
	v_div_scale_f32 v49, vcc, 1.0, v21, 1.0
	v_rcp_f32_e32 v23, v21
	v_mul_f32_e32 v21, v109, v109
	v_fmac_f32_e32 v21, v125, v125
	v_fmac_f32_e32 v21, v29, v29
	v_fmac_f32_e32 v21, v6, v6
	s_nop 1
	v_add_f32_dpp v21, v21, v21 quad_perm:[1,0,3,2] row_mask:0xf bank_mask:0xf
	v_mul_f32_e32 v30, v30, v23
	v_mul_f32_e32 v7, v7, v23
	s_nop 1
	v_add_f32_dpp v21, v21, v21 quad_perm:[2,3,0,1] row_mask:0xf bank_mask:0xf
	s_nop 1
	v_add_f32_dpp v21, v21, v21 row_half_mirror row_mask:0xf bank_mask:0xf
	s_nop 1
	v_add_f32_dpp v21, v21, v21 row_mirror row_mask:0xf bank_mask:0xf
	v_mov_b32_e32 v22, v21
	v_mov_b32_e32 v49, v21
	s_nop 1
	v_permlane16_swap_b32_e32 v22, v49
	v_add_f32_e32 v21, v22, v49
	v_fmamk_f32 v21, v21, 0x3c000000, v100
	v_cmp_gt_f32_e32 vcc, s34, v21
	v_mul_f32_e32 v22, 0x4f800000, v21
	s_nop 0
	v_cndmask_b32_e32 v21, v21, v22, vcc
	v_sqrt_f32_e32 v22, v21
	s_nop 0
	v_add_u32_e32 v49, -1, v22
	v_fma_f32 v50, -v49, v22, v21
	v_cmp_ge_f32_e64 s[4:5], 0, v50
	v_add_u32_e32 v50, 1, v22
	s_nop 0
	v_cndmask_b32_e64 v49, v22, v49, s[4:5]
	v_fma_f32 v22, -v50, v22, v21
	v_cmp_lt_f32_e64 s[4:5], 0, v22
	s_nop 1
	v_cndmask_b32_e64 v22, v49, v50, s[4:5]
	v_mul_f32_e32 v49, 0x37800000, v22
; #define LAS __attribute__((address_space(3)))
; #define LDS_WAIT() asm volatile("s_waitcnt lgkmcnt(0)" ::: "memory")
; DI unsigned cvtpk(float lo, float hi) { f32x2 v = {lo, hi}; bf16x2_t b = __builtin_convertvector(v, bf16x2_t); return __builtin_bit_cast(unsigned, b); }
; DI float bf2f(bf16 b) { return __uint_as_float(((unsigned)b) << 16); }
; DI float siluf_(float x) { return x / (1.f + __expf(-x)); }
; DI void g3_tile_in(const bf16* g, LAS unsigned char* R, int lane) {
; #pragma unroll
;     for (int it = 0; it < 8; ++it) { const int row = 4 * it + (lane >> 4), ch = lane & 15;
;         *(LAS u32x4*)(R + row * G3_PITCH + ch * 16) = *(const u32x4*)(g + (size_t)row * 512 + ch * 8); }
;     LDS_WAIT();
; DI void gla_stage3(const Ctx& c0, int layer, int unit, int cb, LAS unsigned char* lds) {
;     ...
;     for (int rg = 0; rg < 16; ++rg) { float ss = o[0][rg] * o[0][rg] + o[1][rg] * o[1][rg] + o[2][rg] * o[2][rg] + o[3][rg] * o[3][rg];
;         ss += __shfl_xor(ss, 1); ss += __shfl_xor(ss, 2); ss += __shfl_xor(ss, 4); ss += __shfl_xor(ss, 8); ss += __shfl_xor(ss, 16);
;         rs[rg] = 1.f / sqrtf(ss * (1.f / 128.f) + EPS); }
;     LDS_WAIT();
;     g3_tile_in((const bf16*)(c.ws + O_GR) + row0 * 512 + h * 128, R, lane);
; #pragma unroll
;     for (int vb = 0; vb < 4; ++vb) { const float g = gn[32 * vb + r];
; #pragma unroll
;         for (int rg = 0; rg < 16; ++rg) { LAS bf16* e = (LAS bf16*)(R + (4 * hi) * G3_PITCH + r * 2 + ((rg & 3) + 8 * (rg >> 2)) * G3_PITCH + 64 * vb);
;             const float z = bf2f(*e);
;             *e = (bf16)(cvtpk(o[vb][rg] * rs[rg] * g * siluf_(z), 0.f) & 0xffffu); }
	v_cndmask_b32_e32 v22, v22, v49, vcc
	v_cmp_class_f32_e32 vcc, v21, v101
	s_nop 1
	v_cndmask_b32_e32 v21, v22, v21, vcc
	s_nop 0
	v_div_scale_f32 v50, vcc, 1.0, v21, 1.0
	v_rcp_f32_e32 v22, v21
	v_mul_f32_e32 v21, v108, v108
	v_fmac_f32_e32 v21, v124, v124
	v_fmac_f32_e32 v21, v28, v28
	v_fmac_f32_e32 v21, v5, v5
	s_nop 1
	v_add_f32_dpp v21, v21, v21 quad_perm:[1,0,3,2] row_mask:0xf bank_mask:0xf
	v_mul_f32_e32 v29, v29, v22
	v_mul_f32_e32 v6, v6, v22
	s_nop 1
	v_add_f32_dpp v21, v21, v21 quad_perm:[2,3,0,1] row_mask:0xf bank_mask:0xf
	s_nop 1
	v_add_f32_dpp v21, v21, v21 row_half_mirror row_mask:0xf bank_mask:0xf
	s_nop 1
	v_add_f32_dpp v21, v21, v21 row_mirror row_mask:0xf bank_mask:0xf
	v_mov_b32_e32 v49, v21
	v_mov_b32_e32 v50, v21
	s_nop 1
	v_permlane16_swap_b32_e32 v49, v50
	v_add_f32_e32 v21, v49, v50
	v_fmamk_f32 v21, v21, 0x3c000000, v100
	v_cmp_gt_f32_e32 vcc, s34, v21
	v_mul_f32_e32 v49, 0x4f800000, v21
	s_nop 0
	v_cndmask_b32_e32 v21, v21, v49, vcc
	v_sqrt_f32_e32 v49, v21
	s_nop 0
	v_add_u32_e32 v50, -1, v49
	v_fma_f32 v51, -v50, v49, v21
	v_cmp_ge_f32_e64 s[4:5], 0, v51
	v_add_u32_e32 v51, 1, v49
	s_nop 0
	v_cndmask_b32_e64 v50, v49, v50, s[4:5]
	v_fma_f32 v49, -v51, v49, v21
	v_cmp_lt_f32_e64 s[4:5], 0, v49
	s_nop 1
	v_cndmask_b32_e64 v49, v50, v51, s[4:5]
	v_mul_f32_e32 v50, 0x37800000, v49
	v_cndmask_b32_e32 v49, v49, v50, vcc
	v_cmp_class_f32_e32 vcc, v21, v101
	s_nop 1
	v_cndmask_b32_e32 v21, v49, v21, vcc
	s_nop 0
	v_div_scale_f32 v51, vcc, 1.0, v21, 1.0
	v_rcp_f32_e32 v21, v21
	v_mul_f32_e32 v49, v107, v107
	v_fmac_f32_e32 v49, v123, v123
	v_fmac_f32_e32 v49, v26, v26
	v_fmac_f32_e32 v49, v4, v4
	ds_bpermute_b32 v2, v2, v49
	v_mul_f32_e32 v28, v28, v21
	v_mul_f32_e32 v5, v5, v21
	s_waitcnt lgkmcnt(0)
	v_add_f32_e32 v2, v49, v2
	ds_bpermute_b32 v3, v3, v2
	s_waitcnt lgkmcnt(0)
	v_add_f32_e32 v2, v2, v3
	ds_bpermute_b32 v3, v20, v2
	s_waitcnt lgkmcnt(0)
	v_add_f32_e32 v2, v2, v3
	ds_bpermute_b32 v3, v47, v2
	s_waitcnt lgkmcnt(0)
	v_add_f32_e32 v2, v2, v3
	ds_bpermute_b32 v3, v48, v2
	s_waitcnt lgkmcnt(0)
	v_add_f32_e32 v2, v2, v3
	v_fmamk_f32 v2, v2, 0x3c000000, v100
	v_cmp_gt_f32_e32 vcc, s34, v2
	v_mul_f32_e32 v3, 0x4f800000, v2
	s_nop 0
	v_cndmask_b32_e32 v2, v2, v3, vcc
	v_sqrt_f32_e32 v3, v2
	s_nop 0
	v_add_u32_e32 v20, -1, v3
	v_fma_f32 v47, -v20, v3, v2
	v_cmp_ge_f32_e64 s[4:5], 0, v47
	v_add_u32_e32 v47, 1, v3
	s_nop 0
	v_cndmask_b32_e64 v20, v3, v20, s[4:5]
	v_fma_f32 v3, -v47, v3, v2
	v_cmp_lt_f32_e64 s[4:5], 0, v3
	s_nop 1
	v_cndmask_b32_e64 v3, v20, v47, s[4:5]
	v_mul_f32_e32 v20, 0x37800000, v3
	v_cndmask_b32_e32 v3, v3, v20, vcc
	v_cmp_class_f32_e32 vcc, v2, v101
	s_nop 1
	v_cndmask_b32_e32 v2, v3, v2, vcc
	s_nop 0
	v_rcp_f32_e32 v20, v2
	v_mul_f32_e32 v47, v138, v46
	v_mul_f32_e32 v26, v26, v20
	v_mul_f32_e32 v4, v4, v20
	s_waitcnt vmcnt(2) lgkmcnt(0)
	ds_write_b128 v92, v[164:167]
	s_waitcnt vmcnt(0) lgkmcnt(0)
	ds_write_b128 v92, v[170:173] offset:1088
	s_waitcnt vmcnt(13) lgkmcnt(0)
	ds_write_b128 v92, v[174:177] offset:2176
	s_waitcnt vmcnt(8) lgkmcnt(0)
	ds_write_b128 v92, v[178:181] offset:3264
	s_waitcnt vmcnt(9) lgkmcnt(0)
	ds_write_b128 v92, v[196:199] offset:4352
	s_waitcnt vmcnt(10) lgkmcnt(0)
	ds_write_b128 v92, v[200:203] offset:5440
	v_lshl_add_u64 v[2:3], v[168:169], 0, v[80:81]
	s_waitcnt vmcnt(5) lgkmcnt(0)
	ds_write_b128 v92, v[204:207] offset:6528
	global_load_dwordx4 v[48:51], v[2:3], off
	s_waitcnt vmcnt(0) lgkmcnt(0)
	ds_write_b128 v92, v[48:51] offset:7616
	s_waitcnt lgkmcnt(0)
	ds_read_u16 v3, v1
	s_waitcnt lgkmcnt(0)
	v_lshlrev_b32_e32 v3, 16, v3
	v_mul_f32_e32 v48, 0xbfb8aa3b, v3
	v_exp_f32_e32 v48, v48
	s_waitcnt vmcnt(0)
	v_mul_f32_e32 v47, v47, v232
	v_add_f32_e32 v48, 1.0, v48
	v_div_scale_f32 v49, s[0:1], v48, v48, v3
	s_nop 0
	v_rcp_f32_e32 v49, v48
	s_nop 0
	v_mul_f32_e32 v3, v3, v49
	v_mul_f32_e32 v3, v47, v3
	v_cvt_pk_bf16_f32 v3, v3, s0
	ds_write_b16 v1, v3
	ds_read_u16 v3, v1 offset:272
	v_mul_f32_e32 v47, v137, v45
	v_mul_f32_e32 v47, v47, v232
	s_waitcnt lgkmcnt(0)
	v_lshlrev_b32_e32 v3, 16, v3
	v_mul_f32_e32 v48, 0xbfb8aa3b, v3
	v_exp_f32_e32 v48, v48
	s_nop 0
	v_add_f32_e32 v48, 1.0, v48
	v_div_scale_f32 v49, s[0:1], v48, v48, v3
	s_nop 0
	v_rcp_f32_e32 v49, v48
	s_nop 0
	v_mul_f32_e32 v3, v3, v49
	v_mul_f32_e32 v3, v47, v3
	v_cvt_pk_bf16_f32 v3, v3, s0
	ds_write_b16 v1, v3 offset:272
	ds_read_u16 v3, v1 offset:544
	v_mul_f32_e32 v47, v136, v44
	v_mul_f32_e32 v47, v47, v232
	s_waitcnt lgkmcnt(0)
	v_lshlrev_b32_e32 v3, 16, v3
	v_mul_f32_e32 v48, 0xbfb8aa3b, v3
	v_exp_f32_e32 v48, v48
	s_nop 0
	v_add_f32_e32 v48, 1.0, v48
	v_div_scale_f32 v49, s[0:1], v48, v48, v3
	s_nop 0
	v_rcp_f32_e32 v49, v48
	s_nop 0
	v_mul_f32_e32 v3, v3, v49
	v_mul_f32_e32 v3, v47, v3
	v_cvt_pk_bf16_f32 v3, v3, s0
	ds_write_b16 v1, v3 offset:544
	ds_read_u16 v3, v1 offset:816
	v_mul_f32_e32 v47, v135, v43
	v_mul_f32_e32 v47, v47, v232
	s_waitcnt lgkmcnt(0)
	v_lshlrev_b32_e32 v3, 16, v3
	v_mul_f32_e32 v48, 0xbfb8aa3b, v3
	v_exp_f32_e32 v48, v48
	s_nop 0
	v_add_f32_e32 v48, 1.0, v48
	v_div_scale_f32 v49, s[0:1], v48, v48, v3
	s_nop 0
	v_rcp_f32_e32 v49, v48
	s_nop 0
	v_mul_f32_e32 v3, v3, v49
	v_mul_f32_e32 v3, v47, v3
	v_cvt_pk_bf16_f32 v3, v3, s0
	ds_write_b16 v1, v3 offset:816
	ds_read_u16 v3, v1 offset:2176
	v_mul_f32_e32 v47, v134, v42
	v_mul_f32_e32 v47, v47, v232
	s_waitcnt lgkmcnt(0)
	v_lshlrev_b32_e32 v3, 16, v3
	v_mul_f32_e32 v48, 0xbfb8aa3b, v3
	v_exp_f32_e32 v48, v48
	s_nop 0
	v_add_f32_e32 v48, 1.0, v48
	v_div_scale_f32 v49, s[0:1], v48, v48, v3
	s_nop 0
	v_rcp_f32_e32 v49, v48
	s_nop 0
	v_mul_f32_e32 v3, v3, v49
	v_mul_f32_e32 v3, v47, v3
	v_cvt_pk_bf16_f32 v3, v3, s0
	ds_write_b16 v1, v3 offset:2176
	ds_read_u16 v3, v1 offset:2448
	v_mul_f32_e32 v47, v133, v41
	v_mul_f32_e32 v47, v47, v232
	s_waitcnt lgkmcnt(0)
; #define LAS __attribute__((address_space(3)))
; DI unsigned cvtpk(float lo, float hi) { f32x2 v = {lo, hi}; bf16x2_t b = __builtin_convertvector(v, bf16x2_t); return __builtin_bit_cast(unsigned, b); }
; DI float bf2f(bf16 b) { return __uint_as_float(((unsigned)b) << 16); }
; DI float siluf_(float x) { return x / (1.f + __expf(-x)); }
; DI void gla_stage3(const Ctx& c0, int layer, int unit, int cb, LAS unsigned char* lds) {
;     ...
; #pragma unroll
;     for (int vb = 0; vb < 4; ++vb) { const float g = gn[32 * vb + r];
; #pragma unroll
;         for (int rg = 0; rg < 16; ++rg) { LAS bf16* e = (LAS bf16*)(R + (4 * hi) * G3_PITCH + r * 2 + ((rg & 3) + 8 * (rg >> 2)) * G3_PITCH + 64 * vb);
;             const float z = bf2f(*e);
;             *e = (bf16)(cvtpk(o[vb][rg] * rs[rg] * g * siluf_(z), 0.f) & 0xffffu); }
;         asm volatile("" ::: "memory"); }
	v_lshlrev_b32_e32 v3, 16, v3
	v_mul_f32_e32 v48, 0xbfb8aa3b, v3
	v_exp_f32_e32 v48, v48
	s_nop 0
	v_add_f32_e32 v48, 1.0, v48
	v_div_scale_f32 v49, s[0:1], v48, v48, v3
	s_nop 0
	v_rcp_f32_e32 v49, v48
	s_nop 0
	v_mul_f32_e32 v3, v3, v49
	v_mul_f32_e32 v3, v47, v3
	v_cvt_pk_bf16_f32 v3, v3, s0
	ds_write_b16 v1, v3 offset:2448
	ds_read_u16 v3, v1 offset:2720
	v_mul_f32_e32 v47, v132, v40
	v_mul_f32_e32 v47, v47, v232
	s_waitcnt lgkmcnt(0)
	v_lshlrev_b32_e32 v3, 16, v3
	v_mul_f32_e32 v48, 0xbfb8aa3b, v3
	v_exp_f32_e32 v48, v48
	s_nop 0
	v_add_f32_e32 v48, 1.0, v48
	v_div_scale_f32 v49, s[0:1], v48, v48, v3
	s_nop 0
	v_rcp_f32_e32 v49, v48
	s_nop 0
	v_mul_f32_e32 v3, v3, v49
	v_mul_f32_e32 v3, v47, v3
	v_cvt_pk_bf16_f32 v3, v3, s0
	ds_write_b16 v1, v3 offset:2720
	ds_read_u16 v3, v1 offset:2992
	v_mul_f32_e32 v47, v131, v35
	v_mul_f32_e32 v47, v47, v232
	s_waitcnt lgkmcnt(0)
	v_lshlrev_b32_e32 v3, 16, v3
	v_mul_f32_e32 v48, 0xbfb8aa3b, v3
	v_exp_f32_e32 v48, v48
	s_nop 0
	v_add_f32_e32 v48, 1.0, v48
	v_div_scale_f32 v49, s[0:1], v48, v48, v3
	s_nop 0
	v_rcp_f32_e32 v49, v48
	s_nop 0
	v_mul_f32_e32 v3, v3, v49
	v_mul_f32_e32 v3, v47, v3
	v_cvt_pk_bf16_f32 v3, v3, s0
	ds_write_b16 v1, v3 offset:2992
	ds_read_u16 v3, v1 offset:4352
	v_mul_f32_e32 v47, v130, v31
	v_mul_f32_e32 v47, v47, v232
	s_waitcnt lgkmcnt(0)
	v_lshlrev_b32_e32 v3, 16, v3
	v_mul_f32_e32 v48, 0xbfb8aa3b, v3
	v_exp_f32_e32 v48, v48
	s_nop 0
	v_add_f32_e32 v48, 1.0, v48
	v_div_scale_f32 v49, s[0:1], v48, v48, v3
	s_nop 0
	v_rcp_f32_e32 v49, v48
	s_nop 0
	v_mul_f32_e32 v3, v3, v49
	v_mul_f32_e32 v3, v47, v3
	v_cvt_pk_bf16_f32 v3, v3, s0
	ds_write_b16 v1, v3 offset:4352
	ds_read_u16 v3, v1 offset:4624
	v_mul_f32_e32 v47, v129, v27
	v_mul_f32_e32 v47, v47, v232
	s_waitcnt lgkmcnt(0)
	v_lshlrev_b32_e32 v3, 16, v3
	v_mul_f32_e32 v48, 0xbfb8aa3b, v3
	v_exp_f32_e32 v48, v48
	s_nop 0
	v_add_f32_e32 v48, 1.0, v48
	v_div_scale_f32 v49, s[0:1], v48, v48, v3
	s_nop 0
	v_rcp_f32_e32 v49, v48
	s_nop 0
	v_mul_f32_e32 v3, v3, v49
	v_mul_f32_e32 v3, v47, v3
	v_cvt_pk_bf16_f32 v3, v3, s0
	ds_write_b16 v1, v3 offset:4624
	ds_read_u16 v3, v1 offset:4896
	v_mul_f32_e32 v47, v128, v25
	v_mul_f32_e32 v47, v47, v232
	s_waitcnt lgkmcnt(0)
	v_lshlrev_b32_e32 v3, 16, v3
	v_mul_f32_e32 v48, 0xbfb8aa3b, v3
	v_exp_f32_e32 v48, v48
	s_nop 0
	v_add_f32_e32 v48, 1.0, v48
	v_div_scale_f32 v49, s[0:1], v48, v48, v3
	s_nop 0
	v_rcp_f32_e32 v49, v48
	s_nop 0
	v_mul_f32_e32 v3, v3, v49
	v_mul_f32_e32 v3, v47, v3
	v_cvt_pk_bf16_f32 v3, v3, s0
	ds_write_b16 v1, v3 offset:4896
	ds_read_u16 v3, v1 offset:5168
	v_mul_f32_e32 v47, v127, v24
	v_mul_f32_e32 v47, v47, v232
	s_waitcnt lgkmcnt(0)
	v_lshlrev_b32_e32 v3, 16, v3
	v_mul_f32_e32 v48, 0xbfb8aa3b, v3
	v_exp_f32_e32 v48, v48
	s_nop 0
	v_add_f32_e32 v48, 1.0, v48
	v_div_scale_f32 v49, s[0:1], v48, v48, v3
	s_nop 0
	v_rcp_f32_e32 v49, v48
	s_nop 0
	v_mul_f32_e32 v3, v3, v49
	v_mul_f32_e32 v3, v47, v3
	v_cvt_pk_bf16_f32 v3, v3, s0
	ds_write_b16 v1, v3 offset:5168
	ds_read_u16 v3, v1 offset:6528
	v_mul_f32_e32 v47, v126, v23
	v_mul_f32_e32 v47, v47, v232
	s_waitcnt lgkmcnt(0)
	v_lshlrev_b32_e32 v3, 16, v3
	v_mul_f32_e32 v48, 0xbfb8aa3b, v3
	v_exp_f32_e32 v48, v48
	s_nop 0
	v_add_f32_e32 v48, 1.0, v48
	v_div_scale_f32 v49, s[0:1], v48, v48, v3
	s_nop 0
	v_rcp_f32_e32 v49, v48
	s_nop 0
	v_mul_f32_e32 v3, v3, v49
	v_mul_f32_e32 v3, v47, v3
	v_cvt_pk_bf16_f32 v3, v3, s0
	ds_write_b16 v1, v3 offset:6528
	ds_read_u16 v3, v1 offset:6800
	v_mul_f32_e32 v47, v125, v22
	v_mul_f32_e32 v47, v47, v232
	s_waitcnt lgkmcnt(0)
	v_lshlrev_b32_e32 v3, 16, v3
	v_mul_f32_e32 v48, 0xbfb8aa3b, v3
	v_exp_f32_e32 v48, v48
	s_nop 0
	v_add_f32_e32 v48, 1.0, v48
	v_div_scale_f32 v49, s[0:1], v48, v48, v3
	s_nop 0
	v_rcp_f32_e32 v49, v48
	s_nop 0
	v_mul_f32_e32 v3, v3, v49
	v_mul_f32_e32 v3, v47, v3
	v_cvt_pk_bf16_f32 v3, v3, s0
	ds_write_b16 v1, v3 offset:6800
	ds_read_u16 v3, v1 offset:7072
	v_mul_f32_e32 v47, v124, v21
	v_mul_f32_e32 v47, v47, v232
	s_waitcnt lgkmcnt(0)
	v_lshlrev_b32_e32 v3, 16, v3
	v_mul_f32_e32 v48, 0xbfb8aa3b, v3
	v_exp_f32_e32 v48, v48
	s_nop 0
	v_add_f32_e32 v48, 1.0, v48
	v_div_scale_f32 v49, s[0:1], v48, v48, v3
	s_nop 0
	v_rcp_f32_e32 v49, v48
	s_nop 0
	v_mul_f32_e32 v3, v3, v49
	v_mul_f32_e32 v3, v47, v3
	v_cvt_pk_bf16_f32 v3, v3, s0
	ds_write_b16 v1, v3 offset:7072
	ds_read_u16 v3, v1 offset:7344
	v_mul_f32_e32 v47, v123, v20
	v_mul_f32_e32 v2, v47, v232
	s_waitcnt lgkmcnt(0)
	v_lshlrev_b32_e32 v3, 16, v3
	v_mul_f32_e32 v47, 0xbfb8aa3b, v3
	v_exp_f32_e32 v47, v47
	s_nop 0
	v_add_f32_e32 v47, 1.0, v47
	v_div_scale_f32 v48, s[0:1], v47, v47, v3
	s_nop 0
	v_rcp_f32_e32 v48, v47
	s_nop 0
	v_mul_f32_e32 v3, v3, v48
	v_mul_f32_e32 v2, v2, v3
	v_cvt_pk_bf16_f32 v2, v2, s0
	ds_write_b16 v1, v2 offset:7344
	ds_read_u16 v3, v1 offset:64
	v_mul_f32_e32 v47, v122, v46
	s_waitcnt lgkmcnt(0)
	v_lshlrev_b32_e32 v3, 16, v3
	v_mul_f32_e32 v48, 0xbfb8aa3b, v3
	v_exp_f32_e32 v48, v48
	s_waitcnt vmcnt(0)
	v_mul_f32_e32 v47, v47, v234
	v_add_f32_e32 v48, 1.0, v48
	v_div_scale_f32 v49, s[0:1], v48, v48, v3
	s_nop 0
	v_rcp_f32_e32 v49, v48
	s_nop 0
	v_mul_f32_e32 v3, v3, v49
	v_mul_f32_e32 v3, v47, v3
	v_cvt_pk_bf16_f32 v3, v3, s0
	ds_write_b16 v1, v3 offset:64
	ds_read_u16 v3, v1 offset:336
	v_mul_f32_e32 v47, v121, v45
	v_mul_f32_e32 v47, v47, v234
	s_waitcnt lgkmcnt(0)
	v_lshlrev_b32_e32 v3, 16, v3
	v_mul_f32_e32 v48, 0xbfb8aa3b, v3
	v_exp_f32_e32 v48, v48
	s_nop 0
	v_add_f32_e32 v48, 1.0, v48
	v_div_scale_f32 v49, s[0:1], v48, v48, v3
	s_nop 0
	v_rcp_f32_e32 v49, v48
	s_nop 0
	v_mul_f32_e32 v3, v3, v49
	v_mul_f32_e32 v3, v47, v3
	v_cvt_pk_bf16_f32 v3, v3, s0
	ds_write_b16 v1, v3 offset:336
	ds_read_u16 v3, v1 offset:608
	v_mul_f32_e32 v47, v120, v44
	v_mul_f32_e32 v47, v47, v234
	s_waitcnt lgkmcnt(0)
; #define LAS __attribute__((address_space(3)))
; DI unsigned cvtpk(float lo, float hi) { f32x2 v = {lo, hi}; bf16x2_t b = __builtin_convertvector(v, bf16x2_t); return __builtin_bit_cast(unsigned, b); }
; DI float bf2f(bf16 b) { return __uint_as_float(((unsigned)b) << 16); }
; DI float siluf_(float x) { return x / (1.f + __expf(-x)); }
; DI void gla_stage3(const Ctx& c0, int layer, int unit, int cb, LAS unsigned char* lds) {
;     ...
; #pragma unroll
;     for (int vb = 0; vb < 4; ++vb) { const float g = gn[32 * vb + r];
; #pragma unroll
;         for (int rg = 0; rg < 16; ++rg) { LAS bf16* e = (LAS bf16*)(R + (4 * hi) * G3_PITCH + r * 2 + ((rg & 3) + 8 * (rg >> 2)) * G3_PITCH + 64 * vb);
;             const float z = bf2f(*e);
;             *e = (bf16)(cvtpk(o[vb][rg] * rs[rg] * g * siluf_(z), 0.f) & 0xffffu); }
;         asm volatile("" ::: "memory"); }
	v_lshlrev_b32_e32 v3, 16, v3
	v_mul_f32_e32 v48, 0xbfb8aa3b, v3
	v_exp_f32_e32 v48, v48
	s_nop 0
	v_add_f32_e32 v48, 1.0, v48
	v_div_scale_f32 v49, s[0:1], v48, v48, v3
	s_nop 0
	v_rcp_f32_e32 v49, v48
	s_nop 0
	v_mul_f32_e32 v3, v3, v49
	v_mul_f32_e32 v3, v47, v3
	v_cvt_pk_bf16_f32 v3, v3, s0
	ds_write_b16 v1, v3 offset:608
	ds_read_u16 v3, v1 offset:880
	v_mul_f32_e32 v47, v119, v43
	v_mul_f32_e32 v47, v47, v234
	s_waitcnt lgkmcnt(0)
	v_lshlrev_b32_e32 v3, 16, v3
	v_mul_f32_e32 v48, 0xbfb8aa3b, v3
	v_exp_f32_e32 v48, v48
	s_nop 0
	v_add_f32_e32 v48, 1.0, v48
	v_div_scale_f32 v49, s[0:1], v48, v48, v3
	s_nop 0
	v_rcp_f32_e32 v49, v48
	s_nop 0
	v_mul_f32_e32 v3, v3, v49
	v_mul_f32_e32 v3, v47, v3
	v_cvt_pk_bf16_f32 v3, v3, s0
	ds_write_b16 v1, v3 offset:880
	ds_read_u16 v3, v1 offset:2240
	v_mul_f32_e32 v47, v118, v42
	v_mul_f32_e32 v47, v47, v234
	s_waitcnt lgkmcnt(0)
	v_lshlrev_b32_e32 v3, 16, v3
	v_mul_f32_e32 v48, 0xbfb8aa3b, v3
	v_exp_f32_e32 v48, v48
	s_nop 0
	v_add_f32_e32 v48, 1.0, v48
	v_div_scale_f32 v49, s[0:1], v48, v48, v3
	s_nop 0
	v_rcp_f32_e32 v49, v48
	s_nop 0
	v_mul_f32_e32 v3, v3, v49
	v_mul_f32_e32 v3, v47, v3
	v_cvt_pk_bf16_f32 v3, v3, s0
	ds_write_b16 v1, v3 offset:2240
	ds_read_u16 v3, v1 offset:2512
	v_mul_f32_e32 v47, v117, v41
	v_mul_f32_e32 v47, v47, v234
	s_waitcnt lgkmcnt(0)
	v_lshlrev_b32_e32 v3, 16, v3
	v_mul_f32_e32 v48, 0xbfb8aa3b, v3
	v_exp_f32_e32 v48, v48
	s_nop 0
	v_add_f32_e32 v48, 1.0, v48
	v_div_scale_f32 v49, s[0:1], v48, v48, v3
	s_nop 0
	v_rcp_f32_e32 v49, v48
	s_nop 0
	v_mul_f32_e32 v3, v3, v49
	v_mul_f32_e32 v3, v47, v3
	v_cvt_pk_bf16_f32 v3, v3, s0
	ds_write_b16 v1, v3 offset:2512
	ds_read_u16 v3, v1 offset:2784
	v_mul_f32_e32 v47, v116, v40
	v_mul_f32_e32 v47, v47, v234
	s_waitcnt lgkmcnt(0)
	v_lshlrev_b32_e32 v3, 16, v3
	v_mul_f32_e32 v48, 0xbfb8aa3b, v3
	v_exp_f32_e32 v48, v48
	s_nop 0
	v_add_f32_e32 v48, 1.0, v48
	v_div_scale_f32 v49, s[0:1], v48, v48, v3
	s_nop 0
	v_rcp_f32_e32 v49, v48
	s_nop 0
	v_mul_f32_e32 v3, v3, v49
	v_mul_f32_e32 v3, v47, v3
	v_cvt_pk_bf16_f32 v3, v3, s0
	ds_write_b16 v1, v3 offset:2784
	ds_read_u16 v3, v1 offset:3056
	v_mul_f32_e32 v47, v115, v35
	v_mul_f32_e32 v47, v47, v234
	s_waitcnt lgkmcnt(0)
	v_lshlrev_b32_e32 v3, 16, v3
	v_mul_f32_e32 v48, 0xbfb8aa3b, v3
	v_exp_f32_e32 v48, v48
	s_nop 0
	v_add_f32_e32 v48, 1.0, v48
	v_div_scale_f32 v49, s[0:1], v48, v48, v3
	s_nop 0
	v_rcp_f32_e32 v49, v48
	s_nop 0
	v_mul_f32_e32 v3, v3, v49
	v_mul_f32_e32 v3, v47, v3
	v_cvt_pk_bf16_f32 v3, v3, s0
	ds_write_b16 v1, v3 offset:3056
	ds_read_u16 v3, v1 offset:4416
	v_mul_f32_e32 v47, v114, v31
	v_mul_f32_e32 v47, v47, v234
	s_waitcnt lgkmcnt(0)
	v_lshlrev_b32_e32 v3, 16, v3
	v_mul_f32_e32 v48, 0xbfb8aa3b, v3
	v_exp_f32_e32 v48, v48
	s_nop 0
	v_add_f32_e32 v48, 1.0, v48
	v_div_scale_f32 v49, s[0:1], v48, v48, v3
	s_nop 0
	v_rcp_f32_e32 v49, v48
	s_nop 0
	v_mul_f32_e32 v3, v3, v49
	v_mul_f32_e32 v3, v47, v3
	v_cvt_pk_bf16_f32 v3, v3, s0
	ds_write_b16 v1, v3 offset:4416
	ds_read_u16 v3, v1 offset:4688
	v_mul_f32_e32 v47, v113, v27
	v_mul_f32_e32 v47, v47, v234
	s_waitcnt lgkmcnt(0)
	v_lshlrev_b32_e32 v3, 16, v3
	v_mul_f32_e32 v48, 0xbfb8aa3b, v3
	v_exp_f32_e32 v48, v48
	s_nop 0
	v_add_f32_e32 v48, 1.0, v48
	v_div_scale_f32 v49, s[0:1], v48, v48, v3
	s_nop 0
	v_rcp_f32_e32 v49, v48
	s_nop 0
	v_mul_f32_e32 v3, v3, v49
	v_mul_f32_e32 v3, v47, v3
	v_cvt_pk_bf16_f32 v3, v3, s0
	ds_write_b16 v1, v3 offset:4688
	ds_read_u16 v3, v1 offset:4960
	v_mul_f32_e32 v47, v112, v25
	v_mul_f32_e32 v47, v47, v234
	s_waitcnt lgkmcnt(0)
	v_lshlrev_b32_e32 v3, 16, v3
	v_mul_f32_e32 v48, 0xbfb8aa3b, v3
	v_exp_f32_e32 v48, v48
	s_nop 0
	v_add_f32_e32 v48, 1.0, v48
	v_div_scale_f32 v49, s[0:1], v48, v48, v3
	s_nop 0
	v_rcp_f32_e32 v49, v48
	s_nop 0
	v_mul_f32_e32 v3, v3, v49
	v_mul_f32_e32 v3, v47, v3
	v_cvt_pk_bf16_f32 v3, v3, s0
	ds_write_b16 v1, v3 offset:4960
	ds_read_u16 v3, v1 offset:5232
	v_mul_f32_e32 v47, v111, v24
	v_mul_f32_e32 v47, v47, v234
	s_waitcnt lgkmcnt(0)
	v_lshlrev_b32_e32 v3, 16, v3
	v_mul_f32_e32 v48, 0xbfb8aa3b, v3
	v_exp_f32_e32 v48, v48
	s_nop 0
	v_add_f32_e32 v48, 1.0, v48
	v_div_scale_f32 v49, s[0:1], v48, v48, v3
	s_nop 0
	v_rcp_f32_e32 v49, v48
	s_nop 0
	v_mul_f32_e32 v3, v3, v49
	v_mul_f32_e32 v3, v47, v3
	v_cvt_pk_bf16_f32 v3, v3, s0
	ds_write_b16 v1, v3 offset:5232
	ds_read_u16 v3, v1 offset:6592
	v_mul_f32_e32 v47, v110, v23
	v_mul_f32_e32 v47, v47, v234
	s_waitcnt lgkmcnt(0)
	v_lshlrev_b32_e32 v3, 16, v3
	v_mul_f32_e32 v48, 0xbfb8aa3b, v3
	v_exp_f32_e32 v48, v48
	s_nop 0
	v_add_f32_e32 v48, 1.0, v48
	v_div_scale_f32 v49, s[0:1], v48, v48, v3
	s_nop 0
	v_rcp_f32_e32 v49, v48
	s_nop 0
	v_mul_f32_e32 v3, v3, v49
	v_mul_f32_e32 v3, v47, v3
	v_cvt_pk_bf16_f32 v3, v3, s0
	ds_write_b16 v1, v3 offset:6592
	ds_read_u16 v3, v1 offset:6864
	v_mul_f32_e32 v47, v109, v22
	v_mul_f32_e32 v47, v47, v234
	s_waitcnt lgkmcnt(0)
	v_lshlrev_b32_e32 v3, 16, v3
	v_mul_f32_e32 v48, 0xbfb8aa3b, v3
	v_exp_f32_e32 v48, v48
	s_nop 0
	v_add_f32_e32 v48, 1.0, v48
	v_div_scale_f32 v49, s[0:1], v48, v48, v3
	s_nop 0
	v_rcp_f32_e32 v49, v48
	s_nop 0
	v_mul_f32_e32 v3, v3, v49
	v_mul_f32_e32 v3, v47, v3
	v_cvt_pk_bf16_f32 v3, v3, s0
	ds_write_b16 v1, v3 offset:6864
	ds_read_u16 v3, v1 offset:7136
	v_mul_f32_e32 v47, v108, v21
	v_mul_f32_e32 v47, v47, v234
	s_waitcnt lgkmcnt(0)
	v_lshlrev_b32_e32 v3, 16, v3
	v_mul_f32_e32 v48, 0xbfb8aa3b, v3
	v_exp_f32_e32 v48, v48
	s_nop 0
	v_add_f32_e32 v48, 1.0, v48
	v_div_scale_f32 v49, s[0:1], v48, v48, v3
	s_nop 0
	v_rcp_f32_e32 v49, v48
	s_nop 0
	v_mul_f32_e32 v3, v3, v49
	v_mul_f32_e32 v3, v47, v3
	v_cvt_pk_bf16_f32 v3, v3, s0
	ds_write_b16 v1, v3 offset:7136
	ds_read_u16 v3, v1 offset:7408
	v_mul_f32_e32 v47, v107, v20
	v_mul_f32_e32 v2, v47, v234
	s_waitcnt lgkmcnt(0)
; #define LAS __attribute__((address_space(3)))
; DI unsigned cvtpk(float lo, float hi) { f32x2 v = {lo, hi}; bf16x2_t b = __builtin_convertvector(v, bf16x2_t); return __builtin_bit_cast(unsigned, b); }
; DI float bf2f(bf16 b) { return __uint_as_float(((unsigned)b) << 16); }
; DI float siluf_(float x) { return x / (1.f + __expf(-x)); }
; DI void gla_stage3(const Ctx& c0, int layer, int unit, int cb, LAS unsigned char* lds) {
;     ...
; #pragma unroll
;     for (int vb = 0; vb < 4; ++vb) { const float g = gn[32 * vb + r];
; #pragma unroll
;         for (int rg = 0; rg < 16; ++rg) { LAS bf16* e = (LAS bf16*)(R + (4 * hi) * G3_PITCH + r * 2 + ((rg & 3) + 8 * (rg >> 2)) * G3_PITCH + 64 * vb);
;             const float z = bf2f(*e);
;             *e = (bf16)(cvtpk(o[vb][rg] * rs[rg] * g * siluf_(z), 0.f) & 0xffffu); }
;         asm volatile("" ::: "memory"); }
	v_lshlrev_b32_e32 v3, 16, v3
	v_mul_f32_e32 v47, 0xbfb8aa3b, v3
	v_exp_f32_e32 v47, v47
	s_nop 0
	v_add_f32_e32 v47, 1.0, v47
	v_div_scale_f32 v48, s[0:1], v47, v47, v3
	s_nop 0
	v_rcp_f32_e32 v48, v47
	s_nop 0
	v_mul_f32_e32 v3, v3, v48
	v_mul_f32_e32 v2, v2, v3
	v_cvt_pk_bf16_f32 v2, v2, s0
	ds_write_b16 v1, v2 offset:7408
	ds_read_u16 v3, v1 offset:128
	v_mul_f32_e32 v47, v106, v46
	s_waitcnt lgkmcnt(0)
	v_lshlrev_b32_e32 v3, 16, v3
	v_mul_f32_e32 v48, 0xbfb8aa3b, v3
	v_exp_f32_e32 v48, v48
	s_waitcnt vmcnt(0)
	v_mul_f32_e32 v47, v47, v236
	v_add_f32_e32 v48, 1.0, v48
	v_div_scale_f32 v49, s[0:1], v48, v48, v3
	v_mul_f32_e32 v39, v39, v236
	v_mul_f32_e32 v38, v38, v236
	v_mul_f32_e32 v37, v37, v236
	v_rcp_f32_e32 v49, v48
	s_nop 0
	v_mul_f32_e32 v3, v3, v49
	v_mul_f32_e32 v3, v47, v3
	v_cvt_pk_bf16_f32 v3, v3, s0
	ds_write_b16 v1, v3 offset:128
	ds_read_u16 v3, v1 offset:400
	v_mul_f32_e32 v47, v105, v45
	v_mul_f32_e32 v47, v47, v236
	v_mul_f32_e32 v36, v36, v236
	v_mul_f32_e32 v34, v34, v236
	s_waitcnt lgkmcnt(0)
	v_lshlrev_b32_e32 v3, 16, v3
	v_mul_f32_e32 v48, 0xbfb8aa3b, v3
	v_exp_f32_e32 v48, v48
	v_mul_f32_e32 v33, v33, v236
	v_mul_f32_e32 v32, v32, v236
	v_mul_f32_e32 v30, v30, v236
	v_add_f32_e32 v48, 1.0, v48
	v_div_scale_f32 v49, s[0:1], v48, v48, v3
	v_mul_f32_e32 v29, v29, v236
	v_mul_f32_e32 v28, v28, v236
	v_rcp_f32_e32 v49, v48
	s_nop 0
	v_mul_f32_e32 v3, v3, v49
	v_mul_f32_e32 v3, v47, v3
	v_cvt_pk_bf16_f32 v3, v3, s0
	ds_write_b16 v1, v3 offset:400
	ds_read_u16 v3, v1 offset:672
	v_mul_f32_e32 v47, v104, v44
	v_mul_f32_e32 v47, v47, v236
	s_waitcnt lgkmcnt(0)
	v_lshlrev_b32_e32 v3, 16, v3
	v_mul_f32_e32 v48, 0xbfb8aa3b, v3
	v_exp_f32_e32 v48, v48
	s_nop 0
	v_add_f32_e32 v48, 1.0, v48
	v_div_scale_f32 v49, s[0:1], v48, v48, v3
	s_nop 0
	v_rcp_f32_e32 v49, v48
	s_nop 0
	v_mul_f32_e32 v3, v3, v49
	v_mul_f32_e32 v3, v47, v3
	v_cvt_pk_bf16_f32 v3, v3, s0
	ds_write_b16 v1, v3 offset:672
	ds_read_u16 v3, v1 offset:944
	v_mul_f32_e32 v47, v103, v43
	v_mul_f32_e32 v47, v47, v236
	s_waitcnt lgkmcnt(0)
	v_lshlrev_b32_e32 v3, 16, v3
	v_mul_f32_e32 v48, 0xbfb8aa3b, v3
	v_exp_f32_e32 v48, v48
	s_nop 0
	v_add_f32_e32 v48, 1.0, v48
	v_div_scale_f32 v49, s[0:1], v48, v48, v3
	s_nop 0
	v_rcp_f32_e32 v49, v48
	s_nop 0
	v_mul_f32_e32 v3, v3, v49
	v_mul_f32_e32 v3, v47, v3
	v_cvt_pk_bf16_f32 v3, v3, s0
	ds_write_b16 v1, v3 offset:944
	ds_read_u16 v3, v1 offset:2304
	v_mul_f32_e32 v47, v102, v42
	v_mul_f32_e32 v47, v47, v236
	v_mul_f32_e32 v2, v26, v236
	s_waitcnt lgkmcnt(0)
	v_lshlrev_b32_e32 v3, 16, v3
	v_mul_f32_e32 v48, 0xbfb8aa3b, v3
	v_exp_f32_e32 v48, v48
	s_nop 0
	v_add_f32_e32 v48, 1.0, v48
	v_div_scale_f32 v49, s[0:1], v48, v48, v3
	s_nop 0
	v_rcp_f32_e32 v49, v48
	s_nop 0
	v_mul_f32_e32 v3, v3, v49
	v_mul_f32_e32 v3, v47, v3
	v_cvt_pk_bf16_f32 v3, v3, s0
	ds_write_b16 v1, v3 offset:2304
	ds_read_u16 v3, v1 offset:2576
	s_waitcnt lgkmcnt(0)
	v_lshlrev_b32_e32 v3, 16, v3
	v_mul_f32_e32 v47, 0xbfb8aa3b, v3
	v_exp_f32_e32 v47, v47
	s_nop 0
	v_add_f32_e32 v47, 1.0, v47
	v_div_scale_f32 v48, s[0:1], v47, v47, v3
	s_nop 0
	v_rcp_f32_e32 v48, v47
	s_nop 0
	v_mul_f32_e32 v3, v3, v48
	v_mul_f32_e32 v3, v39, v3
	v_cvt_pk_bf16_f32 v3, v3, s0
	ds_write_b16 v1, v3 offset:2576
	ds_read_u16 v3, v1 offset:2848
	s_waitcnt lgkmcnt(0)
	v_lshlrev_b32_e32 v3, 16, v3
	v_mul_f32_e32 v39, 0xbfb8aa3b, v3
	v_exp_f32_e32 v39, v39
	s_nop 0
	v_add_f32_e32 v39, 1.0, v39
	v_div_scale_f32 v47, s[0:1], v39, v39, v3
	s_nop 0
	v_rcp_f32_e32 v47, v39
	s_nop 0
	v_mul_f32_e32 v3, v3, v47
	v_mul_f32_e32 v3, v38, v3
	v_cvt_pk_bf16_f32 v3, v3, s0
	ds_write_b16 v1, v3 offset:2848
	ds_read_u16 v3, v1 offset:3120
	s_waitcnt lgkmcnt(0)
	v_lshlrev_b32_e32 v3, 16, v3
	v_mul_f32_e32 v38, 0xbfb8aa3b, v3
	v_exp_f32_e32 v38, v38
	s_nop 0
	v_add_f32_e32 v38, 1.0, v38
	v_div_scale_f32 v39, s[0:1], v38, v38, v3
	s_nop 0
	v_rcp_f32_e32 v39, v38
	s_nop 0
	v_mul_f32_e32 v3, v3, v39
	v_mul_f32_e32 v3, v37, v3
	v_cvt_pk_bf16_f32 v3, v3, s0
	ds_write_b16 v1, v3 offset:3120
	ds_read_u16 v3, v1 offset:4480
	s_waitcnt lgkmcnt(0)
	v_lshlrev_b32_e32 v3, 16, v3
	v_mul_f32_e32 v37, 0xbfb8aa3b, v3
	v_exp_f32_e32 v37, v37
	s_nop 0
	v_add_f32_e32 v37, 1.0, v37
	v_div_scale_f32 v38, s[0:1], v37, v37, v3
	s_nop 0
	v_rcp_f32_e32 v38, v37
	s_nop 0
	v_mul_f32_e32 v3, v3, v38
	v_mul_f32_e32 v3, v36, v3
	v_cvt_pk_bf16_f32 v3, v3, s0
	ds_write_b16 v1, v3 offset:4480
	ds_read_u16 v3, v1 offset:4752
	s_waitcnt lgkmcnt(0)
	v_lshlrev_b32_e32 v3, 16, v3
	v_mul_f32_e32 v36, 0xbfb8aa3b, v3
	v_exp_f32_e32 v36, v36
	s_nop 0
	v_add_f32_e32 v36, 1.0, v36
	v_div_scale_f32 v37, s[0:1], v36, v36, v3
	s_nop 0
	v_rcp_f32_e32 v37, v36
	s_nop 0
	v_mul_f32_e32 v3, v3, v37
	v_mul_f32_e32 v3, v34, v3
	v_cvt_pk_bf16_f32 v3, v3, s0
	ds_write_b16 v1, v3 offset:4752
	ds_read_u16 v3, v1 offset:5024
	s_waitcnt lgkmcnt(0)
	v_lshlrev_b32_e32 v3, 16, v3
	v_mul_f32_e32 v34, 0xbfb8aa3b, v3
	v_exp_f32_e32 v34, v34
	s_nop 0
	v_add_f32_e32 v34, 1.0, v34
	v_div_scale_f32 v36, s[0:1], v34, v34, v3
	s_nop 0
	v_rcp_f32_e32 v36, v34
	s_nop 0
	v_mul_f32_e32 v3, v3, v36
	v_mul_f32_e32 v3, v33, v3
	v_cvt_pk_bf16_f32 v3, v3, s0
	ds_write_b16 v1, v3 offset:5024
	ds_read_u16 v3, v1 offset:5296
	s_waitcnt lgkmcnt(0)
	v_lshlrev_b32_e32 v3, 16, v3
	v_mul_f32_e32 v33, 0xbfb8aa3b, v3
	v_exp_f32_e32 v33, v33
	s_nop 0
	v_add_f32_e32 v33, 1.0, v33
	v_div_scale_f32 v34, s[0:1], v33, v33, v3
	s_nop 0
	v_rcp_f32_e32 v34, v33
	s_nop 0
	v_mul_f32_e32 v3, v3, v34
	v_mul_f32_e32 v3, v32, v3
	v_cvt_pk_bf16_f32 v3, v3, s0
	ds_write_b16 v1, v3 offset:5296
	ds_read_u16 v3, v1 offset:6656
	s_waitcnt lgkmcnt(0)
; #define LAS __attribute__((address_space(3)))
; DI unsigned cvtpk(float lo, float hi) { f32x2 v = {lo, hi}; bf16x2_t b = __builtin_convertvector(v, bf16x2_t); return __builtin_bit_cast(unsigned, b); }
; DI float bf2f(bf16 b) { return __uint_as_float(((unsigned)b) << 16); }
; DI float siluf_(float x) { return x / (1.f + __expf(-x)); }
; DI void gla_stage3(const Ctx& c0, int layer, int unit, int cb, LAS unsigned char* lds) {
;     ...
; #pragma unroll
;     for (int vb = 0; vb < 4; ++vb) { const float g = gn[32 * vb + r];
; #pragma unroll
;         for (int rg = 0; rg < 16; ++rg) { LAS bf16* e = (LAS bf16*)(R + (4 * hi) * G3_PITCH + r * 2 + ((rg & 3) + 8 * (rg >> 2)) * G3_PITCH + 64 * vb);
;             const float z = bf2f(*e);
;             *e = (bf16)(cvtpk(o[vb][rg] * rs[rg] * g * siluf_(z), 0.f) & 0xffffu); }
;         asm volatile("" ::: "memory"); }
	v_lshlrev_b32_e32 v3, 16, v3
	v_mul_f32_e32 v32, 0xbfb8aa3b, v3
	v_exp_f32_e32 v32, v32
	s_nop 0
	v_add_f32_e32 v32, 1.0, v32
	v_div_scale_f32 v33, s[0:1], v32, v32, v3
	s_nop 0
	v_rcp_f32_e32 v33, v32
	s_nop 0
	v_mul_f32_e32 v3, v3, v33
	v_mul_f32_e32 v3, v30, v3
	v_cvt_pk_bf16_f32 v3, v3, s0
	ds_write_b16 v1, v3 offset:6656
	ds_read_u16 v3, v1 offset:6928
	s_waitcnt lgkmcnt(0)
	v_lshlrev_b32_e32 v3, 16, v3
	v_mul_f32_e32 v30, 0xbfb8aa3b, v3
	v_exp_f32_e32 v30, v30
	s_nop 0
	v_add_f32_e32 v30, 1.0, v30
	v_div_scale_f32 v32, s[0:1], v30, v30, v3
	s_nop 0
	v_rcp_f32_e32 v32, v30
	s_nop 0
	v_mul_f32_e32 v3, v3, v32
	v_mul_f32_e32 v3, v29, v3
	v_cvt_pk_bf16_f32 v3, v3, s0
	ds_write_b16 v1, v3 offset:6928
	ds_read_u16 v3, v1 offset:7200
	s_waitcnt lgkmcnt(0)
	v_lshlrev_b32_e32 v3, 16, v3
	v_mul_f32_e32 v29, 0xbfb8aa3b, v3
	v_exp_f32_e32 v29, v29
	s_nop 0
	v_add_f32_e32 v29, 1.0, v29
	v_div_scale_f32 v30, s[0:1], v29, v29, v3
	s_nop 0
	v_rcp_f32_e32 v30, v29
	s_nop 0
	v_mul_f32_e32 v3, v3, v30
	v_mul_f32_e32 v3, v28, v3
	v_cvt_pk_bf16_f32 v3, v3, s0
	ds_write_b16 v1, v3 offset:7200
	ds_read_u16 v3, v1 offset:7472
	s_waitcnt lgkmcnt(0)
	v_lshlrev_b32_e32 v3, 16, v3
	v_mul_f32_e32 v26, 0xbfb8aa3b, v3
	v_exp_f32_e32 v26, v26
	s_nop 0
	v_add_f32_e32 v26, 1.0, v26
	v_div_scale_f32 v28, s[0:1], v26, v26, v3
	s_nop 0
	v_rcp_f32_e32 v28, v26
	s_nop 0
	v_mul_f32_e32 v3, v3, v28
	v_mul_f32_e32 v2, v2, v3
	v_cvt_pk_bf16_f32 v2, v2, s0
	ds_write_b16 v1, v2 offset:7472
	ds_read_u16 v3, v1 offset:192
	s_waitcnt lgkmcnt(0)
	v_lshlrev_b32_e32 v3, 16, v3
	v_mul_f32_e32 v26, 0xbfb8aa3b, v3
	v_exp_f32_e32 v26, v26
	s_waitcnt vmcnt(31)
	v_mul_f32_e32 v19, v19, v238
	v_add_f32_e32 v26, 1.0, v26
	v_div_scale_f32 v28, s[0:1], v26, v26, v3
	v_mul_f32_e32 v18, v18, v238
	v_mul_f32_e32 v17, v17, v238
	v_mul_f32_e32 v16, v16, v238
	v_rcp_f32_e32 v28, v26
	s_nop 0
	v_mul_f32_e32 v3, v3, v28
	v_mul_f32_e32 v3, v19, v3
	v_cvt_pk_bf16_f32 v3, v3, s0
	ds_write_b16 v1, v3 offset:192
	ds_read_u16 v3, v1 offset:464
	v_mul_f32_e32 v15, v15, v238
	v_mul_f32_e32 v14, v14, v238
	v_mul_f32_e32 v13, v13, v238
	v_mul_f32_e32 v12, v12, v238
	s_waitcnt lgkmcnt(0)
	v_lshlrev_b32_e32 v3, 16, v3
	v_mul_f32_e32 v19, 0xbfb8aa3b, v3
	v_exp_f32_e32 v19, v19
	v_mul_f32_e32 v11, v11, v238
	v_mul_f32_e32 v10, v10, v238
	v_mul_f32_e32 v9, v9, v238
	v_add_f32_e32 v19, 1.0, v19
	v_div_scale_f32 v26, s[0:1], v19, v19, v3
	v_mul_f32_e32 v8, v8, v238
	v_mul_f32_e32 v7, v7, v238
	v_mul_f32_e32 v6, v6, v238
	v_rcp_f32_e32 v26, v19
	s_nop 0
	v_mul_f32_e32 v3, v3, v26
	v_mul_f32_e32 v3, v18, v3
	v_cvt_pk_bf16_f32 v3, v3, s0
	ds_write_b16 v1, v3 offset:464
	ds_read_u16 v3, v1 offset:736
	v_mul_f32_e32 v5, v5, v238
	v_mul_f32_e32 v2, v4, v238
	s_waitcnt lgkmcnt(0)
	v_lshlrev_b32_e32 v3, 16, v3
	v_mul_f32_e32 v18, 0xbfb8aa3b, v3
	v_exp_f32_e32 v18, v18
	s_nop 0
	v_add_f32_e32 v18, 1.0, v18
	v_div_scale_f32 v19, s[0:1], v18, v18, v3
	s_nop 0
	v_rcp_f32_e32 v19, v18
	s_nop 0
	v_mul_f32_e32 v3, v3, v19
	v_mul_f32_e32 v3, v17, v3
	v_cvt_pk_bf16_f32 v3, v3, s0
	ds_write_b16 v1, v3 offset:736
	ds_read_u16 v3, v1 offset:1008
	s_waitcnt lgkmcnt(0)
	v_lshlrev_b32_e32 v3, 16, v3
	v_mul_f32_e32 v17, 0xbfb8aa3b, v3
	v_exp_f32_e32 v17, v17
	s_nop 0
	v_add_f32_e32 v17, 1.0, v17
	v_div_scale_f32 v18, s[0:1], v17, v17, v3
	s_nop 0
	v_rcp_f32_e32 v18, v17
	s_nop 0
	v_mul_f32_e32 v3, v3, v18
	v_mul_f32_e32 v3, v16, v3
	v_cvt_pk_bf16_f32 v3, v3, s0
	ds_write_b16 v1, v3 offset:1008
	ds_read_u16 v3, v1 offset:2368
	s_waitcnt lgkmcnt(0)
	v_lshlrev_b32_e32 v3, 16, v3
	v_mul_f32_e32 v16, 0xbfb8aa3b, v3
	v_exp_f32_e32 v16, v16
	s_nop 0
	v_add_f32_e32 v16, 1.0, v16
	v_div_scale_f32 v17, s[0:1], v16, v16, v3
	s_nop 0
	v_rcp_f32_e32 v17, v16
	s_nop 0
	v_mul_f32_e32 v3, v3, v17
	v_mul_f32_e32 v3, v15, v3
	v_cvt_pk_bf16_f32 v3, v3, s0
	ds_write_b16 v1, v3 offset:2368
	ds_read_u16 v3, v1 offset:2640
	s_waitcnt lgkmcnt(0)
	v_lshlrev_b32_e32 v3, 16, v3
	v_mul_f32_e32 v15, 0xbfb8aa3b, v3
	v_exp_f32_e32 v15, v15
	s_nop 0
	v_add_f32_e32 v15, 1.0, v15
	v_div_scale_f32 v16, s[0:1], v15, v15, v3
	s_nop 0
	v_rcp_f32_e32 v16, v15
	s_nop 0
	v_mul_f32_e32 v3, v3, v16
	v_mul_f32_e32 v3, v14, v3
	v_cvt_pk_bf16_f32 v3, v3, s0
	ds_write_b16 v1, v3 offset:2640
	ds_read_u16 v3, v1 offset:2912
	s_waitcnt lgkmcnt(0)
	v_lshlrev_b32_e32 v3, 16, v3
	v_mul_f32_e32 v14, 0xbfb8aa3b, v3
	v_exp_f32_e32 v14, v14
	s_nop 0
	v_add_f32_e32 v14, 1.0, v14
	v_div_scale_f32 v15, s[0:1], v14, v14, v3
	s_nop 0
	v_rcp_f32_e32 v15, v14
	s_nop 0
	v_mul_f32_e32 v3, v3, v15
	v_mul_f32_e32 v3, v13, v3
	v_cvt_pk_bf16_f32 v3, v3, s0
	ds_write_b16 v1, v3 offset:2912
	ds_read_u16 v3, v1 offset:3184
	s_waitcnt lgkmcnt(0)
; #define LAS __attribute__((address_space(3)))
; #define LDS_WAIT() asm volatile("s_waitcnt lgkmcnt(0)" ::: "memory")
; DI unsigned cvtpk(float lo, float hi) { f32x2 v = {lo, hi}; bf16x2_t b = __builtin_convertvector(v, bf16x2_t); return __builtin_bit_cast(unsigned, b); }
; DI float bf2f(bf16 b) { return __uint_as_float(((unsigned)b) << 16); }
; DI float siluf_(float x) { return x / (1.f + __expf(-x)); }
; DI void g3_tile_out(bf16* g, const LAS unsigned char* R, int lane) {
;     LDS_WAIT();
; #pragma unroll
;     for (int it = 0; it < 8; ++it) { const int row = 4 * it + (lane >> 4), ch = lane & 15;
;         *(u32x4*)(g + (size_t)row * 512 + ch * 8) = *(const LAS u32x4*)(R + row * G3_PITCH + ch * 16); }
;     LDS_WAIT();
; }
; DI void gla_stage3(const Ctx& c0, int layer, int unit, int cb, LAS unsigned char* lds) {
;     ...
; #pragma unroll
;     for (int vb = 0; vb < 4; ++vb) { const float g = gn[32 * vb + r];
; #pragma unroll
;         for (int rg = 0; rg < 16; ++rg) { LAS bf16* e = (LAS bf16*)(R + (4 * hi) * G3_PITCH + r * 2 + ((rg & 3) + 8 * (rg >> 2)) * G3_PITCH + 64 * vb);
;             const float z = bf2f(*e);
;             *e = (bf16)(cvtpk(o[vb][rg] * rs[rg] * g * siluf_(z), 0.f) & 0xffffu); }
;         asm volatile("" ::: "memory"); }
;     g3_tile_out((bf16*)(c.ws + O_OGLA) + row0 * 512 + h * 128, R, lane);
	v_lshlrev_b32_e32 v3, 16, v3
	v_mul_f32_e32 v13, 0xbfb8aa3b, v3
	v_exp_f32_e32 v13, v13
	s_nop 0
	v_add_f32_e32 v13, 1.0, v13
	v_div_scale_f32 v14, s[0:1], v13, v13, v3
	s_nop 0
	v_rcp_f32_e32 v14, v13
	s_nop 0
	v_mul_f32_e32 v3, v3, v14
	v_mul_f32_e32 v3, v12, v3
	v_cvt_pk_bf16_f32 v3, v3, s0
	ds_write_b16 v1, v3 offset:3184
	ds_read_u16 v3, v1 offset:4544
	s_waitcnt lgkmcnt(0)
	v_lshlrev_b32_e32 v3, 16, v3
	v_mul_f32_e32 v12, 0xbfb8aa3b, v3
	v_exp_f32_e32 v12, v12
	s_nop 0
	v_add_f32_e32 v12, 1.0, v12
	v_div_scale_f32 v13, s[0:1], v12, v12, v3
	s_nop 0
	v_rcp_f32_e32 v13, v12
	s_nop 0
	v_mul_f32_e32 v3, v3, v13
	v_mul_f32_e32 v3, v11, v3
	v_cvt_pk_bf16_f32 v3, v3, s0
	ds_write_b16 v1, v3 offset:4544
	ds_read_u16 v3, v1 offset:4816
	s_waitcnt lgkmcnt(0)
	v_lshlrev_b32_e32 v3, 16, v3
	v_mul_f32_e32 v11, 0xbfb8aa3b, v3
	v_exp_f32_e32 v11, v11
	s_nop 0
	v_add_f32_e32 v11, 1.0, v11
	v_div_scale_f32 v12, s[0:1], v11, v11, v3
	s_nop 0
	v_rcp_f32_e32 v12, v11
	s_nop 0
	v_mul_f32_e32 v3, v3, v12
	v_mul_f32_e32 v3, v10, v3
	v_cvt_pk_bf16_f32 v3, v3, s0
	ds_write_b16 v1, v3 offset:4816
	ds_read_u16 v3, v1 offset:5088
	s_waitcnt lgkmcnt(0)
	v_lshlrev_b32_e32 v3, 16, v3
	v_mul_f32_e32 v10, 0xbfb8aa3b, v3
	v_exp_f32_e32 v10, v10
	s_nop 0
	v_add_f32_e32 v10, 1.0, v10
	v_div_scale_f32 v11, s[0:1], v10, v10, v3
	s_nop 0
	v_rcp_f32_e32 v11, v10
	s_nop 0
	v_mul_f32_e32 v3, v3, v11
	v_mul_f32_e32 v3, v9, v3
	v_cvt_pk_bf16_f32 v3, v3, s0
	ds_write_b16 v1, v3 offset:5088
	ds_read_u16 v3, v1 offset:5360
	s_waitcnt lgkmcnt(0)
	v_lshlrev_b32_e32 v3, 16, v3
	v_mul_f32_e32 v9, 0xbfb8aa3b, v3
	v_exp_f32_e32 v9, v9
	s_nop 0
	v_add_f32_e32 v9, 1.0, v9
	v_div_scale_f32 v10, s[0:1], v9, v9, v3
	s_nop 0
	v_rcp_f32_e32 v10, v9
	s_nop 0
	v_mul_f32_e32 v3, v3, v10
	v_mul_f32_e32 v3, v8, v3
	v_cvt_pk_bf16_f32 v3, v3, s0
	ds_write_b16 v1, v3 offset:5360
	ds_read_u16 v3, v1 offset:6720
	s_waitcnt lgkmcnt(0)
	v_lshlrev_b32_e32 v3, 16, v3
	v_mul_f32_e32 v8, 0xbfb8aa3b, v3
	v_exp_f32_e32 v8, v8
	s_nop 0
	v_add_f32_e32 v8, 1.0, v8
	v_div_scale_f32 v9, s[0:1], v8, v8, v3
	s_nop 0
	v_rcp_f32_e32 v9, v8
	s_nop 0
	v_mul_f32_e32 v3, v3, v9
	v_mul_f32_e32 v3, v7, v3
	v_cvt_pk_bf16_f32 v3, v3, s0
	ds_write_b16 v1, v3 offset:6720
	ds_read_u16 v3, v1 offset:6992
	s_waitcnt lgkmcnt(0)
	v_lshlrev_b32_e32 v3, 16, v3
	v_mul_f32_e32 v7, 0xbfb8aa3b, v3
	v_exp_f32_e32 v7, v7
	s_nop 0
	v_add_f32_e32 v7, 1.0, v7
	v_div_scale_f32 v8, s[0:1], v7, v7, v3
	s_nop 0
	v_rcp_f32_e32 v8, v7
	s_nop 0
	v_mul_f32_e32 v3, v3, v8
	v_mul_f32_e32 v3, v6, v3
	v_cvt_pk_bf16_f32 v3, v3, s0
	ds_write_b16 v1, v3 offset:6992
	ds_read_u16 v3, v1 offset:7264
	s_waitcnt lgkmcnt(0)
	v_lshlrev_b32_e32 v3, 16, v3
	v_mul_f32_e32 v6, 0xbfb8aa3b, v3
	v_exp_f32_e32 v6, v6
	s_nop 0
	v_add_f32_e32 v6, 1.0, v6
	v_div_scale_f32 v7, s[0:1], v6, v6, v3
	s_nop 0
	v_rcp_f32_e32 v7, v6
	s_nop 0
	v_mul_f32_e32 v3, v3, v7
	v_mul_f32_e32 v3, v5, v3
	v_cvt_pk_bf16_f32 v3, v3, s0
	ds_write_b16 v1, v3 offset:7264
	ds_read_u16 v3, v1 offset:7536
	s_waitcnt lgkmcnt(0)
	v_lshlrev_b32_e32 v3, 16, v3
	v_mul_f32_e32 v4, 0xbfb8aa3b, v3
	v_exp_f32_e32 v4, v4
	s_nop 0
	v_add_f32_e32 v4, 1.0, v4
	v_div_scale_f32 v5, s[0:1], v4, v4, v3
	s_nop 0
	v_rcp_f32_e32 v5, v4
	s_nop 0
	v_mul_f32_e32 v3, v3, v5
	v_mul_f32_e32 v2, v2, v3
	v_cvt_pk_bf16_f32 v2, v2, s0
	ds_write_b16 v1, v2 offset:7536
	s_waitcnt lgkmcnt(0)
	ds_read_b128 v[2:5], v92
	v_lshl_add_u64 v[6:7], v[90:91], 0, s[22:23]
	v_lshl_add_u64 v[8:9], v[6:7], 0, v[66:67]
	s_waitcnt lgkmcnt(0)
	global_store_dwordx4 v[8:9], v[2:5], off
	ds_read_b128 v[2:5], v92 offset:1088
	v_lshl_add_u64 v[8:9], v[6:7], 0, v[68:69]
	s_waitcnt lgkmcnt(0)
	global_store_dwordx4 v[8:9], v[2:5], off
	ds_read_b128 v[2:5], v92 offset:2176
	v_lshl_add_u64 v[8:9], v[6:7], 0, v[70:71]
	s_waitcnt lgkmcnt(0)
	global_store_dwordx4 v[8:9], v[2:5], off
	ds_read_b128 v[2:5], v92 offset:3264
	v_lshl_add_u64 v[8:9], v[6:7], 0, v[72:73]
	s_waitcnt lgkmcnt(0)
	global_store_dwordx4 v[8:9], v[2:5], off
	ds_read_b128 v[2:5], v92 offset:4352
	v_lshl_add_u64 v[8:9], v[6:7], 0, v[74:75]
	s_waitcnt lgkmcnt(0)
	global_store_dwordx4 v[8:9], v[2:5], off
	ds_read_b128 v[2:5], v92 offset:5440
	v_lshl_add_u64 v[8:9], v[6:7], 0, v[76:77]
	s_waitcnt lgkmcnt(0)
	global_store_dwordx4 v[8:9], v[2:5], off
	ds_read_b128 v[2:5], v92 offset:6528
	v_lshl_add_u64 v[8:9], v[6:7], 0, v[78:79]
	v_lshl_add_u64 v[6:7], v[6:7], 0, v[80:81]
	s_waitcnt lgkmcnt(0)
	global_store_dwordx4 v[8:9], v[2:5], off
	ds_read_b128 v[2:5], v92 offset:7616
	s_waitcnt lgkmcnt(0)
	global_store_dwordx4 v[6:7], v[2:5], off
	s_waitcnt lgkmcnt(0)
	s_cbranch_scc1 .LBB0_604

; #define LAS __attribute__((address_space(3)))
; #define MFMA32(a, b, c) __builtin_amdgcn_mfma_f32_32x32x16_bf16((a), (b), (c), 0, 0, 0)
; DI void gla_stage3(const Ctx& c0, int layer, int unit, int cb, LAS unsigned char* lds) {
;     ...
;     const int lane = c.lane, r = lane & 31, hi = lane >> 5;
;     const int bh = unit >> 6, n = unit & 63, b = bh >> 2, h = bh & 3;
;     const size_t row0 = (size_t)b * SEQ + n * 64 + 32 * cb;
;     LAS unsigned char* R = lds + c.wid * G3_BYTES;
;     const LAS unsigned char* Re = R + (4 * hi) * G3_PITCH + r * 2;
;     const bf16* qgp = (const bf16*)(c.ws + O_QG) + (row0 + r) * 256 + h * 64 + 8 * hi;
;     const float* sp = (const float*)(c.ws + O_UPD) + (size_t)unit * 8192;
;     const float* gn = c.a->in[I_GNORM] + (size_t)layer * 128;
;     bf16x8 qf[4];
; #pragma unroll
;     for (int s = 0; s < 4; ++s) qf[s] = *(const bf16x8*)(qgp + 16 * s);
;     f32x16 o[4];
; #pragma unroll
;     for (int vb = 0; vb < 4; ++vb) {
;         o[vb] = f32x16{};
; #pragma unroll
;         for (int s = 0; s < 4; ++s) { const float* s0 = sp + (size_t)(16 * s + 8 * hi) * 128 + 32 * vb + r;
;             const bf16x8 bfv = pack8(s0[0], s0[128], s0[256], s0[384], s0[512], s0[640], s0[768], s0[896]);
;             o[vb] = MFMA32(qf[s], bfv, o[vb]); }
;         asm volatile("" ::: "memory");
.LBB0_1216:
	s_mov_b64 s[0:1], s[74:75]
	s_mov_b64 s[2:3], s[72:73]
	s_ashr_i32 s2, s34, 8
	s_ashr_i32 s3, s2, 31
	s_lshl_b64 s[2:3], s[2:3], 12
	s_and_b32 s9, s4, 0xfc0
	s_or_b32 s2, s2, s9
	s_or_b64 s[2:3], s[2:3], s[10:11]
	v_mov_b32_e32 v3, s3
	v_or_b32_e32 v2, s2, v152
	s_bfe_u32 s8, s34, 0x20006
	v_lshlrev_b64 v[2:3], 9, v[2:3]
	v_lshl_add_u64 v[2:3], s[0:1], 0, v[2:3]
	s_lshl_b32 s12, s8, 7
	v_lshl_add_u64 v[2:3], v[2:3], 0, s[12:13]
	v_lshl_add_u64 v[2:3], v[2:3], 0, v[86:87]
	v_lshl_add_u64 v[4:5], v[2:3], 0, s[18:19]
	v_add_co_u32_e32 v2, vcc, s6, v2
	v_lshl_add_u64 v[90:91], s[0:1], 0, v[84:85]
	s_nop 0
	v_addc_co_u32_e32 v3, vcc, 0, v3, vcc
	global_load_dwordx4 v[50:53], v[2:3], off
	global_load_dwordx4 v[110:113], v[4:5], off offset:96
	global_load_dwordx4 v[106:109], v[4:5], off offset:64
	global_load_dwordx4 v[102:105], v[4:5], off offset:32
	v_add_co_u32_e32 v2, vcc, s7, v90
	s_lshl_b64 s[2:3], s[2:3], 10
	s_nop 0
	v_addc_co_u32_e32 v3, vcc, -1, v91, vcc
	v_add_co_u32_e32 v58, vcc, s28, v90
	global_load_dword v2, v[2:3], off
	s_nop 0
	v_addc_co_u32_e32 v59, vcc, -1, v91, vcc
	global_load_dword v3, v[58:59], off offset:384
	global_load_dword v4, v[58:59], off offset:896
	global_load_dword v5, v[58:59], off offset:1408
	global_load_dword v6, v[58:59], off offset:1920
	global_load_dword v7, v[58:59], off offset:2432
	global_load_dword v8, v[58:59], off offset:2944
	global_load_dword v9, v[58:59], off offset:3456
	v_add_co_u32_e32 v18, vcc, s15, v90
	s_lshl_b32 s8, s8, 8
	s_nop 0
	v_addc_co_u32_e32 v19, vcc, -1, v91, vcc
	v_add_co_u32_e32 v114, vcc, s29, v90
	global_load_dword v18, v[18:19], off
	s_nop 0
	v_addc_co_u32_e32 v115, vcc, -1, v91, vcc
	global_load_dword v19, v[114:115], off offset:384
	global_load_dword v20, v[114:115], off offset:896
	global_load_dword v21, v[114:115], off offset:1408
	global_load_dword v22, v[114:115], off offset:1920
	global_load_dword v23, v[114:115], off offset:2432
	global_load_dword v24, v[114:115], off offset:2944
	global_load_dword v25, v[114:115], off offset:3456
	s_add_u32 s0, s0, s2
	s_addc_u32 s1, s1, s3
	s_add_u32 s0, s0, s8
	s_addc_u32 s1, s1, 0
	s_add_i32 s34, s34, s14
	s_add_i32 s4, s4, s5
	v_lshl_add_u64 v[84:85], v[84:85], 0, s[16:17]
	s_cmpk_lt_i32 s34, 0x800
	s_waitcnt vmcnt(0) lgkmcnt(0)
	global_load_dword v41, v[114:115], off offset:3584
	global_load_dword v40, v[114:115], off offset:3072
	global_load_dword v39, v[114:115], off offset:2560
	global_load_dword v38, v[114:115], off offset:2048
	global_load_dword v37, v[114:115], off offset:1536
	global_load_dword v36, v[114:115], off offset:1024
	global_load_dword v35, v[114:115], off offset:512
	global_load_dword v34, v[114:115], off
	global_load_dword v145, v[58:59], off offset:3584
	global_load_dword v146, v[58:59], off offset:3072
	global_load_dword v143, v[58:59], off offset:2560
	global_load_dword v144, v[58:59], off offset:2048
	global_load_dword v141, v[58:59], off offset:1536
	global_load_dword v142, v[58:59], off offset:1024
	global_load_dword v139, v[58:59], off offset:512
	global_load_dword v140, v[58:59], off
	v_cvt_pk_bf16_f32 v2, v2, v3
	v_cvt_pk_bf16_f32 v3, v4, v5
	v_cvt_pk_bf16_f32 v4, v6, v7
	v_cvt_pk_bf16_f32 v5, v8, v9
	v_cvt_pk_bf16_f32 v18, v18, v19
	s_nop 0
	v_mfma_f32_32x32x16_bf16 v[2:17], v[50:53], v[2:5], 0
	v_cvt_pk_bf16_f32 v19, v20, v21
	v_cvt_pk_bf16_f32 v20, v22, v23
	v_cvt_pk_bf16_f32 v21, v24, v25
	s_nop 1
	v_mfma_f32_32x32x16_bf16 v[2:17], v[102:105], v[18:21], v[2:17]
	v_add_co_u32_e32 v18, vcc, s26, v90
	s_nop 1
	v_addc_co_u32_e32 v19, vcc, -1, v91, vcc
	v_add_co_u32_e32 v118, vcc, s30, v90
	global_load_dword v18, v[18:19], off
	s_nop 0
	v_addc_co_u32_e32 v119, vcc, -1, v91, vcc
	global_load_dword v19, v[118:119], off offset:384
	global_load_dword v20, v[118:119], off offset:896
	global_load_dword v21, v[118:119], off offset:1408
	global_load_dword v22, v[118:119], off offset:1920
	global_load_dword v23, v[118:119], off offset:2432
	global_load_dword v24, v[118:119], off offset:2944
	global_load_dword v25, v[118:119], off offset:3456
	s_waitcnt vmcnt(0) lgkmcnt(0)
	global_load_dword v63, v[114:115], off offset:3712
	global_load_dword v62, v[114:115], off offset:3200
	global_load_dword v61, v[114:115], off offset:2688
	global_load_dword v60, v[114:115], off offset:2176
	global_load_dword v57, v[114:115], off offset:1664
	global_load_dword v56, v[114:115], off offset:1152
	global_load_dword v55, v[114:115], off offset:640
	global_load_dword v54, v[114:115], off offset:128
	global_load_dword v173, v[58:59], off offset:3712
	global_load_dword v176, v[58:59], off offset:3200
	global_load_dword v171, v[58:59], off offset:2688
	global_load_dword v174, v[58:59], off offset:2176
	global_load_dword v169, v[58:59], off offset:1664
	global_load_dword v172, v[58:59], off offset:1152
	global_load_dword v167, v[58:59], off offset:640
	global_load_dword v170, v[58:59], off offset:128
	global_load_dword v157, v[118:119], off offset:3584
	global_load_dword v160, v[118:119], off offset:3072
	global_load_dword v155, v[118:119], off offset:2560
	global_load_dword v158, v[118:119], off offset:2048
	global_load_dword v149, v[118:119], off offset:1536
	global_load_dword v156, v[118:119], off offset:1024
	global_load_dword v147, v[118:119], off offset:512
	global_load_dword v148, v[118:119], off
	v_cvt_pk_bf16_f32 v18, v18, v19
	v_cvt_pk_bf16_f32 v19, v20, v21
	v_cvt_pk_bf16_f32 v20, v22, v23
	v_cvt_pk_bf16_f32 v21, v24, v25
	s_nop 1
	v_mfma_f32_32x32x16_bf16 v[2:17], v[106:109], v[18:21], v[2:17]
	v_add_co_u32_e32 v18, vcc, s27, v90
	s_nop 1
	v_addc_co_u32_e32 v19, vcc, -1, v91, vcc
	v_add_co_u32_e32 v120, vcc, s31, v90
	global_load_dword v18, v[18:19], off
	s_nop 0
	v_addc_co_u32_e32 v121, vcc, -1, v91, vcc
	global_load_dword v19, v[120:121], off offset:384
	global_load_dword v20, v[120:121], off offset:896
	global_load_dword v21, v[120:121], off offset:1408
	global_load_dword v22, v[120:121], off offset:1920
	global_load_dword v23, v[120:121], off offset:2432
	global_load_dword v24, v[120:121], off offset:2944
	global_load_dword v25, v[120:121], off offset:3456
	v_cmp_lt_i32_e32 vcc, v94, v95
	s_waitcnt vmcnt(0) lgkmcnt(0)
; #define MFMA32(a, b, c) __builtin_amdgcn_mfma_f32_32x32x16_bf16((a), (b), (c), 0, 0, 0)
; DI void gla_stage3(const Ctx& c0, int layer, int unit, int cb, LAS unsigned char* lds) {
;     ...
;     f32x16 o[4];
; #pragma unroll
;     for (int vb = 0; vb < 4; ++vb) {
;         o[vb] = f32x16{};
; #pragma unroll
;         for (int s = 0; s < 4; ++s) { const float* s0 = sp + (size_t)(16 * s + 8 * hi) * 128 + 32 * vb + r;
;             const bf16x8 bfv = pack8(s0[0], s0[128], s0[256], s0[384], s0[512], s0[640], s0[768], s0[896]);
;             o[vb] = MFMA32(qf[s], bfv, o[vb]); }
;         asm volatile("" ::: "memory");
;     ...
;     for (int vb = 0; vb < 4; ++vb) { const float g = gn[32 * vb + r];
	global_load_dword v127, v[114:115], off offset:3840
	global_load_dword v126, v[114:115], off offset:3328
	global_load_dword v125, v[114:115], off offset:2816
	global_load_dword v124, v[114:115], off offset:2304
	global_load_dword v123, v[114:115], off offset:1792
	global_load_dword v122, v[114:115], off offset:1280
	global_load_dword v117, v[114:115], off offset:768
	global_load_dword v116, v[114:115], off offset:256
	global_load_dword v214, v[58:59], off offset:3840
	global_load_dword v212, v[58:59], off offset:3328
	global_load_dword v205, v[58:59], off offset:2816
	global_load_dword v210, v[58:59], off offset:2304
	global_load_dword v203, v[58:59], off offset:1792
	global_load_dword v208, v[58:59], off offset:1280
	global_load_dword v201, v[58:59], off offset:768
	global_load_dword v206, v[58:59], off offset:256
	global_load_dword v199, v[120:121], off offset:3712
	global_load_dword v204, v[120:121], off offset:3200
	global_load_dword v197, v[120:121], off offset:2688
	global_load_dword v202, v[120:121], off offset:2176
	global_load_dword v195, v[120:121], off offset:1664
	global_load_dword v200, v[120:121], off offset:1152
	global_load_dword v183, v[120:121], off offset:640
	global_load_dword v198, v[120:121], off offset:128
	global_load_dword v181, v[118:119], off offset:3712
	global_load_dword v196, v[118:119], off offset:3200
	global_load_dword v179, v[118:119], off offset:2688
	global_load_dword v182, v[118:119], off offset:2176
	global_load_dword v177, v[118:119], off offset:1664
	global_load_dword v180, v[118:119], off offset:1152
	global_load_dword v175, v[118:119], off offset:640
	global_load_dword v178, v[118:119], off offset:128
	global_load_dword v165, v[120:121], off offset:3584
	global_load_dword v168, v[120:121], off offset:3072
	global_load_dword v163, v[120:121], off offset:2560
	global_load_dword v166, v[120:121], off offset:2048
	global_load_dword v161, v[120:121], off offset:1536
	global_load_dword v164, v[120:121], off offset:1024
	global_load_dword v159, v[120:121], off offset:512
	global_load_dword v162, v[120:121], off
	v_cvt_pk_bf16_f32 v18, v18, v19
	v_cvt_pk_bf16_f32 v19, v20, v21
	v_cvt_pk_bf16_f32 v20, v22, v23
	v_cvt_pk_bf16_f32 v21, v24, v25
	s_nop 1
	v_mfma_f32_32x32x16_bf16 v[2:17], v[110:113], v[18:21], v[2:17]
	s_waitcnt vmcnt(40) lgkmcnt(0)
	global_load_dword v238, v[82:83], off offset:896
	global_load_dword v236, v[82:83], off offset:768
	global_load_dword v234, v[82:83], off offset:640
	global_load_dword v232, v[82:83], off offset:512
	global_load_dword v90, v[90:91], off
	global_load_dword v230, v[120:121], off offset:3328
	global_load_dword v219, v[120:121], off offset:2816
	global_load_dword v228, v[120:121], off offset:2304
	global_load_dword v217, v[120:121], off offset:1792
	global_load_dword v226, v[120:121], off offset:1280
	global_load_dword v215, v[120:121], off offset:768
	global_load_dword v224, v[120:121], off offset:256
	global_load_dword v213, v[118:119], off offset:3840
	global_load_dword v222, v[118:119], off offset:3328
	global_load_dword v211, v[118:119], off offset:2816
	global_load_dword v220, v[118:119], off offset:2304
	global_load_dword v209, v[118:119], off offset:1792
	global_load_dword v218, v[118:119], off offset:1280
	global_load_dword v207, v[118:119], off offset:768
	global_load_dword v216, v[118:119], off offset:256
	v_cvt_pk_bf16_f32 v18, v140, v139
	v_cvt_pk_bf16_f32 v34, v34, v35
	v_cvt_pk_bf16_f32 v19, v142, v141
	v_cvt_pk_bf16_f32 v35, v36, v37
	v_cvt_pk_bf16_f32 v20, v144, v143
	v_cvt_pk_bf16_f32 v36, v38, v39
	v_cvt_pk_bf16_f32 v21, v146, v145
	v_cvt_pk_bf16_f32 v37, v40, v41
	s_nop 0
	v_mfma_f32_32x32x16_bf16 v[18:33], v[50:53], v[18:21], 0
	v_mfma_f32_32x32x16_bf16 v[18:33], v[102:105], v[34:37], v[18:33]
	s_waitcnt vmcnt(60) lgkmcnt(0)
	v_cvt_pk_bf16_f32 v34, v148, v147
	v_cvt_pk_bf16_f32 v35, v156, v149
	v_cvt_pk_bf16_f32 v36, v158, v155
	v_cvt_pk_bf16_f32 v37, v160, v157
	s_nop 1
	v_mfma_f32_32x32x16_bf16 v[18:33], v[106:109], v[34:37], v[18:33]
	s_waitcnt vmcnt(20) lgkmcnt(0)
	v_cvt_pk_bf16_f32 v34, v162, v159
	v_cvt_pk_bf16_f32 v35, v164, v161
	v_cvt_pk_bf16_f32 v36, v166, v163
	v_cvt_pk_bf16_f32 v37, v168, v165
	s_nop 1
	v_mfma_f32_32x32x16_bf16 v[18:33], v[110:113], v[34:37], v[18:33]
	s_waitcnt vmcnt(62) lgkmcnt(0)
	v_cvt_pk_bf16_f32 v34, v170, v167
	v_cvt_pk_bf16_f32 v54, v54, v55
	v_cvt_pk_bf16_f32 v35, v172, v169
	v_cvt_pk_bf16_f32 v55, v56, v57
	v_cvt_pk_bf16_f32 v36, v174, v171
	v_cvt_pk_bf16_f32 v56, v60, v61
	v_cvt_pk_bf16_f32 v37, v176, v173
	v_cvt_pk_bf16_f32 v57, v62, v63
	s_nop 0
	v_mfma_f32_32x32x16_bf16 v[34:49], v[50:53], v[34:37], 0
	v_mfma_f32_32x32x16_bf16 v[34:49], v[102:105], v[54:57], v[34:49]
	s_waitcnt vmcnt(28) lgkmcnt(0)
	v_cvt_pk_bf16_f32 v54, v178, v175
	v_cvt_pk_bf16_f32 v55, v180, v177
	v_cvt_pk_bf16_f32 v56, v182, v179
	v_cvt_pk_bf16_f32 v57, v196, v181
	s_nop 1
	v_mfma_f32_32x32x16_bf16 v[34:49], v[106:109], v[54:57], v[34:49]
	s_waitcnt vmcnt(36) lgkmcnt(0)
	v_cvt_pk_bf16_f32 v54, v198, v183
	v_cvt_pk_bf16_f32 v55, v200, v195
	v_cvt_pk_bf16_f32 v56, v202, v197
	v_cvt_pk_bf16_f32 v57, v204, v199
	s_nop 1
	v_mfma_f32_32x32x16_bf16 v[34:49], v[110:113], v[54:57], v[34:49]
	s_nop 0
	s_nop 0
	s_waitcnt vmcnt(44) lgkmcnt(0)
	v_cvt_pk_bf16_f32 v54, v206, v201
	v_cvt_pk_bf16_f32 v114, v116, v117
	v_cvt_pk_bf16_f32 v55, v208, v203
	v_cvt_pk_bf16_f32 v115, v122, v123
	v_cvt_pk_bf16_f32 v56, v210, v205
	v_cvt_pk_bf16_f32 v116, v124, v125
	v_cvt_pk_bf16_f32 v57, v212, v214
	v_cvt_pk_bf16_f32 v117, v126, v127
	s_nop 0
	v_mfma_f32_32x32x16_bf16 v[50:65], v[50:53], v[54:57], 0
	v_mfma_f32_32x32x16_bf16 v[50:65], v[102:105], v[114:117], v[50:65]
	s_waitcnt vmcnt(0) lgkmcnt(0)
; #define LAS __attribute__((address_space(3)))
; #define LDS_WAIT() asm volatile("s_waitcnt lgkmcnt(0)" ::: "memory")
; DI float bf2f(bf16 b) { return __uint_as_float(((unsigned)b) << 16); }
; DI void g3_tile_in(const bf16* g, LAS unsigned char* R, int lane) {
; #pragma unroll
;     for (int it = 0; it < 8; ++it) { const int row = 4 * it + (lane >> 4), ch = lane & 15;
;         *(LAS u32x4*)(R + row * G3_PITCH + ch * 16) = *(const u32x4*)(g + (size_t)row * 512 + ch * 8); }
;     LDS_WAIT();
; DI void gla_stage3(const Ctx& c0, int layer, int unit, int cb, LAS unsigned char* lds) {
;     ...
;     g3_tile_in((const bf16*)(c.ws + O_OINTRA) + row0 * 512 + h * 128, R, lane);
; #pragma unroll
;     for (int vb = 0; vb < 4; ++vb) {
; #pragma unroll
;         for (int rg = 0; rg < 16; ++rg) o[vb][rg] += bf2f(*(const LAS bf16*)(Re + ((rg & 3) + 8 * (rg >> 2)) * G3_PITCH + 64 * vb));
;         asm volatile("" ::: "memory");
;     }
	v_cvt_pk_bf16_f32 v102, v216, v207
	v_cvt_pk_bf16_f32 v103, v218, v209
	v_cvt_pk_bf16_f32 v104, v220, v211
	v_cvt_pk_bf16_f32 v105, v222, v213
	s_nop 1
	v_mfma_f32_32x32x16_bf16 v[50:65], v[106:109], v[102:105], v[50:65]
	s_nop 0
	s_waitcnt vmcnt(8) lgkmcnt(0)
	v_cvt_pk_bf16_f32 v102, v224, v215
	v_cvt_pk_bf16_f32 v103, v226, v217
	v_cvt_pk_bf16_f32 v104, v228, v219
	v_cvt_pk_bf16_f32 v105, v230, v90
	v_lshl_add_u64 v[90:91], s[0:1], 0, v[88:89]
	v_lshl_add_u64 v[106:107], v[90:91], 0, s[20:21]
	v_mfma_f32_32x32x16_bf16 v[50:65], v[110:113], v[102:105], v[50:65]
	v_lshl_add_u64 v[102:103], v[106:107], 0, v[66:67]
	global_load_dwordx4 v[102:105], v[102:103], off
	s_waitcnt vmcnt(0) lgkmcnt(0)
	v_lshl_add_u64 v[168:169], v[90:91], 0, s[22:23]
	v_lshl_add_u64 v[140:141], v[168:169], 0, v[70:71]
	global_load_dwordx4 v[174:177], v[140:141], off
	v_lshl_add_u64 v[140:141], v[106:107], 0, v[70:71]
	global_load_dwordx4 v[146:149], v[140:141], off
	v_lshl_add_u64 v[144:145], v[106:107], 0, v[68:69]
	global_load_dwordx4 v[140:143], v[144:145], off
	ds_write_b128 v92, v[102:105]
	s_waitcnt vmcnt(0) lgkmcnt(0)
	v_lshl_add_u64 v[144:145], v[168:169], 0, v[76:77]
	global_load_dwordx4 v[200:203], v[144:145], off
	v_lshl_add_u64 v[144:145], v[168:169], 0, v[74:75]
	global_load_dwordx4 v[196:199], v[144:145], off
	v_lshl_add_u64 v[144:145], v[168:169], 0, v[72:73]
	global_load_dwordx4 v[178:181], v[144:145], off
	v_lshl_add_u64 v[144:145], v[106:107], 0, v[74:75]
	global_load_dwordx4 v[156:159], v[144:145], off
	v_lshl_add_u64 v[102:103], v[106:107], 0, v[72:73]
	global_load_dwordx4 v[102:105], v[102:103], off
	ds_write_b128 v92, v[140:143] offset:1088
	s_waitcnt vmcnt(5) lgkmcnt(0)
	v_lshl_add_u64 v[140:141], v[168:169], 0, v[78:79]
	global_load_dwordx4 v[204:207], v[140:141], off
	v_lshl_add_u64 v[140:141], v[106:107], 0, v[78:79]
	global_load_dwordx4 v[160:163], v[140:141], off
	v_lshl_add_u64 v[144:145], v[106:107], 0, v[76:77]
	global_load_dwordx4 v[140:143], v[144:145], off
	ds_write_b128 v92, v[146:149] offset:2176
	s_waitcnt vmcnt(3) lgkmcnt(0)
	v_lshl_add_u64 v[144:145], v[168:169], 0, v[66:67]
	global_load_dwordx4 v[164:167], v[144:145], off
	v_lshl_add_u64 v[148:149], v[106:107], 0, v[80:81]
	global_load_dwordx4 v[144:147], v[148:149], off
	ds_write_b128 v92, v[102:105] offset:3264
	s_waitcnt vmcnt(6) lgkmcnt(0)
	v_lshl_add_u64 v[148:149], v[168:169], 0, v[68:69]
	global_load_dwordx4 v[170:173], v[148:149], off
	ds_write_b128 v92, v[156:159] offset:4352
	s_waitcnt vmcnt(3) lgkmcnt(0)
	ds_write_b128 v92, v[140:143] offset:5440
	s_waitcnt vmcnt(4) lgkmcnt(0)
	ds_write_b128 v92, v[160:163] offset:6528
	s_waitcnt vmcnt(1) lgkmcnt(0)
	ds_write_b128 v92, v[144:147] offset:7616
	s_waitcnt lgkmcnt(0)
	ds_read_u16 v138, v1
	ds_read_u16 v137, v1 offset:272
	ds_read_u16 v136, v1 offset:544
	ds_read_u16 v135, v1 offset:816
	ds_read_u16 v134, v1 offset:2176
	ds_read_u16 v133, v1 offset:2448
	ds_read_u16 v132, v1 offset:2720
	ds_read_u16 v131, v1 offset:2992
	s_waitcnt lgkmcnt(0)
	v_lshlrev_b32_e32 v138, 16, v138
	v_add_f32_e32 v138, v2, v138
	v_lshlrev_b32_e32 v137, 16, v137
	v_add_f32_e32 v137, v3, v137
	v_lshlrev_b32_e32 v136, 16, v136
	v_add_f32_e32 v136, v4, v136
	v_lshlrev_b32_e32 v135, 16, v135
	v_add_f32_e32 v135, v5, v135
	v_lshlrev_b32_e32 v134, 16, v134
	v_add_f32_e32 v134, v6, v134
	v_lshlrev_b32_e32 v133, 16, v133
	v_add_f32_e32 v133, v7, v133
	v_lshlrev_b32_e32 v132, 16, v132
	v_add_f32_e32 v132, v8, v132
	v_lshlrev_b32_e32 v131, 16, v131
	v_add_f32_e32 v131, v9, v131
	ds_read_u16 v130, v1 offset:4352
	ds_read_u16 v129, v1 offset:4624
	ds_read_u16 v128, v1 offset:4896
	ds_read_u16 v127, v1 offset:5168
	ds_read_u16 v126, v1 offset:6528
	ds_read_u16 v125, v1 offset:6800
	ds_read_u16 v124, v1 offset:7072
	s_waitcnt lgkmcnt(0)
	v_lshlrev_b32_e32 v130, 16, v130
	v_add_f32_e32 v130, v10, v130
	v_lshlrev_b32_e32 v129, 16, v129
	v_add_f32_e32 v129, v11, v129
	v_lshlrev_b32_e32 v128, 16, v128
	v_add_f32_e32 v128, v12, v128
	v_lshlrev_b32_e32 v127, 16, v127
	v_add_f32_e32 v127, v13, v127
	v_lshlrev_b32_e32 v126, 16, v126
	v_add_f32_e32 v126, v14, v126
	v_lshlrev_b32_e32 v125, 16, v125
	v_add_f32_e32 v125, v15, v125
	v_lshlrev_b32_e32 v124, 16, v124
	v_add_f32_e32 v124, v16, v124
	ds_read_u16 v2, v1 offset:7344
	s_waitcnt lgkmcnt(0)
	v_lshlrev_b32_e32 v2, 16, v2
	v_add_f32_e32 v123, v17, v2
	ds_read_u16 v122, v1 offset:64
	ds_read_u16 v121, v1 offset:336
	ds_read_u16 v120, v1 offset:608
	ds_read_u16 v119, v1 offset:880
	ds_read_u16 v118, v1 offset:2240
	ds_read_u16 v117, v1 offset:2512
	ds_read_u16 v116, v1 offset:2784
	ds_read_u16 v115, v1 offset:3056
	s_waitcnt lgkmcnt(0)
	v_lshlrev_b32_e32 v122, 16, v122
	v_add_f32_e32 v122, v18, v122
	v_lshlrev_b32_e32 v121, 16, v121
	v_add_f32_e32 v121, v19, v121
	v_lshlrev_b32_e32 v120, 16, v120
	v_add_f32_e32 v120, v20, v120
	v_lshlrev_b32_e32 v119, 16, v119
	v_add_f32_e32 v119, v21, v119
	v_lshlrev_b32_e32 v118, 16, v118
	v_add_f32_e32 v118, v22, v118
	v_lshlrev_b32_e32 v117, 16, v117
	v_add_f32_e32 v117, v23, v117
	v_lshlrev_b32_e32 v116, 16, v116
	v_add_f32_e32 v116, v24, v116
	v_lshlrev_b32_e32 v115, 16, v115
	v_add_f32_e32 v115, v25, v115
	ds_read_u16 v114, v1 offset:4416
	ds_read_u16 v113, v1 offset:4688
	ds_read_u16 v112, v1 offset:4960
	ds_read_u16 v111, v1 offset:5232
	ds_read_u16 v110, v1 offset:6592
	ds_read_u16 v109, v1 offset:6864
	ds_read_u16 v108, v1 offset:7136
	s_waitcnt lgkmcnt(0)
; #define LAS __attribute__((address_space(3)))
; DI float bf2f(bf16 b) { return __uint_as_float(((unsigned)b) << 16); }
; DI void gla_stage3(const Ctx& c0, int layer, int unit, int cb, LAS unsigned char* lds) {
;     ...
;     for (int vb = 0; vb < 4; ++vb) {
; #pragma unroll
;         for (int rg = 0; rg < 16; ++rg) o[vb][rg] += bf2f(*(const LAS bf16*)(Re + ((rg & 3) + 8 * (rg >> 2)) * G3_PITCH + 64 * vb));
;         asm volatile("" ::: "memory");
;     }
;     float rs[16];
; #pragma unroll
;     for (int rg = 0; rg < 16; ++rg) { float ss = o[0][rg] * o[0][rg] + o[1][rg] * o[1][rg] + o[2][rg] * o[2][rg] + o[3][rg] * o[3][rg];
;         ss += __shfl_xor(ss, 1); ss += __shfl_xor(ss, 2); ss += __shfl_xor(ss, 4); ss += __shfl_xor(ss, 8); ss += __shfl_xor(ss, 16);
;         rs[rg] = 1.f / sqrtf(ss * (1.f / 128.f) + EPS); }
	v_lshlrev_b32_e32 v114, 16, v114
	v_add_f32_e32 v114, v26, v114
	v_lshlrev_b32_e32 v113, 16, v113
	v_add_f32_e32 v113, v27, v113
	v_lshlrev_b32_e32 v112, 16, v112
	v_add_f32_e32 v112, v28, v112
	v_lshlrev_b32_e32 v111, 16, v111
	v_add_f32_e32 v111, v29, v111
	v_lshlrev_b32_e32 v110, 16, v110
	v_add_f32_e32 v110, v30, v110
	v_lshlrev_b32_e32 v109, 16, v109
	v_add_f32_e32 v109, v31, v109
	v_lshlrev_b32_e32 v108, 16, v108
	v_add_f32_e32 v108, v32, v108
	ds_read_u16 v2, v1 offset:7408
	s_waitcnt lgkmcnt(0)
	v_lshlrev_b32_e32 v2, 16, v2
	v_add_f32_e32 v107, v33, v2
	ds_read_u16 v2, v1 offset:128
	s_waitcnt lgkmcnt(0)
	v_lshlrev_b32_e32 v2, 16, v2
	v_add_f32_e32 v106, v34, v2
	ds_read_u16 v2, v1 offset:400
	s_waitcnt lgkmcnt(0)
	v_lshlrev_b32_e32 v2, 16, v2
	v_add_f32_e32 v105, v35, v2
	ds_read_u16 v2, v1 offset:672
	s_waitcnt lgkmcnt(0)
	v_lshlrev_b32_e32 v2, 16, v2
	v_add_f32_e32 v104, v36, v2
	ds_read_u16 v2, v1 offset:944
	s_waitcnt lgkmcnt(0)
	v_lshlrev_b32_e32 v2, 16, v2
	v_add_f32_e32 v103, v37, v2
	ds_read_u16 v2, v1 offset:2304
	s_waitcnt lgkmcnt(0)
	v_lshlrev_b32_e32 v2, 16, v2
	v_add_f32_e32 v102, v38, v2
	ds_read_u16 v2, v1 offset:2576
	s_waitcnt lgkmcnt(0)
	v_lshlrev_b32_e32 v2, 16, v2
	v_add_f32_e32 v39, v39, v2
	ds_read_u16 v2, v1 offset:2848
	s_waitcnt lgkmcnt(0)
	v_lshlrev_b32_e32 v2, 16, v2
	v_add_f32_e32 v38, v40, v2
	ds_read_u16 v2, v1 offset:3120
	s_waitcnt lgkmcnt(0)
	v_lshlrev_b32_e32 v2, 16, v2
	v_add_f32_e32 v37, v41, v2
	ds_read_u16 v36, v1 offset:4480
	ds_read_u16 v34, v1 offset:4752
	ds_read_u16 v33, v1 offset:5024
	ds_read_u16 v32, v1 offset:5296
	ds_read_u16 v30, v1 offset:6656
	ds_read_u16 v29, v1 offset:6928
	ds_read_u16 v28, v1 offset:7200
	s_waitcnt lgkmcnt(0)
	v_lshlrev_b32_e32 v36, 16, v36
	v_add_f32_e32 v36, v42, v36
	v_lshlrev_b32_e32 v34, 16, v34
	v_add_f32_e32 v34, v43, v34
	v_lshlrev_b32_e32 v33, 16, v33
	v_add_f32_e32 v33, v44, v33
	v_lshlrev_b32_e32 v32, 16, v32
	v_add_f32_e32 v32, v45, v32
	v_lshlrev_b32_e32 v30, 16, v30
	v_add_f32_e32 v30, v46, v30
	v_lshlrev_b32_e32 v29, 16, v29
	v_add_f32_e32 v29, v47, v29
	v_lshlrev_b32_e32 v28, 16, v28
	v_add_f32_e32 v28, v48, v28
	ds_read_u16 v2, v1 offset:7472
	s_waitcnt lgkmcnt(0)
	v_lshlrev_b32_e32 v2, 16, v2
	v_add_f32_e32 v26, v49, v2
	ds_read_u16 v19, v1 offset:192
	ds_read_u16 v18, v1 offset:464
	ds_read_u16 v17, v1 offset:736
	ds_read_u16 v16, v1 offset:1008
	ds_read_u16 v15, v1 offset:2368
	ds_read_u16 v14, v1 offset:2640
	ds_read_u16 v13, v1 offset:2912
	ds_read_u16 v12, v1 offset:3184
	s_waitcnt lgkmcnt(0)
	v_lshlrev_b32_e32 v19, 16, v19
	v_add_f32_e32 v19, v50, v19
	v_lshlrev_b32_e32 v18, 16, v18
	v_add_f32_e32 v18, v51, v18
	v_lshlrev_b32_e32 v17, 16, v17
	v_add_f32_e32 v17, v52, v17
	v_lshlrev_b32_e32 v16, 16, v16
	v_add_f32_e32 v16, v53, v16
	v_lshlrev_b32_e32 v15, 16, v15
	v_add_f32_e32 v15, v54, v15
	v_lshlrev_b32_e32 v14, 16, v14
	v_add_f32_e32 v14, v55, v14
	v_lshlrev_b32_e32 v13, 16, v13
	v_add_f32_e32 v13, v56, v13
	v_lshlrev_b32_e32 v12, 16, v12
	v_add_f32_e32 v12, v57, v12
	ds_read_u16 v11, v1 offset:4544
	ds_read_u16 v10, v1 offset:4816
	ds_read_u16 v9, v1 offset:5088
	ds_read_u16 v8, v1 offset:5360
	ds_read_u16 v7, v1 offset:6720
	ds_read_u16 v6, v1 offset:6992
	ds_read_u16 v5, v1 offset:7264
	s_waitcnt lgkmcnt(0)
	v_lshlrev_b32_e32 v11, 16, v11
	v_add_f32_e32 v11, v58, v11
	v_lshlrev_b32_e32 v10, 16, v10
	v_add_f32_e32 v10, v59, v10
	v_lshlrev_b32_e32 v9, 16, v9
	v_add_f32_e32 v9, v60, v9
	v_lshlrev_b32_e32 v8, 16, v8
	v_add_f32_e32 v8, v61, v8
	v_lshlrev_b32_e32 v7, 16, v7
	v_add_f32_e32 v7, v62, v7
	v_lshlrev_b32_e32 v6, 16, v6
	v_add_f32_e32 v6, v63, v6
	v_lshlrev_b32_e32 v5, 16, v5
	v_add_f32_e32 v5, v64, v5
	ds_read_u16 v2, v1 offset:7536
	s_waitcnt lgkmcnt(0)
	s_waitcnt lgkmcnt(0)
	v_lshlrev_b32_e32 v2, 16, v2
	v_add_f32_e32 v4, v65, v2
	v_cndmask_b32_e32 v2, v93, v94, vcc
	v_cmp_lt_i32_e32 vcc, v96, v95
	v_lshlrev_b32_e32 v2, 2, v2
	s_nop 0
	v_cndmask_b32_e32 v3, v93, v96, vcc
	v_cmp_lt_i32_e32 vcc, v97, v95
	v_lshlrev_b32_e32 v3, 2, v3
	s_nop 0
	v_cndmask_b32_e32 v20, v93, v97, vcc
	v_cmp_lt_i32_e32 vcc, v98, v95
	v_lshlrev_b32_e32 v20, 2, v20
	s_nop 0
	v_cndmask_b32_e32 v21, v93, v98, vcc
	v_cmp_lt_i32_e32 vcc, v99, v95
	v_lshlrev_b32_e32 v47, 2, v21
	s_nop 0
	v_cndmask_b32_e32 v21, v93, v99, vcc
	v_lshlrev_b32_e32 v48, 2, v21
	v_mul_f32_e32 v21, v122, v122
	v_fmac_f32_e32 v21, v138, v138
	v_fmac_f32_e32 v21, v106, v106
	v_fmac_f32_e32 v21, v19, v19
	s_nop 1
	v_add_f32_dpp v21, v21, v21 quad_perm:[1,0,3,2] row_mask:0xf bank_mask:0xf
	s_nop 1
	v_add_f32_dpp v21, v21, v21 quad_perm:[2,3,0,1] row_mask:0xf bank_mask:0xf
	s_nop 1
	v_add_f32_dpp v21, v21, v21 row_half_mirror row_mask:0xf bank_mask:0xf
	s_nop 1
	v_add_f32_dpp v21, v21, v21 row_mirror row_mask:0xf bank_mask:0xf
	v_mov_b32_e32 v22, v21
	v_mov_b32_e32 v23, v21
	s_nop 1
	v_permlane16_swap_b32_e32 v22, v23
	v_add_f32_e32 v21, v22, v23
	v_fmamk_f32 v21, v21, 0x3c000000, v100
	v_cmp_gt_f32_e32 vcc, s33, v21
	v_mul_f32_e32 v22, 0x4f800000, v21
	s_nop 0
	v_cndmask_b32_e32 v21, v21, v22, vcc
	v_sqrt_f32_e32 v22, v21
	s_nop 0
	v_add_u32_e32 v23, -1, v22
	v_fma_f32 v24, -v23, v22, v21
	v_cmp_ge_f32_e64 s[8:9], 0, v24
	v_add_u32_e32 v24, 1, v22
	s_nop 0
	v_cndmask_b32_e64 v23, v22, v23, s[8:9]
	v_fma_f32 v22, -v24, v22, v21
	v_cmp_lt_f32_e64 s[8:9], 0, v22
	s_nop 1
	v_cndmask_b32_e64 v22, v23, v24, s[8:9]
	v_mul_f32_e32 v23, 0x37800000, v22
	v_cndmask_b32_e32 v22, v22, v23, vcc
	v_cmp_class_f32_e32 vcc, v21, v101
	s_nop 1
	v_cndmask_b32_e32 v21, v22, v21, vcc
	s_nop 0
	v_div_scale_f32 v24, vcc, 1.0, v21, 1.0
	v_rcp_f32_e32 v46, v21
	v_mul_f32_e32 v21, v121, v121
; DI void gla_stage3(const Ctx& c0, int layer, int unit, int cb, LAS unsigned char* lds) {
;     ...
;     float rs[16];
; #pragma unroll
;     for (int rg = 0; rg < 16; ++rg) { float ss = o[0][rg] * o[0][rg] + o[1][rg] * o[1][rg] + o[2][rg] * o[2][rg] + o[3][rg] * o[3][rg];
;         ss += __shfl_xor(ss, 1); ss += __shfl_xor(ss, 2); ss += __shfl_xor(ss, 4); ss += __shfl_xor(ss, 8); ss += __shfl_xor(ss, 16);
;         rs[rg] = 1.f / sqrtf(ss * (1.f / 128.f) + EPS); }
	v_fmac_f32_e32 v21, v137, v137
	v_fmac_f32_e32 v21, v105, v105
	v_fmac_f32_e32 v21, v18, v18
	s_nop 1
	v_add_f32_dpp v21, v21, v21 quad_perm:[1,0,3,2] row_mask:0xf bank_mask:0xf
	v_mul_f32_e32 v19, v19, v46
	s_nop 1
	v_add_f32_dpp v21, v21, v21 quad_perm:[2,3,0,1] row_mask:0xf bank_mask:0xf
	s_nop 1
	v_add_f32_dpp v21, v21, v21 row_half_mirror row_mask:0xf bank_mask:0xf
	s_nop 1
	v_add_f32_dpp v21, v21, v21 row_mirror row_mask:0xf bank_mask:0xf
	v_mov_b32_e32 v22, v21
	v_mov_b32_e32 v23, v21
	s_nop 1
	v_permlane16_swap_b32_e32 v22, v23
	v_add_f32_e32 v21, v22, v23
	v_fmamk_f32 v21, v21, 0x3c000000, v100
	v_cmp_gt_f32_e32 vcc, s33, v21
	v_mul_f32_e32 v22, 0x4f800000, v21
	s_nop 0
	v_cndmask_b32_e32 v21, v21, v22, vcc
	v_sqrt_f32_e32 v22, v21
	s_nop 0
	v_add_u32_e32 v23, -1, v22
	v_fma_f32 v24, -v23, v22, v21
	v_cmp_ge_f32_e64 s[8:9], 0, v24
	v_add_u32_e32 v24, 1, v22
	s_nop 0
	v_cndmask_b32_e64 v23, v22, v23, s[8:9]
	v_fma_f32 v22, -v24, v22, v21
	v_cmp_lt_f32_e64 s[8:9], 0, v22
	s_nop 1
	v_cndmask_b32_e64 v22, v23, v24, s[8:9]
	v_mul_f32_e32 v23, 0x37800000, v22
	v_cndmask_b32_e32 v22, v22, v23, vcc
	v_cmp_class_f32_e32 vcc, v21, v101
	s_nop 1
	v_cndmask_b32_e32 v21, v22, v21, vcc
	s_nop 0
	v_div_scale_f32 v24, vcc, 1.0, v21, 1.0
	v_rcp_f32_e32 v45, v21
	v_mul_f32_e32 v21, v120, v120
	v_fmac_f32_e32 v21, v136, v136
	v_fmac_f32_e32 v21, v104, v104
	v_fmac_f32_e32 v21, v17, v17
	s_nop 1
	v_add_f32_dpp v21, v21, v21 quad_perm:[1,0,3,2] row_mask:0xf bank_mask:0xf
	v_mul_f32_e32 v18, v18, v45
	s_nop 1
	v_add_f32_dpp v21, v21, v21 quad_perm:[2,3,0,1] row_mask:0xf bank_mask:0xf
	s_nop 1
	v_add_f32_dpp v21, v21, v21 row_half_mirror row_mask:0xf bank_mask:0xf
	s_nop 1
	v_add_f32_dpp v21, v21, v21 row_mirror row_mask:0xf bank_mask:0xf
	v_mov_b32_e32 v22, v21
	v_mov_b32_e32 v23, v21
	s_nop 1
	v_permlane16_swap_b32_e32 v22, v23
	v_add_f32_e32 v21, v22, v23
	v_fmamk_f32 v21, v21, 0x3c000000, v100
	v_cmp_gt_f32_e32 vcc, s33, v21
	v_mul_f32_e32 v22, 0x4f800000, v21
	s_nop 0
	v_cndmask_b32_e32 v21, v21, v22, vcc
	v_sqrt_f32_e32 v22, v21
	s_nop 0
	v_add_u32_e32 v23, -1, v22
	v_fma_f32 v24, -v23, v22, v21
	v_cmp_ge_f32_e64 s[8:9], 0, v24
	v_add_u32_e32 v24, 1, v22
	s_nop 0
	v_cndmask_b32_e64 v23, v22, v23, s[8:9]
	v_fma_f32 v22, -v24, v22, v21
	v_cmp_lt_f32_e64 s[8:9], 0, v22
	s_nop 1
	v_cndmask_b32_e64 v22, v23, v24, s[8:9]
	v_mul_f32_e32 v23, 0x37800000, v22
	v_cndmask_b32_e32 v22, v22, v23, vcc
	v_cmp_class_f32_e32 vcc, v21, v101
	s_nop 1
	v_cndmask_b32_e32 v21, v22, v21, vcc
	s_nop 0
	v_div_scale_f32 v24, vcc, 1.0, v21, 1.0
	v_rcp_f32_e32 v44, v21
	v_mul_f32_e32 v21, v119, v119
	v_fmac_f32_e32 v21, v135, v135
	v_fmac_f32_e32 v21, v103, v103
	v_fmac_f32_e32 v21, v16, v16
	s_nop 1
	v_add_f32_dpp v21, v21, v21 quad_perm:[1,0,3,2] row_mask:0xf bank_mask:0xf
	v_mul_f32_e32 v17, v17, v44
	s_nop 1
	v_add_f32_dpp v21, v21, v21 quad_perm:[2,3,0,1] row_mask:0xf bank_mask:0xf
	s_nop 1
	v_add_f32_dpp v21, v21, v21 row_half_mirror row_mask:0xf bank_mask:0xf
	s_nop 1
	v_add_f32_dpp v21, v21, v21 row_mirror row_mask:0xf bank_mask:0xf
	v_mov_b32_e32 v22, v21
	v_mov_b32_e32 v23, v21
	s_nop 1
	v_permlane16_swap_b32_e32 v22, v23
	v_add_f32_e32 v21, v22, v23
	v_fmamk_f32 v21, v21, 0x3c000000, v100
	v_cmp_gt_f32_e32 vcc, s33, v21
	v_mul_f32_e32 v22, 0x4f800000, v21
	s_nop 0
	v_cndmask_b32_e32 v21, v21, v22, vcc
	v_sqrt_f32_e32 v22, v21
	s_nop 0
	v_add_u32_e32 v23, -1, v22
	v_fma_f32 v24, -v23, v22, v21
	v_cmp_ge_f32_e64 s[8:9], 0, v24
	v_add_u32_e32 v24, 1, v22
	s_nop 0
	v_cndmask_b32_e64 v23, v22, v23, s[8:9]
	v_fma_f32 v22, -v24, v22, v21
	v_cmp_lt_f32_e64 s[8:9], 0, v22
	s_nop 1
	v_cndmask_b32_e64 v22, v23, v24, s[8:9]
	v_mul_f32_e32 v23, 0x37800000, v22
	v_cndmask_b32_e32 v22, v22, v23, vcc
	v_cmp_class_f32_e32 vcc, v21, v101
	s_nop 1
	v_cndmask_b32_e32 v21, v22, v21, vcc
	s_nop 0
	v_div_scale_f32 v24, vcc, 1.0, v21, 1.0
	v_rcp_f32_e32 v43, v21
	v_mul_f32_e32 v21, v118, v118
	v_fmac_f32_e32 v21, v134, v134
	v_fmac_f32_e32 v21, v102, v102
	v_fmac_f32_e32 v21, v15, v15
	s_nop 1
	v_add_f32_dpp v21, v21, v21 quad_perm:[1,0,3,2] row_mask:0xf bank_mask:0xf
	v_mul_f32_e32 v16, v16, v43
	s_nop 1
	v_add_f32_dpp v21, v21, v21 quad_perm:[2,3,0,1] row_mask:0xf bank_mask:0xf
	s_nop 1
	v_add_f32_dpp v21, v21, v21 row_half_mirror row_mask:0xf bank_mask:0xf
	s_nop 1
	v_add_f32_dpp v21, v21, v21 row_mirror row_mask:0xf bank_mask:0xf
	v_mov_b32_e32 v22, v21
	v_mov_b32_e32 v23, v21
	s_nop 1
	v_permlane16_swap_b32_e32 v22, v23
	v_add_f32_e32 v21, v22, v23
	v_fmamk_f32 v21, v21, 0x3c000000, v100
	v_cmp_gt_f32_e32 vcc, s33, v21
	v_mul_f32_e32 v22, 0x4f800000, v21
	s_nop 0
	v_cndmask_b32_e32 v21, v21, v22, vcc
	v_sqrt_f32_e32 v22, v21
	s_nop 0
	v_add_u32_e32 v23, -1, v22
	v_fma_f32 v24, -v23, v22, v21
	v_cmp_ge_f32_e64 s[8:9], 0, v24
	v_add_u32_e32 v24, 1, v22
	s_nop 0
	v_cndmask_b32_e64 v23, v22, v23, s[8:9]
	v_fma_f32 v22, -v24, v22, v21
	v_cmp_lt_f32_e64 s[8:9], 0, v22
	s_nop 1
	v_cndmask_b32_e64 v22, v23, v24, s[8:9]
	v_mul_f32_e32 v23, 0x37800000, v22
	v_cndmask_b32_e32 v22, v22, v23, vcc
	v_cmp_class_f32_e32 vcc, v21, v101
	s_nop 1
	v_cndmask_b32_e32 v21, v22, v21, vcc
	s_nop 0
	v_div_scale_f32 v24, vcc, 1.0, v21, 1.0
	v_rcp_f32_e32 v42, v21
	v_mul_f32_e32 v21, v117, v117
	v_fmac_f32_e32 v21, v133, v133
	v_fmac_f32_e32 v21, v39, v39
	v_fmac_f32_e32 v21, v14, v14
	s_nop 1
	v_add_f32_dpp v21, v21, v21 quad_perm:[1,0,3,2] row_mask:0xf bank_mask:0xf
	v_mul_f32_e32 v15, v15, v42
	s_nop 1
	v_add_f32_dpp v21, v21, v21 quad_perm:[2,3,0,1] row_mask:0xf bank_mask:0xf
	s_nop 1
	v_add_f32_dpp v21, v21, v21 row_half_mirror row_mask:0xf bank_mask:0xf
	s_nop 1
	v_add_f32_dpp v21, v21, v21 row_mirror row_mask:0xf bank_mask:0xf
; DI void gla_stage3(const Ctx& c0, int layer, int unit, int cb, LAS unsigned char* lds) {
;     ...
;     float rs[16];
; #pragma unroll
;     for (int rg = 0; rg < 16; ++rg) { float ss = o[0][rg] * o[0][rg] + o[1][rg] * o[1][rg] + o[2][rg] * o[2][rg] + o[3][rg] * o[3][rg];
;         ss += __shfl_xor(ss, 1); ss += __shfl_xor(ss, 2); ss += __shfl_xor(ss, 4); ss += __shfl_xor(ss, 8); ss += __shfl_xor(ss, 16);
;         rs[rg] = 1.f / sqrtf(ss * (1.f / 128.f) + EPS); }
	v_mov_b32_e32 v22, v21
	v_mov_b32_e32 v23, v21
	s_nop 1
	v_permlane16_swap_b32_e32 v22, v23
	v_add_f32_e32 v21, v22, v23
	v_fmamk_f32 v21, v21, 0x3c000000, v100
	v_cmp_gt_f32_e32 vcc, s33, v21
	v_mul_f32_e32 v22, 0x4f800000, v21
	s_nop 0
	v_cndmask_b32_e32 v21, v21, v22, vcc
	v_sqrt_f32_e32 v22, v21
	s_nop 0
	v_add_u32_e32 v23, -1, v22
	v_fma_f32 v24, -v23, v22, v21
	v_cmp_ge_f32_e64 s[8:9], 0, v24
	v_add_u32_e32 v24, 1, v22
	s_nop 0
	v_cndmask_b32_e64 v23, v22, v23, s[8:9]
	v_fma_f32 v22, -v24, v22, v21
	v_cmp_lt_f32_e64 s[8:9], 0, v22
	s_nop 1
	v_cndmask_b32_e64 v22, v23, v24, s[8:9]
	v_mul_f32_e32 v23, 0x37800000, v22
	v_cndmask_b32_e32 v22, v22, v23, vcc
	v_cmp_class_f32_e32 vcc, v21, v101
	s_nop 1
	v_cndmask_b32_e32 v21, v22, v21, vcc
	s_nop 0
	v_div_scale_f32 v24, vcc, 1.0, v21, 1.0
	v_rcp_f32_e32 v41, v21
	v_mul_f32_e32 v21, v116, v116
	v_fmac_f32_e32 v21, v132, v132
	v_fmac_f32_e32 v21, v38, v38
	v_fmac_f32_e32 v21, v13, v13
	s_nop 1
	v_add_f32_dpp v21, v21, v21 quad_perm:[1,0,3,2] row_mask:0xf bank_mask:0xf
	v_mul_f32_e32 v39, v39, v41
	v_mul_f32_e32 v14, v14, v41
	s_nop 1
	v_add_f32_dpp v21, v21, v21 quad_perm:[2,3,0,1] row_mask:0xf bank_mask:0xf
	s_nop 1
	v_add_f32_dpp v21, v21, v21 row_half_mirror row_mask:0xf bank_mask:0xf
	s_nop 1
	v_add_f32_dpp v21, v21, v21 row_mirror row_mask:0xf bank_mask:0xf
	v_mov_b32_e32 v22, v21
	v_mov_b32_e32 v23, v21
	s_nop 1
	v_permlane16_swap_b32_e32 v22, v23
	v_add_f32_e32 v21, v22, v23
	v_fmamk_f32 v21, v21, 0x3c000000, v100
	v_cmp_gt_f32_e32 vcc, s33, v21
	v_mul_f32_e32 v22, 0x4f800000, v21
	s_nop 0
	v_cndmask_b32_e32 v21, v21, v22, vcc
	v_sqrt_f32_e32 v22, v21
	s_nop 0
	v_add_u32_e32 v23, -1, v22
	v_fma_f32 v24, -v23, v22, v21
	v_cmp_ge_f32_e64 s[8:9], 0, v24
	v_add_u32_e32 v24, 1, v22
	s_nop 0
	v_cndmask_b32_e64 v23, v22, v23, s[8:9]
	v_fma_f32 v22, -v24, v22, v21
	v_cmp_lt_f32_e64 s[8:9], 0, v22
	s_nop 1
	v_cndmask_b32_e64 v22, v23, v24, s[8:9]
	v_mul_f32_e32 v23, 0x37800000, v22
	v_cndmask_b32_e32 v22, v22, v23, vcc
	v_cmp_class_f32_e32 vcc, v21, v101
	s_nop 1
	v_cndmask_b32_e32 v21, v22, v21, vcc
	s_nop 0
	v_div_scale_f32 v24, vcc, 1.0, v21, 1.0
	v_rcp_f32_e32 v40, v21
	v_mul_f32_e32 v21, v115, v115
	v_fmac_f32_e32 v21, v131, v131
	v_fmac_f32_e32 v21, v37, v37
	v_fmac_f32_e32 v21, v12, v12
	s_nop 1
	v_add_f32_dpp v21, v21, v21 quad_perm:[1,0,3,2] row_mask:0xf bank_mask:0xf
	v_mul_f32_e32 v38, v38, v40
	v_mul_f32_e32 v13, v13, v40
	s_nop 1
	v_add_f32_dpp v21, v21, v21 quad_perm:[2,3,0,1] row_mask:0xf bank_mask:0xf
	s_nop 1
	v_add_f32_dpp v21, v21, v21 row_half_mirror row_mask:0xf bank_mask:0xf
	s_nop 1
	v_add_f32_dpp v21, v21, v21 row_mirror row_mask:0xf bank_mask:0xf
	v_mov_b32_e32 v22, v21
	v_mov_b32_e32 v23, v21
	s_nop 1
	v_permlane16_swap_b32_e32 v22, v23
	v_add_f32_e32 v21, v22, v23
	v_fmamk_f32 v21, v21, 0x3c000000, v100
	v_cmp_gt_f32_e32 vcc, s33, v21
	v_mul_f32_e32 v22, 0x4f800000, v21
	s_nop 0
	v_cndmask_b32_e32 v21, v21, v22, vcc
	v_sqrt_f32_e32 v22, v21
	s_nop 0
	v_add_u32_e32 v23, -1, v22
	v_fma_f32 v24, -v23, v22, v21
	v_cmp_ge_f32_e64 s[8:9], 0, v24
	v_add_u32_e32 v24, 1, v22
	s_nop 0
	v_cndmask_b32_e64 v23, v22, v23, s[8:9]
	v_fma_f32 v22, -v24, v22, v21
	v_cmp_lt_f32_e64 s[8:9], 0, v22
	s_nop 1
	v_cndmask_b32_e64 v22, v23, v24, s[8:9]
	v_mul_f32_e32 v23, 0x37800000, v22
	v_cndmask_b32_e32 v22, v22, v23, vcc
	v_cmp_class_f32_e32 vcc, v21, v101
	s_nop 1
	v_cndmask_b32_e32 v21, v22, v21, vcc
	s_nop 0
	v_div_scale_f32 v24, vcc, 1.0, v21, 1.0
	v_rcp_f32_e32 v35, v21
	v_mul_f32_e32 v21, v114, v114
	v_fmac_f32_e32 v21, v130, v130
	v_fmac_f32_e32 v21, v36, v36
	v_fmac_f32_e32 v21, v11, v11
	s_nop 1
	v_add_f32_dpp v21, v21, v21 quad_perm:[1,0,3,2] row_mask:0xf bank_mask:0xf
	v_mul_f32_e32 v37, v37, v35
	v_mul_f32_e32 v12, v12, v35
	s_nop 1
	v_add_f32_dpp v21, v21, v21 quad_perm:[2,3,0,1] row_mask:0xf bank_mask:0xf
	s_nop 1
	v_add_f32_dpp v21, v21, v21 row_half_mirror row_mask:0xf bank_mask:0xf
	s_nop 1
	v_add_f32_dpp v21, v21, v21 row_mirror row_mask:0xf bank_mask:0xf
	v_mov_b32_e32 v22, v21
	v_mov_b32_e32 v23, v21
	s_nop 1
	v_permlane16_swap_b32_e32 v22, v23
	v_add_f32_e32 v21, v22, v23
	v_fmamk_f32 v21, v21, 0x3c000000, v100
	v_cmp_gt_f32_e32 vcc, s33, v21
	v_mul_f32_e32 v22, 0x4f800000, v21
	s_nop 0
	v_cndmask_b32_e32 v21, v21, v22, vcc
	v_sqrt_f32_e32 v22, v21
	s_nop 0
	v_add_u32_e32 v23, -1, v22
	v_fma_f32 v24, -v23, v22, v21
	v_cmp_ge_f32_e64 s[8:9], 0, v24
	v_add_u32_e32 v24, 1, v22
	s_nop 0
	v_cndmask_b32_e64 v23, v22, v23, s[8:9]
	v_fma_f32 v22, -v24, v22, v21
	v_cmp_lt_f32_e64 s[8:9], 0, v22
	s_nop 1
	v_cndmask_b32_e64 v22, v23, v24, s[8:9]
	v_mul_f32_e32 v23, 0x37800000, v22
	v_cndmask_b32_e32 v22, v22, v23, vcc
	v_cmp_class_f32_e32 vcc, v21, v101
	s_nop 1
	v_cndmask_b32_e32 v21, v22, v21, vcc
	s_nop 0
	v_div_scale_f32 v24, vcc, 1.0, v21, 1.0
	v_rcp_f32_e32 v31, v21
	v_mul_f32_e32 v21, v113, v113
	v_fmac_f32_e32 v21, v129, v129
	v_fmac_f32_e32 v21, v34, v34
	v_fmac_f32_e32 v21, v10, v10
	s_nop 1
	v_add_f32_dpp v21, v21, v21 quad_perm:[1,0,3,2] row_mask:0xf bank_mask:0xf
	v_mul_f32_e32 v36, v36, v31
	v_mul_f32_e32 v11, v11, v31
	s_nop 1
	v_add_f32_dpp v21, v21, v21 quad_perm:[2,3,0,1] row_mask:0xf bank_mask:0xf
	s_nop 1
	v_add_f32_dpp v21, v21, v21 row_half_mirror row_mask:0xf bank_mask:0xf
	s_nop 1
	v_add_f32_dpp v21, v21, v21 row_mirror row_mask:0xf bank_mask:0xf
	v_mov_b32_e32 v22, v21
	v_mov_b32_e32 v23, v21
	s_nop 1
	v_permlane16_swap_b32_e32 v22, v23
	v_add_f32_e32 v21, v22, v23
	v_fmamk_f32 v21, v21, 0x3c000000, v100
	v_cmp_gt_f32_e32 vcc, s33, v21
	v_mul_f32_e32 v22, 0x4f800000, v21
	s_nop 0
	v_cndmask_b32_e32 v21, v21, v22, vcc
	v_sqrt_f32_e32 v22, v21
	s_nop 0
; DI void gla_stage3(const Ctx& c0, int layer, int unit, int cb, LAS unsigned char* lds) {
;     ...
;     float rs[16];
; #pragma unroll
;     for (int rg = 0; rg < 16; ++rg) { float ss = o[0][rg] * o[0][rg] + o[1][rg] * o[1][rg] + o[2][rg] * o[2][rg] + o[3][rg] * o[3][rg];
;         ss += __shfl_xor(ss, 1); ss += __shfl_xor(ss, 2); ss += __shfl_xor(ss, 4); ss += __shfl_xor(ss, 8); ss += __shfl_xor(ss, 16);
;         rs[rg] = 1.f / sqrtf(ss * (1.f / 128.f) + EPS); }
	v_add_u32_e32 v23, -1, v22
	v_fma_f32 v24, -v23, v22, v21
	v_cmp_ge_f32_e64 s[8:9], 0, v24
	v_add_u32_e32 v24, 1, v22
	s_nop 0
	v_cndmask_b32_e64 v23, v22, v23, s[8:9]
	v_fma_f32 v22, -v24, v22, v21
	v_cmp_lt_f32_e64 s[8:9], 0, v22
	s_nop 1
	v_cndmask_b32_e64 v22, v23, v24, s[8:9]
	v_mul_f32_e32 v23, 0x37800000, v22
	v_cndmask_b32_e32 v22, v22, v23, vcc
	v_cmp_class_f32_e32 vcc, v21, v101
	s_nop 1
	v_cndmask_b32_e32 v21, v22, v21, vcc
	s_nop 0
	v_div_scale_f32 v24, vcc, 1.0, v21, 1.0
	v_rcp_f32_e32 v27, v21
	v_mul_f32_e32 v21, v112, v112
	v_fmac_f32_e32 v21, v128, v128
	v_fmac_f32_e32 v21, v33, v33
	v_fmac_f32_e32 v21, v9, v9
	s_nop 1
	v_add_f32_dpp v21, v21, v21 quad_perm:[1,0,3,2] row_mask:0xf bank_mask:0xf
	v_mul_f32_e32 v34, v34, v27
	v_mul_f32_e32 v10, v10, v27
	s_nop 1
	v_add_f32_dpp v21, v21, v21 quad_perm:[2,3,0,1] row_mask:0xf bank_mask:0xf
	s_nop 1
	v_add_f32_dpp v21, v21, v21 row_half_mirror row_mask:0xf bank_mask:0xf
	s_nop 1
	v_add_f32_dpp v21, v21, v21 row_mirror row_mask:0xf bank_mask:0xf
	v_mov_b32_e32 v22, v21
	v_mov_b32_e32 v23, v21
	s_nop 1
	v_permlane16_swap_b32_e32 v22, v23
	v_add_f32_e32 v21, v22, v23
	v_fmamk_f32 v21, v21, 0x3c000000, v100
	v_cmp_gt_f32_e32 vcc, s33, v21
	v_mul_f32_e32 v22, 0x4f800000, v21
	s_nop 0
	v_cndmask_b32_e32 v21, v21, v22, vcc
	v_sqrt_f32_e32 v22, v21
	s_nop 0
	v_add_u32_e32 v23, -1, v22
	v_fma_f32 v24, -v23, v22, v21
	v_cmp_ge_f32_e64 s[8:9], 0, v24
	v_add_u32_e32 v24, 1, v22
	s_nop 0
	v_cndmask_b32_e64 v23, v22, v23, s[8:9]
	v_fma_f32 v22, -v24, v22, v21
	v_cmp_lt_f32_e64 s[8:9], 0, v22
	s_nop 1
	v_cndmask_b32_e64 v22, v23, v24, s[8:9]
	v_mul_f32_e32 v23, 0x37800000, v22
	v_cndmask_b32_e32 v22, v22, v23, vcc
	v_cmp_class_f32_e32 vcc, v21, v101
	s_nop 1
	v_cndmask_b32_e32 v21, v22, v21, vcc
	s_nop 0
	v_div_scale_f32 v24, vcc, 1.0, v21, 1.0
	v_rcp_f32_e32 v25, v21
	v_mul_f32_e32 v21, v111, v111
	v_fmac_f32_e32 v21, v127, v127
	v_fmac_f32_e32 v21, v32, v32
	v_fmac_f32_e32 v21, v8, v8
	s_nop 1
	v_add_f32_dpp v21, v21, v21 quad_perm:[1,0,3,2] row_mask:0xf bank_mask:0xf
	v_mul_f32_e32 v33, v33, v25
	v_mul_f32_e32 v9, v9, v25
	s_nop 1
	v_add_f32_dpp v21, v21, v21 quad_perm:[2,3,0,1] row_mask:0xf bank_mask:0xf
	s_nop 1
	v_add_f32_dpp v21, v21, v21 row_half_mirror row_mask:0xf bank_mask:0xf
	s_nop 1
	v_add_f32_dpp v21, v21, v21 row_mirror row_mask:0xf bank_mask:0xf
	v_mov_b32_e32 v22, v21
	v_mov_b32_e32 v23, v21
	s_nop 1
	v_permlane16_swap_b32_e32 v22, v23
	v_add_f32_e32 v21, v22, v23
	v_fmamk_f32 v21, v21, 0x3c000000, v100
	v_cmp_gt_f32_e32 vcc, s33, v21
	v_mul_f32_e32 v22, 0x4f800000, v21
	s_nop 0
	v_cndmask_b32_e32 v21, v21, v22, vcc
	v_sqrt_f32_e32 v22, v21
	s_nop 0
	v_add_u32_e32 v23, -1, v22
	v_fma_f32 v24, -v23, v22, v21
	v_cmp_ge_f32_e64 s[8:9], 0, v24
	v_add_u32_e32 v24, 1, v22
	s_nop 0
	v_cndmask_b32_e64 v23, v22, v23, s[8:9]
	v_fma_f32 v22, -v24, v22, v21
	v_cmp_lt_f32_e64 s[8:9], 0, v22
	s_nop 1
	v_cndmask_b32_e64 v22, v23, v24, s[8:9]
	v_mul_f32_e32 v23, 0x37800000, v22
	v_cndmask_b32_e32 v22, v22, v23, vcc
	v_cmp_class_f32_e32 vcc, v21, v101
	s_nop 1
	v_cndmask_b32_e32 v21, v22, v21, vcc
	s_nop 0
	v_div_scale_f32 v24, vcc, 1.0, v21, 1.0
	v_rcp_f32_e32 v24, v21
	v_mul_f32_e32 v21, v110, v110
	v_fmac_f32_e32 v21, v126, v126
	v_fmac_f32_e32 v21, v30, v30
	v_fmac_f32_e32 v21, v7, v7
	s_nop 1
	v_add_f32_dpp v21, v21, v21 quad_perm:[1,0,3,2] row_mask:0xf bank_mask:0xf
	v_mul_f32_e32 v32, v32, v24
	v_mul_f32_e32 v8, v8, v24
	s_nop 1
	v_add_f32_dpp v21, v21, v21 quad_perm:[2,3,0,1] row_mask:0xf bank_mask:0xf
	s_nop 1
	v_add_f32_dpp v21, v21, v21 row_half_mirror row_mask:0xf bank_mask:0xf
	s_nop 1
	v_add_f32_dpp v21, v21, v21 row_mirror row_mask:0xf bank_mask:0xf
	v_mov_b32_e32 v22, v21
	v_mov_b32_e32 v23, v21
	s_nop 1
	v_permlane16_swap_b32_e32 v22, v23
	v_add_f32_e32 v21, v22, v23
	v_fmamk_f32 v21, v21, 0x3c000000, v100
	v_cmp_gt_f32_e32 vcc, s33, v21
	v_mul_f32_e32 v22, 0x4f800000, v21
	s_nop 0
	v_cndmask_b32_e32 v21, v21, v22, vcc
	v_sqrt_f32_e32 v22, v21
	s_nop 0
	v_add_u32_e32 v23, -1, v22
	v_fma_f32 v49, -v23, v22, v21
	v_cmp_ge_f32_e64 s[8:9], 0, v49
	v_add_u32_e32 v49, 1, v22
	s_nop 0
	v_cndmask_b32_e64 v23, v22, v23, s[8:9]
	v_fma_f32 v22, -v49, v22, v21
	v_cmp_lt_f32_e64 s[8:9], 0, v22
	s_nop 1
	v_cndmask_b32_e64 v22, v23, v49, s[8:9]
	v_mul_f32_e32 v23, 0x37800000, v22
	v_cndmask_b32_e32 v22, v22, v23, vcc
	v_cmp_class_f32_e32 vcc, v21, v101
	s_nop 1
	v_cndmask_b32_e32 v21, v22, v21, vcc
	s_nop 0
	v_div_scale_f32 v49, vcc, 1.0, v21, 1.0
	v_rcp_f32_e32 v23, v21
	v_mul_f32_e32 v21, v109, v109
	v_fmac_f32_e32 v21, v125, v125
	v_fmac_f32_e32 v21, v29, v29
	v_fmac_f32_e32 v21, v6, v6
	s_nop 1
	v_add_f32_dpp v21, v21, v21 quad_perm:[1,0,3,2] row_mask:0xf bank_mask:0xf
	v_mul_f32_e32 v30, v30, v23
	v_mul_f32_e32 v7, v7, v23
	s_nop 1
	v_add_f32_dpp v21, v21, v21 quad_perm:[2,3,0,1] row_mask:0xf bank_mask:0xf
	s_nop 1
	v_add_f32_dpp v21, v21, v21 row_half_mirror row_mask:0xf bank_mask:0xf
	s_nop 1
	v_add_f32_dpp v21, v21, v21 row_mirror row_mask:0xf bank_mask:0xf
	v_mov_b32_e32 v22, v21
	v_mov_b32_e32 v49, v21
	s_nop 1
	v_permlane16_swap_b32_e32 v22, v49
	v_add_f32_e32 v21, v22, v49
	v_fmamk_f32 v21, v21, 0x3c000000, v100
	v_cmp_gt_f32_e32 vcc, s33, v21
	v_mul_f32_e32 v22, 0x4f800000, v21
	s_nop 0
	v_cndmask_b32_e32 v21, v21, v22, vcc
	v_sqrt_f32_e32 v22, v21
	s_nop 0
	v_add_u32_e32 v49, -1, v22
	v_fma_f32 v50, -v49, v22, v21
	v_cmp_ge_f32_e64 s[8:9], 0, v50
	v_add_u32_e32 v50, 1, v22
	s_nop 0
	v_cndmask_b32_e64 v49, v22, v49, s[8:9]
	v_fma_f32 v22, -v50, v22, v21
	v_cmp_lt_f32_e64 s[8:9], 0, v22
	s_nop 1
	v_cndmask_b32_e64 v22, v49, v50, s[8:9]
	v_mul_f32_e32 v49, 0x37800000, v22
; #define LAS __attribute__((address_space(3)))
; #define LDS_WAIT() asm volatile("s_waitcnt lgkmcnt(0)" ::: "memory")
; DI unsigned cvtpk(float lo, float hi) { f32x2 v = {lo, hi}; bf16x2_t b = __builtin_convertvector(v, bf16x2_t); return __builtin_bit_cast(unsigned, b); }
; DI float bf2f(bf16 b) { return __uint_as_float(((unsigned)b) << 16); }
; DI float siluf_(float x) { return x / (1.f + __expf(-x)); }
; DI void g3_tile_in(const bf16* g, LAS unsigned char* R, int lane) {
; #pragma unroll
;     for (int it = 0; it < 8; ++it) { const int row = 4 * it + (lane >> 4), ch = lane & 15;
;         *(LAS u32x4*)(R + row * G3_PITCH + ch * 16) = *(const u32x4*)(g + (size_t)row * 512 + ch * 8); }
;     LDS_WAIT();
; DI void gla_stage3(const Ctx& c0, int layer, int unit, int cb, LAS unsigned char* lds) {
;     ...
;     for (int rg = 0; rg < 16; ++rg) { float ss = o[0][rg] * o[0][rg] + o[1][rg] * o[1][rg] + o[2][rg] * o[2][rg] + o[3][rg] * o[3][rg];
;         ss += __shfl_xor(ss, 1); ss += __shfl_xor(ss, 2); ss += __shfl_xor(ss, 4); ss += __shfl_xor(ss, 8); ss += __shfl_xor(ss, 16);
;         rs[rg] = 1.f / sqrtf(ss * (1.f / 128.f) + EPS); }
;     LDS_WAIT();
;     g3_tile_in((const bf16*)(c.ws + O_GR) + row0 * 512 + h * 128, R, lane);
; #pragma unroll
;     for (int vb = 0; vb < 4; ++vb) { const float g = gn[32 * vb + r];
; #pragma unroll
;         for (int rg = 0; rg < 16; ++rg) { LAS bf16* e = (LAS bf16*)(R + (4 * hi) * G3_PITCH + r * 2 + ((rg & 3) + 8 * (rg >> 2)) * G3_PITCH + 64 * vb);
;             const float z = bf2f(*e);
;             *e = (bf16)(cvtpk(o[vb][rg] * rs[rg] * g * siluf_(z), 0.f) & 0xffffu); }
	v_cndmask_b32_e32 v22, v22, v49, vcc
	v_cmp_class_f32_e32 vcc, v21, v101
	s_nop 1
	v_cndmask_b32_e32 v21, v22, v21, vcc
	s_nop 0
	v_div_scale_f32 v50, vcc, 1.0, v21, 1.0
	v_rcp_f32_e32 v22, v21
	v_mul_f32_e32 v21, v108, v108
	v_fmac_f32_e32 v21, v124, v124
	v_fmac_f32_e32 v21, v28, v28
	v_fmac_f32_e32 v21, v5, v5
	s_nop 1
	v_add_f32_dpp v21, v21, v21 quad_perm:[1,0,3,2] row_mask:0xf bank_mask:0xf
	v_mul_f32_e32 v29, v29, v22
	v_mul_f32_e32 v6, v6, v22
	s_nop 1
	v_add_f32_dpp v21, v21, v21 quad_perm:[2,3,0,1] row_mask:0xf bank_mask:0xf
	s_nop 1
	v_add_f32_dpp v21, v21, v21 row_half_mirror row_mask:0xf bank_mask:0xf
	s_nop 1
	v_add_f32_dpp v21, v21, v21 row_mirror row_mask:0xf bank_mask:0xf
	v_mov_b32_e32 v49, v21
	v_mov_b32_e32 v50, v21
	s_nop 1
	v_permlane16_swap_b32_e32 v49, v50
	v_add_f32_e32 v21, v49, v50
	v_fmamk_f32 v21, v21, 0x3c000000, v100
	v_cmp_gt_f32_e32 vcc, s33, v21
	v_mul_f32_e32 v49, 0x4f800000, v21
	s_nop 0
	v_cndmask_b32_e32 v21, v21, v49, vcc
	v_sqrt_f32_e32 v49, v21
	s_nop 0
	v_add_u32_e32 v50, -1, v49
	v_fma_f32 v51, -v50, v49, v21
	v_cmp_ge_f32_e64 s[8:9], 0, v51
	v_add_u32_e32 v51, 1, v49
	s_nop 0
	v_cndmask_b32_e64 v50, v49, v50, s[8:9]
	v_fma_f32 v49, -v51, v49, v21
	v_cmp_lt_f32_e64 s[8:9], 0, v49
	s_nop 1
	v_cndmask_b32_e64 v49, v50, v51, s[8:9]
	v_mul_f32_e32 v50, 0x37800000, v49
	v_cndmask_b32_e32 v49, v49, v50, vcc
	v_cmp_class_f32_e32 vcc, v21, v101
	s_nop 1
	v_cndmask_b32_e32 v21, v49, v21, vcc
	s_nop 0
	v_div_scale_f32 v51, vcc, 1.0, v21, 1.0
	v_rcp_f32_e32 v21, v21
	v_mul_f32_e32 v49, v107, v107
	v_fmac_f32_e32 v49, v123, v123
	v_fmac_f32_e32 v49, v26, v26
	v_fmac_f32_e32 v49, v4, v4
	ds_bpermute_b32 v2, v2, v49
	v_mul_f32_e32 v28, v28, v21
	v_mul_f32_e32 v5, v5, v21
	s_waitcnt lgkmcnt(0)
	v_add_f32_e32 v2, v49, v2
	ds_bpermute_b32 v3, v3, v2
	s_waitcnt lgkmcnt(0)
	v_add_f32_e32 v2, v2, v3
	ds_bpermute_b32 v3, v20, v2
	s_waitcnt lgkmcnt(0)
	v_add_f32_e32 v2, v2, v3
	ds_bpermute_b32 v3, v47, v2
	s_waitcnt lgkmcnt(0)
	v_add_f32_e32 v2, v2, v3
	ds_bpermute_b32 v3, v48, v2
	s_waitcnt lgkmcnt(0)
	v_add_f32_e32 v2, v2, v3
	v_fmamk_f32 v2, v2, 0x3c000000, v100
	v_cmp_gt_f32_e32 vcc, s33, v2
	v_mul_f32_e32 v3, 0x4f800000, v2
	s_nop 0
	v_cndmask_b32_e32 v2, v2, v3, vcc
	v_sqrt_f32_e32 v3, v2
	s_nop 0
	v_add_u32_e32 v20, -1, v3
	v_fma_f32 v47, -v20, v3, v2
	v_cmp_ge_f32_e64 s[8:9], 0, v47
	v_add_u32_e32 v47, 1, v3
	s_nop 0
	v_cndmask_b32_e64 v20, v3, v20, s[8:9]
	v_fma_f32 v3, -v47, v3, v2
	v_cmp_lt_f32_e64 s[8:9], 0, v3
	s_nop 1
	v_cndmask_b32_e64 v3, v20, v47, s[8:9]
	v_mul_f32_e32 v20, 0x37800000, v3
	v_cndmask_b32_e32 v3, v3, v20, vcc
	v_cmp_class_f32_e32 vcc, v2, v101
	s_nop 1
	v_cndmask_b32_e32 v2, v3, v2, vcc
	s_nop 0
	v_rcp_f32_e32 v20, v2
	v_mul_f32_e32 v47, v138, v46
	v_mul_f32_e32 v26, v26, v20
	v_mul_f32_e32 v4, v4, v20
	s_waitcnt vmcnt(2) lgkmcnt(0)
	ds_write_b128 v92, v[164:167]
	s_waitcnt vmcnt(0) lgkmcnt(0)
	ds_write_b128 v92, v[170:173] offset:1088
	s_waitcnt vmcnt(13) lgkmcnt(0)
	ds_write_b128 v92, v[174:177] offset:2176
	s_waitcnt vmcnt(8) lgkmcnt(0)
	ds_write_b128 v92, v[178:181] offset:3264
	s_waitcnt vmcnt(9) lgkmcnt(0)
	ds_write_b128 v92, v[196:199] offset:4352
	s_waitcnt vmcnt(10) lgkmcnt(0)
	ds_write_b128 v92, v[200:203] offset:5440
	v_lshl_add_u64 v[2:3], v[168:169], 0, v[80:81]
	s_waitcnt vmcnt(5) lgkmcnt(0)
	ds_write_b128 v92, v[204:207] offset:6528
	global_load_dwordx4 v[48:51], v[2:3], off
	s_waitcnt vmcnt(0) lgkmcnt(0)
	ds_write_b128 v92, v[48:51] offset:7616
	s_waitcnt lgkmcnt(0)
	ds_read_u16 v3, v1
	s_waitcnt lgkmcnt(0)
	v_lshlrev_b32_e32 v3, 16, v3
	v_mul_f32_e32 v48, 0xbfb8aa3b, v3
	v_exp_f32_e32 v48, v48
	s_waitcnt vmcnt(0)
	v_mul_f32_e32 v47, v47, v232
	v_add_f32_e32 v48, 1.0, v48
	v_div_scale_f32 v49, s[0:1], v48, v48, v3
	s_nop 0
	v_rcp_f32_e32 v49, v48
	s_nop 0
	v_mul_f32_e32 v3, v3, v49
	v_mul_f32_e32 v3, v47, v3
	v_cvt_pk_bf16_f32 v3, v3, s0
	ds_write_b16 v1, v3
	ds_read_u16 v3, v1 offset:272
	v_mul_f32_e32 v47, v137, v45
	v_mul_f32_e32 v47, v47, v232
	s_waitcnt lgkmcnt(0)
	v_lshlrev_b32_e32 v3, 16, v3
	v_mul_f32_e32 v48, 0xbfb8aa3b, v3
	v_exp_f32_e32 v48, v48
	s_nop 0
	v_add_f32_e32 v48, 1.0, v48
	v_div_scale_f32 v49, s[0:1], v48, v48, v3
	s_nop 0
	v_rcp_f32_e32 v49, v48
	s_nop 0
	v_mul_f32_e32 v3, v3, v49
	v_mul_f32_e32 v3, v47, v3
	v_cvt_pk_bf16_f32 v3, v3, s0
	ds_write_b16 v1, v3 offset:272
	ds_read_u16 v3, v1 offset:544
	v_mul_f32_e32 v47, v136, v44
	v_mul_f32_e32 v47, v47, v232
	s_waitcnt lgkmcnt(0)
	v_lshlrev_b32_e32 v3, 16, v3
	v_mul_f32_e32 v48, 0xbfb8aa3b, v3
	v_exp_f32_e32 v48, v48
	s_nop 0
	v_add_f32_e32 v48, 1.0, v48
	v_div_scale_f32 v49, s[0:1], v48, v48, v3
	s_nop 0
	v_rcp_f32_e32 v49, v48
	s_nop 0
	v_mul_f32_e32 v3, v3, v49
	v_mul_f32_e32 v3, v47, v3
	v_cvt_pk_bf16_f32 v3, v3, s0
	ds_write_b16 v1, v3 offset:544
	ds_read_u16 v3, v1 offset:816
	v_mul_f32_e32 v47, v135, v43
	v_mul_f32_e32 v47, v47, v232
	s_waitcnt lgkmcnt(0)
	v_lshlrev_b32_e32 v3, 16, v3
	v_mul_f32_e32 v48, 0xbfb8aa3b, v3
	v_exp_f32_e32 v48, v48
	s_nop 0
	v_add_f32_e32 v48, 1.0, v48
	v_div_scale_f32 v49, s[0:1], v48, v48, v3
	s_nop 0
	v_rcp_f32_e32 v49, v48
	s_nop 0
	v_mul_f32_e32 v3, v3, v49
	v_mul_f32_e32 v3, v47, v3
	v_cvt_pk_bf16_f32 v3, v3, s0
	ds_write_b16 v1, v3 offset:816
	ds_read_u16 v3, v1 offset:2176
	v_mul_f32_e32 v47, v134, v42
	v_mul_f32_e32 v47, v47, v232
	s_waitcnt lgkmcnt(0)
	v_lshlrev_b32_e32 v3, 16, v3
	v_mul_f32_e32 v48, 0xbfb8aa3b, v3
	v_exp_f32_e32 v48, v48
	s_nop 0
	v_add_f32_e32 v48, 1.0, v48
	v_div_scale_f32 v49, s[0:1], v48, v48, v3
	s_nop 0
	v_rcp_f32_e32 v49, v48
	s_nop 0
	v_mul_f32_e32 v3, v3, v49
	v_mul_f32_e32 v3, v47, v3
	v_cvt_pk_bf16_f32 v3, v3, s0
	ds_write_b16 v1, v3 offset:2176
	ds_read_u16 v3, v1 offset:2448
	v_mul_f32_e32 v47, v133, v41
	v_mul_f32_e32 v47, v47, v232
	s_waitcnt lgkmcnt(0)
; #define LAS __attribute__((address_space(3)))
; DI unsigned cvtpk(float lo, float hi) { f32x2 v = {lo, hi}; bf16x2_t b = __builtin_convertvector(v, bf16x2_t); return __builtin_bit_cast(unsigned, b); }
; DI float bf2f(bf16 b) { return __uint_as_float(((unsigned)b) << 16); }
; DI float siluf_(float x) { return x / (1.f + __expf(-x)); }
; DI void gla_stage3(const Ctx& c0, int layer, int unit, int cb, LAS unsigned char* lds) {
;     ...
;     for (int vb = 0; vb < 4; ++vb) { const float g = gn[32 * vb + r];
; #pragma unroll
;         for (int rg = 0; rg < 16; ++rg) { LAS bf16* e = (LAS bf16*)(R + (4 * hi) * G3_PITCH + r * 2 + ((rg & 3) + 8 * (rg >> 2)) * G3_PITCH + 64 * vb);
;             const float z = bf2f(*e);
;             *e = (bf16)(cvtpk(o[vb][rg] * rs[rg] * g * siluf_(z), 0.f) & 0xffffu); }
	v_lshlrev_b32_e32 v3, 16, v3
	v_mul_f32_e32 v48, 0xbfb8aa3b, v3
	v_exp_f32_e32 v48, v48
	s_nop 0
	v_add_f32_e32 v48, 1.0, v48
	v_div_scale_f32 v49, s[0:1], v48, v48, v3
	s_nop 0
	v_rcp_f32_e32 v49, v48
	s_nop 0
	v_mul_f32_e32 v3, v3, v49
	v_mul_f32_e32 v3, v47, v3
	v_cvt_pk_bf16_f32 v3, v3, s0
	ds_write_b16 v1, v3 offset:2448
	ds_read_u16 v3, v1 offset:2720
	v_mul_f32_e32 v47, v132, v40
	v_mul_f32_e32 v47, v47, v232
	s_waitcnt lgkmcnt(0)
	v_lshlrev_b32_e32 v3, 16, v3
	v_mul_f32_e32 v48, 0xbfb8aa3b, v3
	v_exp_f32_e32 v48, v48
	s_nop 0
	v_add_f32_e32 v48, 1.0, v48
	v_div_scale_f32 v49, s[0:1], v48, v48, v3
	s_nop 0
	v_rcp_f32_e32 v49, v48
	s_nop 0
	v_mul_f32_e32 v3, v3, v49
	v_mul_f32_e32 v3, v47, v3
	v_cvt_pk_bf16_f32 v3, v3, s0
	ds_write_b16 v1, v3 offset:2720
	ds_read_u16 v3, v1 offset:2992
	v_mul_f32_e32 v47, v131, v35
	v_mul_f32_e32 v47, v47, v232
	s_waitcnt lgkmcnt(0)
	v_lshlrev_b32_e32 v3, 16, v3
	v_mul_f32_e32 v48, 0xbfb8aa3b, v3
	v_exp_f32_e32 v48, v48
	s_nop 0
	v_add_f32_e32 v48, 1.0, v48
	v_div_scale_f32 v49, s[0:1], v48, v48, v3
	s_nop 0
	v_rcp_f32_e32 v49, v48
	s_nop 0
	v_mul_f32_e32 v3, v3, v49
	v_mul_f32_e32 v3, v47, v3
	v_cvt_pk_bf16_f32 v3, v3, s0
	ds_write_b16 v1, v3 offset:2992
	ds_read_u16 v3, v1 offset:4352
	v_mul_f32_e32 v47, v130, v31
	v_mul_f32_e32 v47, v47, v232
	s_waitcnt lgkmcnt(0)
	v_lshlrev_b32_e32 v3, 16, v3
	v_mul_f32_e32 v48, 0xbfb8aa3b, v3
	v_exp_f32_e32 v48, v48
	s_nop 0
	v_add_f32_e32 v48, 1.0, v48
	v_div_scale_f32 v49, s[0:1], v48, v48, v3
	s_nop 0
	v_rcp_f32_e32 v49, v48
	s_nop 0
	v_mul_f32_e32 v3, v3, v49
	v_mul_f32_e32 v3, v47, v3
	v_cvt_pk_bf16_f32 v3, v3, s0
	ds_write_b16 v1, v3 offset:4352
	ds_read_u16 v3, v1 offset:4624
	v_mul_f32_e32 v47, v129, v27
	v_mul_f32_e32 v47, v47, v232
	s_waitcnt lgkmcnt(0)
	v_lshlrev_b32_e32 v3, 16, v3
	v_mul_f32_e32 v48, 0xbfb8aa3b, v3
	v_exp_f32_e32 v48, v48
	s_nop 0
	v_add_f32_e32 v48, 1.0, v48
	v_div_scale_f32 v49, s[0:1], v48, v48, v3
	s_nop 0
	v_rcp_f32_e32 v49, v48
	s_nop 0
	v_mul_f32_e32 v3, v3, v49
	v_mul_f32_e32 v3, v47, v3
	v_cvt_pk_bf16_f32 v3, v3, s0
	ds_write_b16 v1, v3 offset:4624
	ds_read_u16 v3, v1 offset:4896
	v_mul_f32_e32 v47, v128, v25
	v_mul_f32_e32 v47, v47, v232
	s_waitcnt lgkmcnt(0)
	v_lshlrev_b32_e32 v3, 16, v3
	v_mul_f32_e32 v48, 0xbfb8aa3b, v3
	v_exp_f32_e32 v48, v48
	s_nop 0
	v_add_f32_e32 v48, 1.0, v48
	v_div_scale_f32 v49, s[0:1], v48, v48, v3
	s_nop 0
	v_rcp_f32_e32 v49, v48
	s_nop 0
	v_mul_f32_e32 v3, v3, v49
	v_mul_f32_e32 v3, v47, v3
	v_cvt_pk_bf16_f32 v3, v3, s0
	ds_write_b16 v1, v3 offset:4896
	ds_read_u16 v3, v1 offset:5168
	v_mul_f32_e32 v47, v127, v24
	v_mul_f32_e32 v47, v47, v232
	s_waitcnt lgkmcnt(0)
	v_lshlrev_b32_e32 v3, 16, v3
	v_mul_f32_e32 v48, 0xbfb8aa3b, v3
	v_exp_f32_e32 v48, v48
	s_nop 0
	v_add_f32_e32 v48, 1.0, v48
	v_div_scale_f32 v49, s[0:1], v48, v48, v3
	s_nop 0
	v_rcp_f32_e32 v49, v48
	s_nop 0
	v_mul_f32_e32 v3, v3, v49
	v_mul_f32_e32 v3, v47, v3
	v_cvt_pk_bf16_f32 v3, v3, s0
	ds_write_b16 v1, v3 offset:5168
	ds_read_u16 v3, v1 offset:6528
	v_mul_f32_e32 v47, v126, v23
	v_mul_f32_e32 v47, v47, v232
	s_waitcnt lgkmcnt(0)
	v_lshlrev_b32_e32 v3, 16, v3
	v_mul_f32_e32 v48, 0xbfb8aa3b, v3
	v_exp_f32_e32 v48, v48
	s_nop 0
	v_add_f32_e32 v48, 1.0, v48
	v_div_scale_f32 v49, s[0:1], v48, v48, v3
	s_nop 0
	v_rcp_f32_e32 v49, v48
	s_nop 0
	v_mul_f32_e32 v3, v3, v49
	v_mul_f32_e32 v3, v47, v3
	v_cvt_pk_bf16_f32 v3, v3, s0
	ds_write_b16 v1, v3 offset:6528
	ds_read_u16 v3, v1 offset:6800
	v_mul_f32_e32 v47, v125, v22
	v_mul_f32_e32 v47, v47, v232
	s_waitcnt lgkmcnt(0)
	v_lshlrev_b32_e32 v3, 16, v3
	v_mul_f32_e32 v48, 0xbfb8aa3b, v3
	v_exp_f32_e32 v48, v48
	s_nop 0
	v_add_f32_e32 v48, 1.0, v48
	v_div_scale_f32 v49, s[0:1], v48, v48, v3
	s_nop 0
	v_rcp_f32_e32 v49, v48
	s_nop 0
	v_mul_f32_e32 v3, v3, v49
	v_mul_f32_e32 v3, v47, v3
	v_cvt_pk_bf16_f32 v3, v3, s0
	ds_write_b16 v1, v3 offset:6800
	ds_read_u16 v3, v1 offset:7072
	v_mul_f32_e32 v47, v124, v21
	v_mul_f32_e32 v47, v47, v232
	s_waitcnt lgkmcnt(0)
	v_lshlrev_b32_e32 v3, 16, v3
	v_mul_f32_e32 v48, 0xbfb8aa3b, v3
	v_exp_f32_e32 v48, v48
	s_nop 0
	v_add_f32_e32 v48, 1.0, v48
	v_div_scale_f32 v49, s[0:1], v48, v48, v3
	s_nop 0
	v_rcp_f32_e32 v49, v48
	s_nop 0
	v_mul_f32_e32 v3, v3, v49
	v_mul_f32_e32 v3, v47, v3
	v_cvt_pk_bf16_f32 v3, v3, s0
	ds_write_b16 v1, v3 offset:7072
	ds_read_u16 v3, v1 offset:7344
	v_mul_f32_e32 v47, v123, v20
	v_mul_f32_e32 v2, v47, v232
	s_waitcnt lgkmcnt(0)
	v_lshlrev_b32_e32 v3, 16, v3
	v_mul_f32_e32 v47, 0xbfb8aa3b, v3
	v_exp_f32_e32 v47, v47
	s_nop 0
	v_add_f32_e32 v47, 1.0, v47
	v_div_scale_f32 v48, s[0:1], v47, v47, v3
	s_nop 0
	v_rcp_f32_e32 v48, v47
	s_nop 0
	v_mul_f32_e32 v3, v3, v48
	v_mul_f32_e32 v2, v2, v3
	v_cvt_pk_bf16_f32 v2, v2, s0
	ds_write_b16 v1, v2 offset:7344
	ds_read_u16 v3, v1 offset:64
	v_mul_f32_e32 v47, v122, v46
	s_waitcnt lgkmcnt(0)
	v_lshlrev_b32_e32 v3, 16, v3
	v_mul_f32_e32 v48, 0xbfb8aa3b, v3
	v_exp_f32_e32 v48, v48
	s_waitcnt vmcnt(0)
	v_mul_f32_e32 v47, v47, v234
	v_add_f32_e32 v48, 1.0, v48
	v_div_scale_f32 v49, s[0:1], v48, v48, v3
	s_nop 0
	v_rcp_f32_e32 v49, v48
	s_nop 0
	v_mul_f32_e32 v3, v3, v49
	v_mul_f32_e32 v3, v47, v3
	v_cvt_pk_bf16_f32 v3, v3, s0
	ds_write_b16 v1, v3 offset:64
	ds_read_u16 v3, v1 offset:336
	v_mul_f32_e32 v47, v121, v45
	v_mul_f32_e32 v47, v47, v234
	s_waitcnt lgkmcnt(0)
	v_lshlrev_b32_e32 v3, 16, v3
	v_mul_f32_e32 v48, 0xbfb8aa3b, v3
	v_exp_f32_e32 v48, v48
	s_nop 0
	v_add_f32_e32 v48, 1.0, v48
	v_div_scale_f32 v49, s[0:1], v48, v48, v3
	s_nop 0
	v_rcp_f32_e32 v49, v48
	s_nop 0
	v_mul_f32_e32 v3, v3, v49
	v_mul_f32_e32 v3, v47, v3
	v_cvt_pk_bf16_f32 v3, v3, s0
	ds_write_b16 v1, v3 offset:336
	ds_read_u16 v3, v1 offset:608
	v_mul_f32_e32 v47, v120, v44
	v_mul_f32_e32 v47, v47, v234
	s_waitcnt lgkmcnt(0)
; #define LAS __attribute__((address_space(3)))
; DI unsigned cvtpk(float lo, float hi) { f32x2 v = {lo, hi}; bf16x2_t b = __builtin_convertvector(v, bf16x2_t); return __builtin_bit_cast(unsigned, b); }
; DI float bf2f(bf16 b) { return __uint_as_float(((unsigned)b) << 16); }
; DI float siluf_(float x) { return x / (1.f + __expf(-x)); }
; DI void gla_stage3(const Ctx& c0, int layer, int unit, int cb, LAS unsigned char* lds) {
;     ...
;     for (int vb = 0; vb < 4; ++vb) { const float g = gn[32 * vb + r];
; #pragma unroll
;         for (int rg = 0; rg < 16; ++rg) { LAS bf16* e = (LAS bf16*)(R + (4 * hi) * G3_PITCH + r * 2 + ((rg & 3) + 8 * (rg >> 2)) * G3_PITCH + 64 * vb);
;             const float z = bf2f(*e);
;             *e = (bf16)(cvtpk(o[vb][rg] * rs[rg] * g * siluf_(z), 0.f) & 0xffffu); }
	v_lshlrev_b32_e32 v3, 16, v3
	v_mul_f32_e32 v48, 0xbfb8aa3b, v3
	v_exp_f32_e32 v48, v48
	s_nop 0
	v_add_f32_e32 v48, 1.0, v48
	v_div_scale_f32 v49, s[0:1], v48, v48, v3
	s_nop 0
	v_rcp_f32_e32 v49, v48
	s_nop 0
	v_mul_f32_e32 v3, v3, v49
	v_mul_f32_e32 v3, v47, v3
	v_cvt_pk_bf16_f32 v3, v3, s0
	ds_write_b16 v1, v3 offset:608
	ds_read_u16 v3, v1 offset:880
	v_mul_f32_e32 v47, v119, v43
	v_mul_f32_e32 v47, v47, v234
	s_waitcnt lgkmcnt(0)
	v_lshlrev_b32_e32 v3, 16, v3
	v_mul_f32_e32 v48, 0xbfb8aa3b, v3
	v_exp_f32_e32 v48, v48
	s_nop 0
	v_add_f32_e32 v48, 1.0, v48
	v_div_scale_f32 v49, s[0:1], v48, v48, v3
	s_nop 0
	v_rcp_f32_e32 v49, v48
	s_nop 0
	v_mul_f32_e32 v3, v3, v49
	v_mul_f32_e32 v3, v47, v3
	v_cvt_pk_bf16_f32 v3, v3, s0
	ds_write_b16 v1, v3 offset:880
	ds_read_u16 v3, v1 offset:2240
	v_mul_f32_e32 v47, v118, v42
	v_mul_f32_e32 v47, v47, v234
	s_waitcnt lgkmcnt(0)
	v_lshlrev_b32_e32 v3, 16, v3
	v_mul_f32_e32 v48, 0xbfb8aa3b, v3
	v_exp_f32_e32 v48, v48
	s_nop 0
	v_add_f32_e32 v48, 1.0, v48
	v_div_scale_f32 v49, s[0:1], v48, v48, v3
	s_nop 0
	v_rcp_f32_e32 v49, v48
	s_nop 0
	v_mul_f32_e32 v3, v3, v49
	v_mul_f32_e32 v3, v47, v3
	v_cvt_pk_bf16_f32 v3, v3, s0
	ds_write_b16 v1, v3 offset:2240
	ds_read_u16 v3, v1 offset:2512
	v_mul_f32_e32 v47, v117, v41
	v_mul_f32_e32 v47, v47, v234
	s_waitcnt lgkmcnt(0)
	v_lshlrev_b32_e32 v3, 16, v3
	v_mul_f32_e32 v48, 0xbfb8aa3b, v3
	v_exp_f32_e32 v48, v48
	s_nop 0
	v_add_f32_e32 v48, 1.0, v48
	v_div_scale_f32 v49, s[0:1], v48, v48, v3
	s_nop 0
	v_rcp_f32_e32 v49, v48
	s_nop 0
	v_mul_f32_e32 v3, v3, v49
	v_mul_f32_e32 v3, v47, v3
	v_cvt_pk_bf16_f32 v3, v3, s0
	ds_write_b16 v1, v3 offset:2512
	ds_read_u16 v3, v1 offset:2784
	v_mul_f32_e32 v47, v116, v40
	v_mul_f32_e32 v47, v47, v234
	s_waitcnt lgkmcnt(0)
	v_lshlrev_b32_e32 v3, 16, v3
	v_mul_f32_e32 v48, 0xbfb8aa3b, v3
	v_exp_f32_e32 v48, v48
	s_nop 0
	v_add_f32_e32 v48, 1.0, v48
	v_div_scale_f32 v49, s[0:1], v48, v48, v3
	s_nop 0
	v_rcp_f32_e32 v49, v48
	s_nop 0
	v_mul_f32_e32 v3, v3, v49
	v_mul_f32_e32 v3, v47, v3
	v_cvt_pk_bf16_f32 v3, v3, s0
	ds_write_b16 v1, v3 offset:2784
	ds_read_u16 v3, v1 offset:3056
	v_mul_f32_e32 v47, v115, v35
	v_mul_f32_e32 v47, v47, v234
	s_waitcnt lgkmcnt(0)
	v_lshlrev_b32_e32 v3, 16, v3
	v_mul_f32_e32 v48, 0xbfb8aa3b, v3
	v_exp_f32_e32 v48, v48
	s_nop 0
	v_add_f32_e32 v48, 1.0, v48
	v_div_scale_f32 v49, s[0:1], v48, v48, v3
	s_nop 0
	v_rcp_f32_e32 v49, v48
	s_nop 0
	v_mul_f32_e32 v3, v3, v49
	v_mul_f32_e32 v3, v47, v3
	v_cvt_pk_bf16_f32 v3, v3, s0
	ds_write_b16 v1, v3 offset:3056
	ds_read_u16 v3, v1 offset:4416
	v_mul_f32_e32 v47, v114, v31
	v_mul_f32_e32 v47, v47, v234
	s_waitcnt lgkmcnt(0)
	v_lshlrev_b32_e32 v3, 16, v3
	v_mul_f32_e32 v48, 0xbfb8aa3b, v3
	v_exp_f32_e32 v48, v48
	s_nop 0
	v_add_f32_e32 v48, 1.0, v48
	v_div_scale_f32 v49, s[0:1], v48, v48, v3
	s_nop 0
	v_rcp_f32_e32 v49, v48
	s_nop 0
	v_mul_f32_e32 v3, v3, v49
	v_mul_f32_e32 v3, v47, v3
	v_cvt_pk_bf16_f32 v3, v3, s0
	ds_write_b16 v1, v3 offset:4416
	ds_read_u16 v3, v1 offset:4688
	v_mul_f32_e32 v47, v113, v27
	v_mul_f32_e32 v47, v47, v234
	s_waitcnt lgkmcnt(0)
	v_lshlrev_b32_e32 v3, 16, v3
	v_mul_f32_e32 v48, 0xbfb8aa3b, v3
	v_exp_f32_e32 v48, v48
	s_nop 0
	v_add_f32_e32 v48, 1.0, v48
	v_div_scale_f32 v49, s[0:1], v48, v48, v3
	s_nop 0
	v_rcp_f32_e32 v49, v48
	s_nop 0
	v_mul_f32_e32 v3, v3, v49
	v_mul_f32_e32 v3, v47, v3
	v_cvt_pk_bf16_f32 v3, v3, s0
	ds_write_b16 v1, v3 offset:4688
	ds_read_u16 v3, v1 offset:4960
	v_mul_f32_e32 v47, v112, v25
	v_mul_f32_e32 v47, v47, v234
	s_waitcnt lgkmcnt(0)
	v_lshlrev_b32_e32 v3, 16, v3
	v_mul_f32_e32 v48, 0xbfb8aa3b, v3
	v_exp_f32_e32 v48, v48
	s_nop 0
	v_add_f32_e32 v48, 1.0, v48
	v_div_scale_f32 v49, s[0:1], v48, v48, v3
	s_nop 0
	v_rcp_f32_e32 v49, v48
	s_nop 0
	v_mul_f32_e32 v3, v3, v49
	v_mul_f32_e32 v3, v47, v3
	v_cvt_pk_bf16_f32 v3, v3, s0
	ds_write_b16 v1, v3 offset:4960
	ds_read_u16 v3, v1 offset:5232
	v_mul_f32_e32 v47, v111, v24
	v_mul_f32_e32 v47, v47, v234
	s_waitcnt lgkmcnt(0)
	v_lshlrev_b32_e32 v3, 16, v3
	v_mul_f32_e32 v48, 0xbfb8aa3b, v3
	v_exp_f32_e32 v48, v48
	s_nop 0
	v_add_f32_e32 v48, 1.0, v48
	v_div_scale_f32 v49, s[0:1], v48, v48, v3
	s_nop 0
	v_rcp_f32_e32 v49, v48
	s_nop 0
	v_mul_f32_e32 v3, v3, v49
	v_mul_f32_e32 v3, v47, v3
	v_cvt_pk_bf16_f32 v3, v3, s0
	ds_write_b16 v1, v3 offset:5232
	ds_read_u16 v3, v1 offset:6592
	v_mul_f32_e32 v47, v110, v23
	v_mul_f32_e32 v47, v47, v234
	s_waitcnt lgkmcnt(0)
	v_lshlrev_b32_e32 v3, 16, v3
	v_mul_f32_e32 v48, 0xbfb8aa3b, v3
	v_exp_f32_e32 v48, v48
	s_nop 0
	v_add_f32_e32 v48, 1.0, v48
	v_div_scale_f32 v49, s[0:1], v48, v48, v3
	s_nop 0
	v_rcp_f32_e32 v49, v48
	s_nop 0
	v_mul_f32_e32 v3, v3, v49
	v_mul_f32_e32 v3, v47, v3
	v_cvt_pk_bf16_f32 v3, v3, s0
	ds_write_b16 v1, v3 offset:6592
	ds_read_u16 v3, v1 offset:6864
	v_mul_f32_e32 v47, v109, v22
	v_mul_f32_e32 v47, v47, v234
	s_waitcnt lgkmcnt(0)
	v_lshlrev_b32_e32 v3, 16, v3
	v_mul_f32_e32 v48, 0xbfb8aa3b, v3
	v_exp_f32_e32 v48, v48
	s_nop 0
	v_add_f32_e32 v48, 1.0, v48
	v_div_scale_f32 v49, s[0:1], v48, v48, v3
	s_nop 0
	v_rcp_f32_e32 v49, v48
	s_nop 0
	v_mul_f32_e32 v3, v3, v49
	v_mul_f32_e32 v3, v47, v3
	v_cvt_pk_bf16_f32 v3, v3, s0
	ds_write_b16 v1, v3 offset:6864
	ds_read_u16 v3, v1 offset:7136
	v_mul_f32_e32 v47, v108, v21
	v_mul_f32_e32 v47, v47, v234
	s_waitcnt lgkmcnt(0)
	v_lshlrev_b32_e32 v3, 16, v3
	v_mul_f32_e32 v48, 0xbfb8aa3b, v3
	v_exp_f32_e32 v48, v48
	s_nop 0
	v_add_f32_e32 v48, 1.0, v48
	v_div_scale_f32 v49, s[0:1], v48, v48, v3
	s_nop 0
	v_rcp_f32_e32 v49, v48
	s_nop 0
	v_mul_f32_e32 v3, v3, v49
	v_mul_f32_e32 v3, v47, v3
	v_cvt_pk_bf16_f32 v3, v3, s0
	ds_write_b16 v1, v3 offset:7136
	ds_read_u16 v3, v1 offset:7408
	v_mul_f32_e32 v47, v107, v20
	v_mul_f32_e32 v2, v47, v234
	s_waitcnt lgkmcnt(0)
; #define LAS __attribute__((address_space(3)))
; DI unsigned cvtpk(float lo, float hi) { f32x2 v = {lo, hi}; bf16x2_t b = __builtin_convertvector(v, bf16x2_t); return __builtin_bit_cast(unsigned, b); }
; DI float bf2f(bf16 b) { return __uint_as_float(((unsigned)b) << 16); }
; DI float siluf_(float x) { return x / (1.f + __expf(-x)); }
; DI void gla_stage3(const Ctx& c0, int layer, int unit, int cb, LAS unsigned char* lds) {
;     ...
;     for (int vb = 0; vb < 4; ++vb) { const float g = gn[32 * vb + r];
; #pragma unroll
;         for (int rg = 0; rg < 16; ++rg) { LAS bf16* e = (LAS bf16*)(R + (4 * hi) * G3_PITCH + r * 2 + ((rg & 3) + 8 * (rg >> 2)) * G3_PITCH + 64 * vb);
;             const float z = bf2f(*e);
;             *e = (bf16)(cvtpk(o[vb][rg] * rs[rg] * g * siluf_(z), 0.f) & 0xffffu); }
	v_lshlrev_b32_e32 v3, 16, v3
	v_mul_f32_e32 v47, 0xbfb8aa3b, v3
	v_exp_f32_e32 v47, v47
	s_nop 0
	v_add_f32_e32 v47, 1.0, v47
	v_div_scale_f32 v48, s[0:1], v47, v47, v3
	s_nop 0
	v_rcp_f32_e32 v48, v47
	s_nop 0
	v_mul_f32_e32 v3, v3, v48
	v_mul_f32_e32 v2, v2, v3
	v_cvt_pk_bf16_f32 v2, v2, s0
	ds_write_b16 v1, v2 offset:7408
	ds_read_u16 v3, v1 offset:128
	v_mul_f32_e32 v47, v106, v46
	s_waitcnt lgkmcnt(0)
	v_lshlrev_b32_e32 v3, 16, v3
	v_mul_f32_e32 v48, 0xbfb8aa3b, v3
	v_exp_f32_e32 v48, v48
	s_waitcnt vmcnt(0)
	v_mul_f32_e32 v47, v47, v236
	v_add_f32_e32 v48, 1.0, v48
	v_div_scale_f32 v49, s[0:1], v48, v48, v3
	v_mul_f32_e32 v39, v39, v236
	v_mul_f32_e32 v38, v38, v236
	v_mul_f32_e32 v37, v37, v236
	v_rcp_f32_e32 v49, v48
	s_nop 0
	v_mul_f32_e32 v3, v3, v49
	v_mul_f32_e32 v3, v47, v3
	v_cvt_pk_bf16_f32 v3, v3, s0
	ds_write_b16 v1, v3 offset:128
	ds_read_u16 v3, v1 offset:400
	v_mul_f32_e32 v47, v105, v45
	v_mul_f32_e32 v47, v47, v236
	v_mul_f32_e32 v36, v36, v236
	v_mul_f32_e32 v34, v34, v236
	s_waitcnt lgkmcnt(0)
	v_lshlrev_b32_e32 v3, 16, v3
	v_mul_f32_e32 v48, 0xbfb8aa3b, v3
	v_exp_f32_e32 v48, v48
	v_mul_f32_e32 v33, v33, v236
	v_mul_f32_e32 v32, v32, v236
	v_mul_f32_e32 v30, v30, v236
	v_add_f32_e32 v48, 1.0, v48
	v_div_scale_f32 v49, s[0:1], v48, v48, v3
	v_mul_f32_e32 v29, v29, v236
	v_mul_f32_e32 v28, v28, v236
	v_rcp_f32_e32 v49, v48
	s_nop 0
	v_mul_f32_e32 v3, v3, v49
	v_mul_f32_e32 v3, v47, v3
	v_cvt_pk_bf16_f32 v3, v3, s0
	ds_write_b16 v1, v3 offset:400
	ds_read_u16 v3, v1 offset:672
	v_mul_f32_e32 v47, v104, v44
	v_mul_f32_e32 v47, v47, v236
	s_waitcnt lgkmcnt(0)
	v_lshlrev_b32_e32 v3, 16, v3
	v_mul_f32_e32 v48, 0xbfb8aa3b, v3
	v_exp_f32_e32 v48, v48
	s_nop 0
	v_add_f32_e32 v48, 1.0, v48
	v_div_scale_f32 v49, s[0:1], v48, v48, v3
	s_nop 0
	v_rcp_f32_e32 v49, v48
	s_nop 0
	v_mul_f32_e32 v3, v3, v49
	v_mul_f32_e32 v3, v47, v3
	v_cvt_pk_bf16_f32 v3, v3, s0
	ds_write_b16 v1, v3 offset:672
	ds_read_u16 v3, v1 offset:944
	v_mul_f32_e32 v47, v103, v43
	v_mul_f32_e32 v47, v47, v236
	s_waitcnt lgkmcnt(0)
	v_lshlrev_b32_e32 v3, 16, v3
	v_mul_f32_e32 v48, 0xbfb8aa3b, v3
	v_exp_f32_e32 v48, v48
	s_nop 0
	v_add_f32_e32 v48, 1.0, v48
	v_div_scale_f32 v49, s[0:1], v48, v48, v3
	s_nop 0
	v_rcp_f32_e32 v49, v48
	s_nop 0
	v_mul_f32_e32 v3, v3, v49
	v_mul_f32_e32 v3, v47, v3
	v_cvt_pk_bf16_f32 v3, v3, s0
	ds_write_b16 v1, v3 offset:944
	ds_read_u16 v3, v1 offset:2304
	v_mul_f32_e32 v47, v102, v42
	v_mul_f32_e32 v47, v47, v236
	v_mul_f32_e32 v2, v26, v236
	s_waitcnt lgkmcnt(0)
	v_lshlrev_b32_e32 v3, 16, v3
	v_mul_f32_e32 v48, 0xbfb8aa3b, v3
	v_exp_f32_e32 v48, v48
	s_nop 0
	v_add_f32_e32 v48, 1.0, v48
	v_div_scale_f32 v49, s[0:1], v48, v48, v3
	s_nop 0
	v_rcp_f32_e32 v49, v48
	s_nop 0
	v_mul_f32_e32 v3, v3, v49
	v_mul_f32_e32 v3, v47, v3
	v_cvt_pk_bf16_f32 v3, v3, s0
	ds_write_b16 v1, v3 offset:2304
	ds_read_u16 v3, v1 offset:2576
	s_waitcnt lgkmcnt(0)
	v_lshlrev_b32_e32 v3, 16, v3
	v_mul_f32_e32 v47, 0xbfb8aa3b, v3
	v_exp_f32_e32 v47, v47
	s_nop 0
	v_add_f32_e32 v47, 1.0, v47
	v_div_scale_f32 v48, s[0:1], v47, v47, v3
	s_nop 0
	v_rcp_f32_e32 v48, v47
	s_nop 0
	v_mul_f32_e32 v3, v3, v48
	v_mul_f32_e32 v3, v39, v3
	v_cvt_pk_bf16_f32 v3, v3, s0
	ds_write_b16 v1, v3 offset:2576
	ds_read_u16 v3, v1 offset:2848
	s_waitcnt lgkmcnt(0)
	v_lshlrev_b32_e32 v3, 16, v3
	v_mul_f32_e32 v39, 0xbfb8aa3b, v3
	v_exp_f32_e32 v39, v39
	s_nop 0
	v_add_f32_e32 v39, 1.0, v39
	v_div_scale_f32 v47, s[0:1], v39, v39, v3
	s_nop 0
	v_rcp_f32_e32 v47, v39
	s_nop 0
	v_mul_f32_e32 v3, v3, v47
	v_mul_f32_e32 v3, v38, v3
	v_cvt_pk_bf16_f32 v3, v3, s0
	ds_write_b16 v1, v3 offset:2848
	ds_read_u16 v3, v1 offset:3120
	s_waitcnt lgkmcnt(0)
	v_lshlrev_b32_e32 v3, 16, v3
	v_mul_f32_e32 v38, 0xbfb8aa3b, v3
	v_exp_f32_e32 v38, v38
	s_nop 0
	v_add_f32_e32 v38, 1.0, v38
	v_div_scale_f32 v39, s[0:1], v38, v38, v3
	s_nop 0
	v_rcp_f32_e32 v39, v38
	s_nop 0
	v_mul_f32_e32 v3, v3, v39
	v_mul_f32_e32 v3, v37, v3
	v_cvt_pk_bf16_f32 v3, v3, s0
	ds_write_b16 v1, v3 offset:3120
	ds_read_u16 v3, v1 offset:4480
	s_waitcnt lgkmcnt(0)
	v_lshlrev_b32_e32 v3, 16, v3
	v_mul_f32_e32 v37, 0xbfb8aa3b, v3
	v_exp_f32_e32 v37, v37
	s_nop 0
	v_add_f32_e32 v37, 1.0, v37
	v_div_scale_f32 v38, s[0:1], v37, v37, v3
	s_nop 0
	v_rcp_f32_e32 v38, v37
	s_nop 0
	v_mul_f32_e32 v3, v3, v38
	v_mul_f32_e32 v3, v36, v3
	v_cvt_pk_bf16_f32 v3, v3, s0
	ds_write_b16 v1, v3 offset:4480
	ds_read_u16 v3, v1 offset:4752
	s_waitcnt lgkmcnt(0)
	v_lshlrev_b32_e32 v3, 16, v3
	v_mul_f32_e32 v36, 0xbfb8aa3b, v3
	v_exp_f32_e32 v36, v36
	s_nop 0
	v_add_f32_e32 v36, 1.0, v36
	v_div_scale_f32 v37, s[0:1], v36, v36, v3
	s_nop 0
	v_rcp_f32_e32 v37, v36
	s_nop 0
	v_mul_f32_e32 v3, v3, v37
	v_mul_f32_e32 v3, v34, v3
	v_cvt_pk_bf16_f32 v3, v3, s0
	ds_write_b16 v1, v3 offset:4752
	ds_read_u16 v3, v1 offset:5024
	s_waitcnt lgkmcnt(0)
	v_lshlrev_b32_e32 v3, 16, v3
	v_mul_f32_e32 v34, 0xbfb8aa3b, v3
	v_exp_f32_e32 v34, v34
	s_nop 0
	v_add_f32_e32 v34, 1.0, v34
	v_div_scale_f32 v36, s[0:1], v34, v34, v3
	s_nop 0
	v_rcp_f32_e32 v36, v34
	s_nop 0
	v_mul_f32_e32 v3, v3, v36
	v_mul_f32_e32 v3, v33, v3
	v_cvt_pk_bf16_f32 v3, v3, s0
	ds_write_b16 v1, v3 offset:5024
	ds_read_u16 v3, v1 offset:5296
	s_waitcnt lgkmcnt(0)
	v_lshlrev_b32_e32 v3, 16, v3
	v_mul_f32_e32 v33, 0xbfb8aa3b, v3
	v_exp_f32_e32 v33, v33
	s_nop 0
	v_add_f32_e32 v33, 1.0, v33
	v_div_scale_f32 v34, s[0:1], v33, v33, v3
	s_nop 0
	v_rcp_f32_e32 v34, v33
	s_nop 0
	v_mul_f32_e32 v3, v3, v34
	v_mul_f32_e32 v3, v32, v3
	v_cvt_pk_bf16_f32 v3, v3, s0
	ds_write_b16 v1, v3 offset:5296
	ds_read_u16 v3, v1 offset:6656
	s_waitcnt lgkmcnt(0)
; #define LAS __attribute__((address_space(3)))
; DI unsigned cvtpk(float lo, float hi) { f32x2 v = {lo, hi}; bf16x2_t b = __builtin_convertvector(v, bf16x2_t); return __builtin_bit_cast(unsigned, b); }
; DI float bf2f(bf16 b) { return __uint_as_float(((unsigned)b) << 16); }
; DI float siluf_(float x) { return x / (1.f + __expf(-x)); }
; DI void gla_stage3(const Ctx& c0, int layer, int unit, int cb, LAS unsigned char* lds) {
;     ...
;     for (int vb = 0; vb < 4; ++vb) { const float g = gn[32 * vb + r];
; #pragma unroll
;         for (int rg = 0; rg < 16; ++rg) { LAS bf16* e = (LAS bf16*)(R + (4 * hi) * G3_PITCH + r * 2 + ((rg & 3) + 8 * (rg >> 2)) * G3_PITCH + 64 * vb);
;             const float z = bf2f(*e);
;             *e = (bf16)(cvtpk(o[vb][rg] * rs[rg] * g * siluf_(z), 0.f) & 0xffffu); }
	v_lshlrev_b32_e32 v3, 16, v3
	v_mul_f32_e32 v32, 0xbfb8aa3b, v3
	v_exp_f32_e32 v32, v32
	s_nop 0
	v_add_f32_e32 v32, 1.0, v32
	v_div_scale_f32 v33, s[0:1], v32, v32, v3
	s_nop 0
	v_rcp_f32_e32 v33, v32
	s_nop 0
	v_mul_f32_e32 v3, v3, v33
	v_mul_f32_e32 v3, v30, v3
	v_cvt_pk_bf16_f32 v3, v3, s0
	ds_write_b16 v1, v3 offset:6656
	ds_read_u16 v3, v1 offset:6928
	s_waitcnt lgkmcnt(0)
	v_lshlrev_b32_e32 v3, 16, v3
	v_mul_f32_e32 v30, 0xbfb8aa3b, v3
	v_exp_f32_e32 v30, v30
	s_nop 0
	v_add_f32_e32 v30, 1.0, v30
	v_div_scale_f32 v32, s[0:1], v30, v30, v3
	s_nop 0
	v_rcp_f32_e32 v32, v30
	s_nop 0
	v_mul_f32_e32 v3, v3, v32
	v_mul_f32_e32 v3, v29, v3
	v_cvt_pk_bf16_f32 v3, v3, s0
	ds_write_b16 v1, v3 offset:6928
	ds_read_u16 v3, v1 offset:7200
	s_waitcnt lgkmcnt(0)
	v_lshlrev_b32_e32 v3, 16, v3
	v_mul_f32_e32 v29, 0xbfb8aa3b, v3
	v_exp_f32_e32 v29, v29
	s_nop 0
	v_add_f32_e32 v29, 1.0, v29
	v_div_scale_f32 v30, s[0:1], v29, v29, v3
	s_nop 0
	v_rcp_f32_e32 v30, v29
	s_nop 0
	v_mul_f32_e32 v3, v3, v30
	v_mul_f32_e32 v3, v28, v3
	v_cvt_pk_bf16_f32 v3, v3, s0
	ds_write_b16 v1, v3 offset:7200
	ds_read_u16 v3, v1 offset:7472
	s_waitcnt lgkmcnt(0)
	v_lshlrev_b32_e32 v3, 16, v3
	v_mul_f32_e32 v26, 0xbfb8aa3b, v3
	v_exp_f32_e32 v26, v26
	s_nop 0
	v_add_f32_e32 v26, 1.0, v26
	v_div_scale_f32 v28, s[0:1], v26, v26, v3
	s_nop 0
	v_rcp_f32_e32 v28, v26
	s_nop 0
	v_mul_f32_e32 v3, v3, v28
	v_mul_f32_e32 v2, v2, v3
	v_cvt_pk_bf16_f32 v2, v2, s0
	ds_write_b16 v1, v2 offset:7472
	ds_read_u16 v3, v1 offset:192
	s_waitcnt lgkmcnt(0)
	v_lshlrev_b32_e32 v3, 16, v3
	v_mul_f32_e32 v26, 0xbfb8aa3b, v3
	v_exp_f32_e32 v26, v26
	s_waitcnt vmcnt(31)
	v_mul_f32_e32 v19, v19, v238
	v_add_f32_e32 v26, 1.0, v26
	v_div_scale_f32 v28, s[0:1], v26, v26, v3
	v_mul_f32_e32 v18, v18, v238
	v_mul_f32_e32 v17, v17, v238
	v_mul_f32_e32 v16, v16, v238
	v_rcp_f32_e32 v28, v26
	s_nop 0
	v_mul_f32_e32 v3, v3, v28
	v_mul_f32_e32 v3, v19, v3
	v_cvt_pk_bf16_f32 v3, v3, s0
	ds_write_b16 v1, v3 offset:192
	ds_read_u16 v3, v1 offset:464
	v_mul_f32_e32 v15, v15, v238
	v_mul_f32_e32 v14, v14, v238
	v_mul_f32_e32 v13, v13, v238
	v_mul_f32_e32 v12, v12, v238
	s_waitcnt lgkmcnt(0)
	v_lshlrev_b32_e32 v3, 16, v3
	v_mul_f32_e32 v19, 0xbfb8aa3b, v3
	v_exp_f32_e32 v19, v19
	v_mul_f32_e32 v11, v11, v238
	v_mul_f32_e32 v10, v10, v238
	v_mul_f32_e32 v9, v9, v238
	v_add_f32_e32 v19, 1.0, v19
	v_div_scale_f32 v26, s[0:1], v19, v19, v3
	v_mul_f32_e32 v8, v8, v238
	v_mul_f32_e32 v7, v7, v238
	v_mul_f32_e32 v6, v6, v238
	v_rcp_f32_e32 v26, v19
	s_nop 0
	v_mul_f32_e32 v3, v3, v26
	v_mul_f32_e32 v3, v18, v3
	v_cvt_pk_bf16_f32 v3, v3, s0
	ds_write_b16 v1, v3 offset:464
	ds_read_u16 v3, v1 offset:736
	v_mul_f32_e32 v5, v5, v238
	v_mul_f32_e32 v2, v4, v238
	s_waitcnt lgkmcnt(0)
	v_lshlrev_b32_e32 v3, 16, v3
	v_mul_f32_e32 v18, 0xbfb8aa3b, v3
	v_exp_f32_e32 v18, v18
	s_nop 0
	v_add_f32_e32 v18, 1.0, v18
	v_div_scale_f32 v19, s[0:1], v18, v18, v3
	s_nop 0
	v_rcp_f32_e32 v19, v18
	s_nop 0
	v_mul_f32_e32 v3, v3, v19
	v_mul_f32_e32 v3, v17, v3
	v_cvt_pk_bf16_f32 v3, v3, s0
	ds_write_b16 v1, v3 offset:736
	ds_read_u16 v3, v1 offset:1008
	s_waitcnt lgkmcnt(0)
	v_lshlrev_b32_e32 v3, 16, v3
	v_mul_f32_e32 v17, 0xbfb8aa3b, v3
	v_exp_f32_e32 v17, v17
	s_nop 0
	v_add_f32_e32 v17, 1.0, v17
	v_div_scale_f32 v18, s[0:1], v17, v17, v3
	s_nop 0
	v_rcp_f32_e32 v18, v17
	s_nop 0
	v_mul_f32_e32 v3, v3, v18
	v_mul_f32_e32 v3, v16, v3
	v_cvt_pk_bf16_f32 v3, v3, s0
	ds_write_b16 v1, v3 offset:1008
	ds_read_u16 v3, v1 offset:2368
	s_waitcnt lgkmcnt(0)
	v_lshlrev_b32_e32 v3, 16, v3
	v_mul_f32_e32 v16, 0xbfb8aa3b, v3
	v_exp_f32_e32 v16, v16
	s_nop 0
	v_add_f32_e32 v16, 1.0, v16
	v_div_scale_f32 v17, s[0:1], v16, v16, v3
	s_nop 0
	v_rcp_f32_e32 v17, v16
	s_nop 0
	v_mul_f32_e32 v3, v3, v17
	v_mul_f32_e32 v3, v15, v3
	v_cvt_pk_bf16_f32 v3, v3, s0
	ds_write_b16 v1, v3 offset:2368
	ds_read_u16 v3, v1 offset:2640
	s_waitcnt lgkmcnt(0)
	v_lshlrev_b32_e32 v3, 16, v3
	v_mul_f32_e32 v15, 0xbfb8aa3b, v3
	v_exp_f32_e32 v15, v15
	s_nop 0
	v_add_f32_e32 v15, 1.0, v15
	v_div_scale_f32 v16, s[0:1], v15, v15, v3
	s_nop 0
	v_rcp_f32_e32 v16, v15
	s_nop 0
	v_mul_f32_e32 v3, v3, v16
	v_mul_f32_e32 v3, v14, v3
	v_cvt_pk_bf16_f32 v3, v3, s0
	ds_write_b16 v1, v3 offset:2640
	ds_read_u16 v3, v1 offset:2912
	s_waitcnt lgkmcnt(0)
	v_lshlrev_b32_e32 v3, 16, v3
	v_mul_f32_e32 v14, 0xbfb8aa3b, v3
	v_exp_f32_e32 v14, v14
	s_nop 0
	v_add_f32_e32 v14, 1.0, v14
	v_div_scale_f32 v15, s[0:1], v14, v14, v3
	s_nop 0
	v_rcp_f32_e32 v15, v14
	s_nop 0
	v_mul_f32_e32 v3, v3, v15
	v_mul_f32_e32 v3, v13, v3
	v_cvt_pk_bf16_f32 v3, v3, s0
	ds_write_b16 v1, v3 offset:2912
	ds_read_u16 v3, v1 offset:3184
	s_waitcnt lgkmcnt(0)
; #define LAS __attribute__((address_space(3)))
; #define LDS_WAIT() asm volatile("s_waitcnt lgkmcnt(0)" ::: "memory")
; DI unsigned cvtpk(float lo, float hi) { f32x2 v = {lo, hi}; bf16x2_t b = __builtin_convertvector(v, bf16x2_t); return __builtin_bit_cast(unsigned, b); }
; DI float bf2f(bf16 b) { return __uint_as_float(((unsigned)b) << 16); }
; DI float siluf_(float x) { return x / (1.f + __expf(-x)); }
; DI void g3_tile_out(bf16* g, const LAS unsigned char* R, int lane) {
;     LDS_WAIT();
; #pragma unroll
;     for (int it = 0; it < 8; ++it) { const int row = 4 * it + (lane >> 4), ch = lane & 15;
;         *(u32x4*)(g + (size_t)row * 512 + ch * 8) = *(const LAS u32x4*)(R + row * G3_PITCH + ch * 16); }
;     LDS_WAIT();
; DI void gla_stage3(const Ctx& c0, int layer, int unit, int cb, LAS unsigned char* lds) {
;     ...
;     for (int vb = 0; vb < 4; ++vb) { const float g = gn[32 * vb + r];
; #pragma unroll
;         for (int rg = 0; rg < 16; ++rg) { LAS bf16* e = (LAS bf16*)(R + (4 * hi) * G3_PITCH + r * 2 + ((rg & 3) + 8 * (rg >> 2)) * G3_PITCH + 64 * vb);
;             const float z = bf2f(*e);
;             *e = (bf16)(cvtpk(o[vb][rg] * rs[rg] * g * siluf_(z), 0.f) & 0xffffu); }
;         asm volatile("" ::: "memory"); }
;     g3_tile_out((bf16*)(c.ws + O_OGLA) + row0 * 512 + h * 128, R, lane);
	v_lshlrev_b32_e32 v3, 16, v3
	v_mul_f32_e32 v13, 0xbfb8aa3b, v3
	v_exp_f32_e32 v13, v13
	s_nop 0
	v_add_f32_e32 v13, 1.0, v13
	v_div_scale_f32 v14, s[0:1], v13, v13, v3
	s_nop 0
	v_rcp_f32_e32 v14, v13
	s_nop 0
	v_mul_f32_e32 v3, v3, v14
	v_mul_f32_e32 v3, v12, v3
	v_cvt_pk_bf16_f32 v3, v3, s0
	ds_write_b16 v1, v3 offset:3184
	ds_read_u16 v3, v1 offset:4544
	s_waitcnt lgkmcnt(0)
	v_lshlrev_b32_e32 v3, 16, v3
	v_mul_f32_e32 v12, 0xbfb8aa3b, v3
	v_exp_f32_e32 v12, v12
	s_nop 0
	v_add_f32_e32 v12, 1.0, v12
	v_div_scale_f32 v13, s[0:1], v12, v12, v3
	s_nop 0
	v_rcp_f32_e32 v13, v12
	s_nop 0
	v_mul_f32_e32 v3, v3, v13
	v_mul_f32_e32 v3, v11, v3
	v_cvt_pk_bf16_f32 v3, v3, s0
	ds_write_b16 v1, v3 offset:4544
	ds_read_u16 v3, v1 offset:4816
	s_waitcnt lgkmcnt(0)
	v_lshlrev_b32_e32 v3, 16, v3
	v_mul_f32_e32 v11, 0xbfb8aa3b, v3
	v_exp_f32_e32 v11, v11
	s_nop 0
	v_add_f32_e32 v11, 1.0, v11
	v_div_scale_f32 v12, s[0:1], v11, v11, v3
	s_nop 0
	v_rcp_f32_e32 v12, v11
	s_nop 0
	v_mul_f32_e32 v3, v3, v12
	v_mul_f32_e32 v3, v10, v3
	v_cvt_pk_bf16_f32 v3, v3, s0
	ds_write_b16 v1, v3 offset:4816
	ds_read_u16 v3, v1 offset:5088
	s_waitcnt lgkmcnt(0)
	v_lshlrev_b32_e32 v3, 16, v3
	v_mul_f32_e32 v10, 0xbfb8aa3b, v3
	v_exp_f32_e32 v10, v10
	s_nop 0
	v_add_f32_e32 v10, 1.0, v10
	v_div_scale_f32 v11, s[0:1], v10, v10, v3
	s_nop 0
	v_rcp_f32_e32 v11, v10
	s_nop 0
	v_mul_f32_e32 v3, v3, v11
	v_mul_f32_e32 v3, v9, v3
	v_cvt_pk_bf16_f32 v3, v3, s0
	ds_write_b16 v1, v3 offset:5088
	ds_read_u16 v3, v1 offset:5360
	s_waitcnt lgkmcnt(0)
	v_lshlrev_b32_e32 v3, 16, v3
	v_mul_f32_e32 v9, 0xbfb8aa3b, v3
	v_exp_f32_e32 v9, v9
	s_nop 0
	v_add_f32_e32 v9, 1.0, v9
	v_div_scale_f32 v10, s[0:1], v9, v9, v3
	s_nop 0
	v_rcp_f32_e32 v10, v9
	s_nop 0
	v_mul_f32_e32 v3, v3, v10
	v_mul_f32_e32 v3, v8, v3
	v_cvt_pk_bf16_f32 v3, v3, s0
	ds_write_b16 v1, v3 offset:5360
	ds_read_u16 v3, v1 offset:6720
	s_waitcnt lgkmcnt(0)
	v_lshlrev_b32_e32 v3, 16, v3
	v_mul_f32_e32 v8, 0xbfb8aa3b, v3
	v_exp_f32_e32 v8, v8
	s_nop 0
	v_add_f32_e32 v8, 1.0, v8
	v_div_scale_f32 v9, s[0:1], v8, v8, v3
	s_nop 0
	v_rcp_f32_e32 v9, v8
	s_nop 0
	v_mul_f32_e32 v3, v3, v9
	v_mul_f32_e32 v3, v7, v3
	v_cvt_pk_bf16_f32 v3, v3, s0
	ds_write_b16 v1, v3 offset:6720
	ds_read_u16 v3, v1 offset:6992
	s_waitcnt lgkmcnt(0)
	v_lshlrev_b32_e32 v3, 16, v3
	v_mul_f32_e32 v7, 0xbfb8aa3b, v3
	v_exp_f32_e32 v7, v7
	s_nop 0
	v_add_f32_e32 v7, 1.0, v7
	v_div_scale_f32 v8, s[0:1], v7, v7, v3
	s_nop 0
	v_rcp_f32_e32 v8, v7
	s_nop 0
	v_mul_f32_e32 v3, v3, v8
	v_mul_f32_e32 v3, v6, v3
	v_cvt_pk_bf16_f32 v3, v3, s0
	ds_write_b16 v1, v3 offset:6992
	ds_read_u16 v3, v1 offset:7264
	s_waitcnt lgkmcnt(0)
	v_lshlrev_b32_e32 v3, 16, v3
	v_mul_f32_e32 v6, 0xbfb8aa3b, v3
	v_exp_f32_e32 v6, v6
	s_nop 0
	v_add_f32_e32 v6, 1.0, v6
	v_div_scale_f32 v7, s[0:1], v6, v6, v3
	s_nop 0
	v_rcp_f32_e32 v7, v6
	s_nop 0
	v_mul_f32_e32 v3, v3, v7
	v_mul_f32_e32 v3, v5, v3
	v_cvt_pk_bf16_f32 v3, v3, s0
	ds_write_b16 v1, v3 offset:7264
	ds_read_u16 v3, v1 offset:7536
	s_waitcnt lgkmcnt(0)
	v_lshlrev_b32_e32 v3, 16, v3
	v_mul_f32_e32 v4, 0xbfb8aa3b, v3
	v_exp_f32_e32 v4, v4
	s_nop 0
	v_add_f32_e32 v4, 1.0, v4
	v_div_scale_f32 v5, s[0:1], v4, v4, v3
	s_nop 0
	v_rcp_f32_e32 v5, v4
	s_nop 0
	v_mul_f32_e32 v3, v3, v5
	v_mul_f32_e32 v2, v2, v3
	v_cvt_pk_bf16_f32 v2, v2, s0
	ds_write_b16 v1, v2 offset:7536
	s_waitcnt lgkmcnt(0)
	ds_read_b128 v[2:5], v92
	v_lshl_add_u64 v[6:7], v[90:91], 0, s[24:25]
	v_lshl_add_u64 v[8:9], v[6:7], 0, v[66:67]
	s_waitcnt lgkmcnt(0)
	global_store_dwordx4 v[8:9], v[2:5], off
	ds_read_b128 v[2:5], v92 offset:1088
	v_lshl_add_u64 v[8:9], v[6:7], 0, v[68:69]
	s_waitcnt lgkmcnt(0)
	global_store_dwordx4 v[8:9], v[2:5], off
	ds_read_b128 v[2:5], v92 offset:2176
	v_lshl_add_u64 v[8:9], v[6:7], 0, v[70:71]
	s_waitcnt lgkmcnt(0)
	global_store_dwordx4 v[8:9], v[2:5], off
	ds_read_b128 v[2:5], v92 offset:3264
	v_lshl_add_u64 v[8:9], v[6:7], 0, v[72:73]
	s_waitcnt lgkmcnt(0)
	global_store_dwordx4 v[8:9], v[2:5], off
	ds_read_b128 v[2:5], v92 offset:4352
	v_lshl_add_u64 v[8:9], v[6:7], 0, v[74:75]
	s_waitcnt lgkmcnt(0)
	global_store_dwordx4 v[8:9], v[2:5], off
	ds_read_b128 v[2:5], v92 offset:5440
	v_lshl_add_u64 v[8:9], v[6:7], 0, v[76:77]
	s_waitcnt lgkmcnt(0)
	global_store_dwordx4 v[8:9], v[2:5], off
	ds_read_b128 v[2:5], v92 offset:6528
	v_lshl_add_u64 v[8:9], v[6:7], 0, v[78:79]
	v_lshl_add_u64 v[6:7], v[6:7], 0, v[80:81]
	s_waitcnt lgkmcnt(0)
	global_store_dwordx4 v[8:9], v[2:5], off
	ds_read_b128 v[2:5], v92 offset:7616
	s_waitcnt lgkmcnt(0)
	global_store_dwordx4 v[6:7], v[2:5], off
	s_waitcnt lgkmcnt(0)
	s_cbranch_scc1 .LBB0_1216
